# GEMM DIST2 loops: counted vmcnt + LDS stores interleaved into MFMA block; ff2/in-proj/ff1 epilogue loads batched; dn_scan K fragments hoisted
# speedup vs baseline: 1.0304x; 1.0156x over previous
; template <int MODE, int HALF>
; __device__ void gemm_phase(const P& p, int layer, char* smem) {
;     ...
;       for (int mi = 0; mi < 4; ++mi) {
; #pragma unroll
;         for (int j = 0; j < 4; ++j) {
;           size_t grow = row0 + wm * 64 + mi * 16 + lqe * 4 + j;
;           float rstd = rsqrtf(RSa[grow] * (1.f / 1024.f) + 1e-6f);
; #pragma unroll
;           for (int ni = 0; ni < 8; ++ni) {
;             float v = fmaxf(acc[mi][ni][j] * rstd, 0.f);
;             pb[(lqe * 4 + j) * 136 + ni * 16 + lre] = f2bf(v * v);
;           }
;         }
;         asm volatile("" ::: "memory");
.LBB0_153:
	s_ashr_i32 s0, s8, 31
	s_lshr_b32 s0, s0, 29
	s_add_i32 s14, s8, s0
	s_ashr_i32 s0, s14, 3
	s_ashr_i32 s1, s0, 31
	v_mov_b32_e32 v211, v184
	v_mov_b32_e32 v216, v179
	s_lshl_b64 s[12:13], s[0:1], 9
	v_lshlrev_b32_e32 v202, 2, v211
	v_ashrrev_i32_e32 v203, 31, v202
	v_lshl_add_u64 v[204:205], v[194:195], 0, s[12:13]
	v_lshl_add_u64 v[208:209], v[202:203], 2, v[204:205]
	global_load_dwordx4 v[212:215], v[208:209], off
	global_load_dwordx4 v[0:3], v[208:209], off offset:64
	global_load_dwordx4 v[4:7], v[208:209], off offset:128
	global_load_dwordx4 v[8:11], v[208:209], off offset:192
	s_movk_i32 s12, 0x440
	v_mul_lo_u32 v203, v211, s12
	s_and_b32 s12, s14, 0xfffff8
	v_mov_b64_e32 v[206:207], s[16:17]
	s_sub_i32 s12, s8, s12
	s_mov_b32 s14, 0x3a800000
	v_lshl_or_b32 v204, s12, 8, v189
	s_mov_b32 s12, 0x800000
	v_lshlrev_b32_e32 v202, 1, v216
	s_lshl_b64 s[0:1], s[0:1], 7
	v_add3_u32 v211, v185, v202, v203
	v_lshl_add_u64 v[202:203], s[0:1], 0, v[186:187]
	s_add_i32 s8, s8, s60
	s_cmpk_gt_i32 s8, 0xbff
	s_waitcnt vmcnt(0)
	v_pk_fma_f32 v[212:213], v[212:213], s[14:15], v[206:207] op_sel_hi:[1,0,0]
	s_nop 0
	v_mul_f32_e32 v205, 0x4b800000, v212
	v_cmp_gt_f32_e32 vcc, s12, v212
	v_mul_f32_e32 v216, 0x4b800000, v213
	v_cmp_gt_f32_e64 s[0:1], s12, v213
	v_cndmask_b32_e32 v205, v212, v205, vcc
	s_nop 0
	v_cndmask_b32_e64 v212, v213, v216, s[0:1]
	v_rsq_f32_e32 v213, v205
	v_rsq_f32_e32 v212, v212
	v_ashrrev_i32_e32 v205, 31, v204
	v_lshl_add_u64 v[204:205], v[204:205], 1, v[200:201]
	v_mul_f32_e32 v216, 0x45800000, v213
	v_mul_f32_e32 v217, 0x45800000, v212
	v_cndmask_b32_e32 v213, v213, v216, vcc
	v_cndmask_b32_e64 v212, v212, v217, s[0:1]
	v_mul_f32_e32 v172, v172, v213
	v_mul_f32_e32 v144, v144, v213
	v_mul_f32_e32 v168, v168, v213
	v_mul_f32_e32 v164, v164, v213
	v_mul_f32_e32 v160, v160, v213
	v_mul_f32_e32 v156, v156, v213
	v_mul_f32_e32 v152, v152, v213
	v_mul_f32_e32 v148, v148, v213
	v_mul_f32_e32 v173, v173, v212
	v_mul_f32_e32 v169, v169, v212
	v_mul_f32_e32 v165, v165, v212
	v_mul_f32_e32 v161, v161, v212
	v_mul_f32_e32 v157, v157, v212
	v_max_f32_e32 v172, 0, v172
	v_max_f32_e32 v144, 0, v144
	v_max_f32_e32 v168, 0, v168
	v_max_f32_e32 v164, 0, v164
	v_max_f32_e32 v160, 0, v160
	v_max_f32_e32 v156, 0, v156
	v_max_f32_e32 v152, 0, v152
	v_max_f32_e32 v148, 0, v148
	v_max_f32_e32 v173, 0, v173
	v_max_f32_e32 v169, 0, v169
	v_max_f32_e32 v165, 0, v165
	v_max_f32_e32 v161, 0, v161
	v_max_f32_e32 v157, 0, v157
	v_mul_f32_e32 v172, v172, v172
	v_mul_f32_e32 v144, v144, v144
	v_mul_f32_e32 v168, v168, v168
	v_mul_f32_e32 v164, v164, v164
	v_mul_f32_e32 v160, v160, v160
	v_mul_f32_e32 v156, v156, v156
	v_mul_f32_e32 v152, v152, v152
	v_mul_f32_e32 v148, v148, v148
	v_mul_f32_e32 v173, v173, v173
	v_mul_f32_e32 v169, v169, v169
	v_mul_f32_e32 v165, v165, v165
	v_mul_f32_e32 v161, v161, v161
	v_mul_f32_e32 v157, v157, v157
	v_cvt_pk_bf16_f32 v172, v172, s0
	v_cvt_pk_bf16_f32 v144, v144, s0
	v_cvt_pk_bf16_f32 v168, v168, s0
	v_cvt_pk_bf16_f32 v164, v164, s0
	v_cvt_pk_bf16_f32 v160, v160, s0
	v_cvt_pk_bf16_f32 v156, v156, s0
	v_cvt_pk_bf16_f32 v152, v152, s0
	v_cvt_pk_bf16_f32 v148, v148, s0
	v_cvt_pk_bf16_f32 v173, v173, s0
	v_cvt_pk_bf16_f32 v169, v169, s0
	v_cvt_pk_bf16_f32 v165, v165, s0
	v_cvt_pk_bf16_f32 v161, v161, s0
	v_cvt_pk_bf16_f32 v157, v157, s0
	ds_write_b16 v211, v172 offset:49152
	ds_write_b16 v211, v168 offset:49184
	ds_write_b16 v211, v164 offset:49216
	ds_write_b16 v211, v160 offset:49248
	ds_write_b16 v211, v156 offset:49280
	ds_write_b16 v211, v152 offset:49312
	ds_write_b16 v211, v148 offset:49344
	ds_write_b16 v211, v144 offset:49376
	ds_write_b16 v211, v173 offset:49424
	ds_write_b16 v211, v169 offset:49456
	ds_write_b16 v211, v165 offset:49488
	ds_write_b16 v211, v161 offset:49520
	ds_write_b16 v211, v157 offset:49552
	v_mul_f32_e32 v144, v153, v212
	v_max_f32_e32 v144, 0, v144
	v_mul_f32_e32 v144, v144, v144
	v_cvt_pk_bf16_f32 v144, v144, s0
	ds_write_b16 v211, v144 offset:49584
	v_mul_f32_e32 v144, v149, v212
	v_max_f32_e32 v144, 0, v144
	v_mul_f32_e32 v144, v144, v144
	v_cvt_pk_bf16_f32 v144, v144, s0
	ds_write_b16 v211, v144 offset:49616
	v_mul_f32_e32 v144, v145, v212
	v_max_f32_e32 v148, 0, v144
	v_pk_fma_f32 v[144:145], v[214:215], s[14:15], v[206:207] op_sel_hi:[1,0,0]
	v_mul_f32_e32 v148, v148, v148
	v_mul_f32_e32 v149, 0x4b800000, v144
	v_cmp_gt_f32_e32 vcc, s12, v144
	v_cvt_pk_bf16_f32 v148, v148, s0
	ds_write_b16 v211, v148 offset:49648
	v_cndmask_b32_e32 v144, v144, v149, vcc
	v_rsq_f32_e32 v144, v144
	v_mov_b32_e32 v149, v203
	v_mul_f32_e32 v148, 0x45800000, v144
	v_cndmask_b32_e32 v144, v144, v148, vcc
	v_mul_f32_e32 v148, v174, v144
	v_max_f32_e32 v148, 0, v148
	v_mul_f32_e32 v148, v148, v148
	v_cvt_pk_bf16_f32 v148, v148, s0
	ds_write_b16 v211, v148 offset:49696
	v_mul_f32_e32 v148, v170, v144
	v_max_f32_e32 v148, 0, v148
	v_mul_f32_e32 v148, v148, v148
	v_cvt_pk_bf16_f32 v148, v148, s0
	ds_write_b16 v211, v148 offset:49728
	v_mul_f32_e32 v148, v166, v144
	v_max_f32_e32 v148, 0, v148
	v_mul_f32_e32 v148, v148, v148
	v_cvt_pk_bf16_f32 v148, v148, s0
	ds_write_b16 v211, v148 offset:49760
	v_mul_f32_e32 v148, v162, v144
	v_max_f32_e32 v148, 0, v148
	v_mul_f32_e32 v148, v148, v148
	v_cvt_pk_bf16_f32 v148, v148, s0
	ds_write_b16 v211, v148 offset:49792
	v_mul_f32_e32 v148, v158, v144
	v_max_f32_e32 v148, 0, v148
	v_mul_f32_e32 v148, v148, v148
	v_cvt_pk_bf16_f32 v148, v148, s0
	ds_write_b16 v211, v148 offset:49824
	v_mul_f32_e32 v148, v154, v144
	v_max_f32_e32 v148, 0, v148
	v_mul_f32_e32 v148, v148, v148
	v_cvt_pk_bf16_f32 v148, v148, s0
	ds_write_b16 v211, v148 offset:49856
	v_mul_f32_e32 v148, v150, v144
; template <int MODE, int HALF>
; __device__ void gemm_phase(const P& p, int layer, char* smem) {
;     ...
;       for (int mi = 0; mi < 4; ++mi) {
; #pragma unroll
;         for (int j = 0; j < 4; ++j) {
;           size_t grow = row0 + wm * 64 + mi * 16 + lqe * 4 + j;
;           float rstd = rsqrtf(RSa[grow] * (1.f / 1024.f) + 1e-6f);
; #pragma unroll
;           for (int ni = 0; ni < 8; ++ni) {
;             float v = fmaxf(acc[mi][ni][j] * rstd, 0.f);
;             pb[(lqe * 4 + j) * 136 + ni * 16 + lre] = f2bf(v * v);
;           }
;         }
;         asm volatile("" ::: "memory");
; #pragma unroll
;         for (int it = 0; it < 4; ++it) {
;           int idx = it * 64 + lane, r = idx >> 4, ch = idx & 15;
;           uint4 o4 = *(const uint4*)(pb + r * 136 + ch * 8);
;           *(uint4*)(Hp + (row0 + wm * 64 + mi * 16 + r) * 2048 + nt * 128 + ch * 8) = o4;
;         }
	v_mul_f32_e32 v144, v146, v144
	v_mul_f32_e32 v146, 0x4b800000, v145
	v_cmp_gt_f32_e32 vcc, s12, v145
	v_max_f32_e32 v144, 0, v144
	v_mul_f32_e32 v144, v144, v144
	v_cndmask_b32_e32 v145, v145, v146, vcc
	v_rsq_f32_e32 v145, v145
	v_cvt_pk_bf16_f32 v144, v144, s0
	ds_write_b16 v211, v144 offset:49920
	v_max_f32_e32 v148, 0, v148
	v_mul_f32_e32 v144, 0x45800000, v145
	v_cndmask_b32_e32 v144, v145, v144, vcc
	v_mul_f32_e32 v145, v175, v144
	v_max_f32_e32 v145, 0, v145
	v_mul_f32_e32 v145, v145, v145
	v_cvt_pk_bf16_f32 v145, v145, s0
	ds_write_b16 v211, v145 offset:49968
	v_mul_f32_e32 v145, v171, v144
	v_max_f32_e32 v145, 0, v145
	v_mul_f32_e32 v145, v145, v145
	v_cvt_pk_bf16_f32 v145, v145, s0
	ds_write_b16 v211, v145 offset:50000
	v_mul_f32_e32 v145, v167, v144
	v_max_f32_e32 v145, 0, v145
	v_mul_f32_e32 v145, v145, v145
	v_cvt_pk_bf16_f32 v145, v145, s0
	ds_write_b16 v211, v145 offset:50032
	v_mul_f32_e32 v145, v163, v144
	v_max_f32_e32 v145, 0, v145
	v_mul_f32_e32 v145, v145, v145
	v_cvt_pk_bf16_f32 v145, v145, s0
	ds_write_b16 v211, v145 offset:50064
	v_mul_f32_e32 v145, v159, v144
	v_max_f32_e32 v145, 0, v145
	v_mul_f32_e32 v145, v145, v145
	v_cvt_pk_bf16_f32 v145, v145, s0
	ds_write_b16 v211, v145 offset:50096
	v_mul_f32_e32 v145, v155, v144
	v_max_f32_e32 v145, 0, v145
	v_mul_f32_e32 v145, v145, v145
	v_cvt_pk_bf16_f32 v145, v145, s0
	ds_write_b16 v211, v145 offset:50128
	v_mul_f32_e32 v145, v151, v144
	v_mul_f32_e32 v144, v147, v144
	v_max_f32_e32 v145, 0, v145
	v_max_f32_e32 v144, 0, v144
	v_mul_f32_e32 v148, v148, v148
	v_mul_f32_e32 v145, v145, v145
	v_mul_f32_e32 v144, v144, v144
	v_cvt_pk_bf16_f32 v148, v148, s0
	v_cvt_pk_bf16_f32 v145, v145, s0
	v_cvt_pk_bf16_f32 v144, v144, s0
	ds_write_b16 v211, v148 offset:49888
	ds_write_b16 v211, v145 offset:50160
	ds_write_b16 v211, v144 offset:50192
	ds_read_b128 v[144:147], v176 offset:49152
	v_or_b32_e32 v148, v202, v184
	v_lshlrev_b64 v[148:149], 12, v[148:149]
	v_lshl_add_u64 v[152:153], v[204:205], 0, v[148:149]
	ds_read_b128 v[148:151], v176 offset:50240
	s_waitcnt lgkmcnt(1)
	global_store_dwordx4 v[152:153], v[144:147], off
	s_nop 1
	v_or_b32_e32 v144, v202, v188
	v_mov_b32_e32 v145, v203
	v_lshlrev_b64 v[144:145], 12, v[144:145]
	v_lshl_add_u64 v[144:145], v[204:205], 0, v[144:145]
	s_waitcnt lgkmcnt(0)
	global_store_dwordx4 v[144:145], v[148:151], off
	ds_read_b128 v[144:147], v176 offset:51328
	s_nop 0
	v_or_b32_e32 v148, v202, v190
	v_mov_b32_e32 v149, v203
	v_lshlrev_b64 v[148:149], 12, v[148:149]
	v_lshl_add_u64 v[152:153], v[204:205], 0, v[148:149]
	ds_read_b128 v[148:151], v176 offset:52416
	s_waitcnt lgkmcnt(1)
	global_store_dwordx4 v[152:153], v[144:147], off
	s_nop 1
	v_or_b32_e32 v144, v202, v192
	v_mov_b32_e32 v145, v203
	v_lshlrev_b64 v[144:145], 12, v[144:145]
	v_lshl_add_u64 v[144:145], v[204:205], 0, v[144:145]
	s_waitcnt lgkmcnt(0)
	global_store_dwordx4 v[144:145], v[148:151], off
	v_mov_b32_e32 v144, v0
	v_mov_b32_e32 v145, v1
	v_mov_b32_e32 v146, v2
	v_mov_b32_e32 v147, v3
	v_pk_fma_f32 v[144:145], v[144:145], s[14:15], v[206:207] op_sel_hi:[1,0,0]
	s_nop 0
	v_mul_f32_e32 v148, 0x4b800000, v144
	v_cmp_gt_f32_e32 vcc, s12, v144
	s_nop 1
	v_cndmask_b32_e32 v144, v144, v148, vcc
	v_rsq_f32_e32 v144, v144
	s_nop 0
	v_mul_f32_e32 v148, 0x45800000, v144
	v_cndmask_b32_e32 v144, v144, v148, vcc
	v_mul_f32_e32 v116, v116, v144
	v_max_f32_e32 v116, 0, v116
	v_mul_f32_e32 v116, v116, v116
	v_cvt_pk_bf16_f32 v116, v116, s0
	ds_write_b16 v211, v116 offset:49344
	v_mul_f32_e32 v116, 0x4b800000, v145
	v_cmp_gt_f32_e32 vcc, s12, v145
	v_mul_f32_e32 v112, v112, v144
	v_max_f32_e32 v112, 0, v112
	v_cndmask_b32_e32 v116, v145, v116, vcc
	v_rsq_f32_e32 v116, v116
	v_mul_f32_e32 v112, v112, v112
	v_cvt_pk_bf16_f32 v112, v112, s0
	ds_write_b16 v211, v112 offset:49376
	v_mul_f32_e32 v112, 0x45800000, v116
	v_cndmask_b32_e32 v112, v116, v112, vcc
	v_mul_f32_e32 v116, v141, v112
	v_max_f32_e32 v116, 0, v116
	v_mul_f32_e32 v116, v116, v116
	v_cvt_pk_bf16_f32 v116, v116, s0
	ds_write_b16 v211, v116 offset:49424
	v_mul_f32_e32 v116, v137, v112
	v_max_f32_e32 v116, 0, v116
	v_mul_f32_e32 v116, v116, v116
	v_cvt_pk_bf16_f32 v116, v116, s0
	ds_write_b16 v211, v116 offset:49456
	v_mul_f32_e32 v116, v133, v112
	v_max_f32_e32 v116, 0, v116
	v_mul_f32_e32 v116, v116, v116
	v_cvt_pk_bf16_f32 v116, v116, s0
	ds_write_b16 v211, v116 offset:49488
	v_mul_f32_e32 v116, v129, v112
	v_max_f32_e32 v116, 0, v116
	v_mul_f32_e32 v116, v116, v116
	v_cvt_pk_bf16_f32 v116, v116, s0
	ds_write_b16 v211, v116 offset:49520
	v_mul_f32_e32 v116, v125, v112
	v_max_f32_e32 v116, 0, v116
	v_mul_f32_e32 v116, v116, v116
	v_cvt_pk_bf16_f32 v116, v116, s0
	ds_write_b16 v211, v116 offset:49552
	v_mul_f32_e32 v116, v121, v112
	v_max_f32_e32 v116, 0, v116
	v_mul_f32_e32 v116, v116, v116
	v_cvt_pk_bf16_f32 v116, v116, s0
	ds_write_b16 v211, v116 offset:49584
	v_mul_f32_e32 v116, v117, v112
	v_max_f32_e32 v116, 0, v116
	v_mul_f32_e32 v116, v116, v116
	v_cvt_pk_bf16_f32 v116, v116, s0
	v_mul_f32_e32 v112, v113, v112
	ds_write_b16 v211, v116 offset:49616
	v_max_f32_e32 v116, 0, v112
	v_pk_fma_f32 v[112:113], v[146:147], s[14:15], v[206:207] op_sel_hi:[1,0,0]
	v_mul_f32_e32 v116, v116, v116
	v_mul_f32_e32 v117, 0x4b800000, v112
	v_cmp_gt_f32_e32 vcc, s12, v112
	v_cvt_pk_bf16_f32 v116, v116, s0
	ds_write_b16 v211, v116 offset:49648
	v_cndmask_b32_e32 v112, v112, v117, vcc
	v_rsq_f32_e32 v112, v112
	v_mul_f32_e32 v140, v140, v144
	v_mul_f32_e32 v136, v136, v144
	v_mul_f32_e32 v132, v132, v144
	v_mul_f32_e32 v116, 0x45800000, v112
	v_cndmask_b32_e32 v112, v112, v116, vcc
	v_mul_f32_e32 v116, v142, v112
	v_max_f32_e32 v116, 0, v116
; template <int MODE, int HALF>
; __device__ void gemm_phase(const P& p, int layer, char* smem) {
;     ...
;       for (int mi = 0; mi < 4; ++mi) {
; #pragma unroll
;         for (int j = 0; j < 4; ++j) {
;           size_t grow = row0 + wm * 64 + mi * 16 + lqe * 4 + j;
;           float rstd = rsqrtf(RSa[grow] * (1.f / 1024.f) + 1e-6f);
; #pragma unroll
;           for (int ni = 0; ni < 8; ++ni) {
;             float v = fmaxf(acc[mi][ni][j] * rstd, 0.f);
;             pb[(lqe * 4 + j) * 136 + ni * 16 + lre] = f2bf(v * v);
;           }
;         }
;         asm volatile("" ::: "memory");
; #pragma unroll
;         for (int it = 0; it < 4; ++it) {
;           int idx = it * 64 + lane, r = idx >> 4, ch = idx & 15;
;           uint4 o4 = *(const uint4*)(pb + r * 136 + ch * 8);
;           *(uint4*)(Hp + (row0 + wm * 64 + mi * 16 + r) * 2048 + nt * 128 + ch * 8) = o4;
;         }
	v_mul_f32_e32 v116, v116, v116
	v_cvt_pk_bf16_f32 v116, v116, s0
	ds_write_b16 v211, v116 offset:49696
	v_mul_f32_e32 v116, v138, v112
	v_max_f32_e32 v116, 0, v116
	v_mul_f32_e32 v116, v116, v116
	v_cvt_pk_bf16_f32 v116, v116, s0
	ds_write_b16 v211, v116 offset:49728
	v_mul_f32_e32 v116, v134, v112
	v_max_f32_e32 v116, 0, v116
	v_mul_f32_e32 v116, v116, v116
	v_cvt_pk_bf16_f32 v116, v116, s0
	ds_write_b16 v211, v116 offset:49760
	v_mul_f32_e32 v116, v130, v112
	v_max_f32_e32 v116, 0, v116
	v_mul_f32_e32 v116, v116, v116
	v_cvt_pk_bf16_f32 v116, v116, s0
	ds_write_b16 v211, v116 offset:49792
	v_mul_f32_e32 v116, v126, v112
	v_max_f32_e32 v116, 0, v116
	v_mul_f32_e32 v116, v116, v116
	v_cvt_pk_bf16_f32 v116, v116, s0
	ds_write_b16 v211, v116 offset:49824
	v_mul_f32_e32 v116, v122, v112
	v_max_f32_e32 v116, 0, v116
	v_mul_f32_e32 v116, v116, v116
	v_cvt_pk_bf16_f32 v116, v116, s0
	ds_write_b16 v211, v116 offset:49856
	v_mul_f32_e32 v116, v118, v112
	v_mul_f32_e32 v112, v114, v112
	v_mul_f32_e32 v114, 0x4b800000, v113
	v_cmp_gt_f32_e32 vcc, s12, v113
	v_max_f32_e32 v112, 0, v112
	v_mul_f32_e32 v112, v112, v112
	v_cndmask_b32_e32 v113, v113, v114, vcc
	v_rsq_f32_e32 v113, v113
	v_cvt_pk_bf16_f32 v112, v112, s0
	ds_write_b16 v211, v112 offset:49920
	v_mul_f32_e32 v128, v128, v144
	v_mul_f32_e32 v112, 0x45800000, v113
	v_cndmask_b32_e32 v112, v113, v112, vcc
	v_mul_f32_e32 v113, v143, v112
	v_max_f32_e32 v113, 0, v113
	v_mul_f32_e32 v113, v113, v113
	v_cvt_pk_bf16_f32 v113, v113, s0
	ds_write_b16 v211, v113 offset:49968
	v_mul_f32_e32 v113, v139, v112
	v_max_f32_e32 v113, 0, v113
	v_mul_f32_e32 v113, v113, v113
	v_cvt_pk_bf16_f32 v113, v113, s0
	ds_write_b16 v211, v113 offset:50000
	v_mul_f32_e32 v113, v135, v112
	v_max_f32_e32 v113, 0, v113
	v_mul_f32_e32 v113, v113, v113
	v_cvt_pk_bf16_f32 v113, v113, s0
	ds_write_b16 v211, v113 offset:50032
	v_mul_f32_e32 v113, v131, v112
	v_max_f32_e32 v113, 0, v113
	v_mul_f32_e32 v113, v113, v113
	v_cvt_pk_bf16_f32 v113, v113, s0
	ds_write_b16 v211, v113 offset:50064
	v_mul_f32_e32 v113, v127, v112
	v_max_f32_e32 v113, 0, v113
	v_mul_f32_e32 v113, v113, v113
	v_cvt_pk_bf16_f32 v113, v113, s0
	ds_write_b16 v211, v113 offset:50096
	v_mul_f32_e32 v113, v123, v112
	v_max_f32_e32 v113, 0, v113
	v_mul_f32_e32 v113, v113, v113
	v_cvt_pk_bf16_f32 v113, v113, s0
	v_mul_f32_e32 v124, v124, v144
	v_mul_f32_e32 v120, v120, v144
	ds_write_b16 v211, v113 offset:50128
	v_mul_f32_e32 v113, v119, v112
	v_mul_f32_e32 v112, v115, v112
	v_max_f32_e32 v140, 0, v140
	v_max_f32_e32 v136, 0, v136
	v_max_f32_e32 v132, 0, v132
	v_max_f32_e32 v128, 0, v128
	v_max_f32_e32 v124, 0, v124
	v_max_f32_e32 v120, 0, v120
	v_max_f32_e32 v116, 0, v116
	v_max_f32_e32 v113, 0, v113
	v_max_f32_e32 v112, 0, v112
	v_mul_f32_e32 v140, v140, v140
	v_mul_f32_e32 v136, v136, v136
	v_mul_f32_e32 v132, v132, v132
	v_mul_f32_e32 v128, v128, v128
	v_mul_f32_e32 v124, v124, v124
	v_mul_f32_e32 v120, v120, v120
	v_mul_f32_e32 v116, v116, v116
	v_mul_f32_e32 v113, v113, v113
	v_mul_f32_e32 v112, v112, v112
	v_cvt_pk_bf16_f32 v140, v140, s0
	v_cvt_pk_bf16_f32 v136, v136, s0
	v_cvt_pk_bf16_f32 v132, v132, s0
	v_cvt_pk_bf16_f32 v128, v128, s0
	v_cvt_pk_bf16_f32 v124, v124, s0
	v_cvt_pk_bf16_f32 v120, v120, s0
	v_cvt_pk_bf16_f32 v116, v116, s0
	v_cvt_pk_bf16_f32 v113, v113, s0
	v_cvt_pk_bf16_f32 v112, v112, s0
	ds_write_b16 v211, v140 offset:49152
	ds_write_b16 v211, v136 offset:49184
	ds_write_b16 v211, v132 offset:49216
	ds_write_b16 v211, v128 offset:49248
	ds_write_b16 v211, v124 offset:49280
	ds_write_b16 v211, v120 offset:49312
	ds_write_b16 v211, v116 offset:49888
	ds_write_b16 v211, v113 offset:50160
	ds_write_b16 v211, v112 offset:50192
	v_or_b32_e32 v122, 16, v202
	ds_read_b128 v[112:115], v176 offset:49152
	v_or_b32_e32 v116, v122, v184
	v_mov_b32_e32 v117, v203
	v_lshlrev_b64 v[116:117], 12, v[116:117]
	v_lshl_add_u64 v[120:121], v[204:205], 0, v[116:117]
	ds_read_b128 v[116:119], v176 offset:50240
	s_waitcnt lgkmcnt(1)
	global_store_dwordx4 v[120:121], v[112:115], off
	s_nop 1
	v_or_b32_e32 v112, v122, v188
	v_mov_b32_e32 v113, v203
	v_lshlrev_b64 v[112:113], 12, v[112:113]
	v_lshl_add_u64 v[112:113], v[204:205], 0, v[112:113]
	s_waitcnt lgkmcnt(0)
	global_store_dwordx4 v[112:113], v[116:119], off
	ds_read_b128 v[112:115], v176 offset:51328
	s_nop 0
	v_or_b32_e32 v116, v122, v190
	v_mov_b32_e32 v117, v203
	v_lshlrev_b64 v[116:117], 12, v[116:117]
	v_lshl_add_u64 v[120:121], v[204:205], 0, v[116:117]
	ds_read_b128 v[116:119], v176 offset:52416
	s_waitcnt lgkmcnt(1)
	global_store_dwordx4 v[120:121], v[112:115], off
	s_nop 1
	v_or_b32_e32 v112, v122, v192
	v_mov_b32_e32 v113, v203
	v_lshlrev_b64 v[112:113], 12, v[112:113]
	v_lshl_add_u64 v[112:113], v[204:205], 0, v[112:113]
	s_waitcnt lgkmcnt(0)
; template <int MODE, int HALF>
; __device__ void gemm_phase(const P& p, int layer, char* smem) {
;     ...
;       for (int mi = 0; mi < 4; ++mi) {
; #pragma unroll
;         for (int j = 0; j < 4; ++j) {
;           size_t grow = row0 + wm * 64 + mi * 16 + lqe * 4 + j;
;           float rstd = rsqrtf(RSa[grow] * (1.f / 1024.f) + 1e-6f);
; #pragma unroll
;           for (int ni = 0; ni < 8; ++ni) {
;             float v = fmaxf(acc[mi][ni][j] * rstd, 0.f);
;             pb[(lqe * 4 + j) * 136 + ni * 16 + lre] = f2bf(v * v);
;           }
;         }
;         asm volatile("" ::: "memory");
	global_store_dwordx4 v[112:113], v[116:119], off
	v_mov_b32_e32 v112, v4
	v_mov_b32_e32 v113, v5
	v_mov_b32_e32 v114, v6
	v_mov_b32_e32 v115, v7
	v_pk_fma_f32 v[112:113], v[112:113], s[14:15], v[206:207] op_sel_hi:[1,0,0]
	s_nop 0
	v_mul_f32_e32 v116, 0x4b800000, v112
	v_cmp_gt_f32_e32 vcc, s12, v112
	s_nop 1
	v_cndmask_b32_e32 v112, v112, v116, vcc
	v_rsq_f32_e32 v112, v112
	s_nop 0
	v_mul_f32_e32 v116, 0x45800000, v112
	v_cndmask_b32_e32 v112, v112, v116, vcc
	v_mul_f32_e32 v84, v84, v112
	v_max_f32_e32 v84, 0, v84
	v_mul_f32_e32 v84, v84, v84
	v_cvt_pk_bf16_f32 v84, v84, s0
	ds_write_b16 v211, v84 offset:49344
	v_mul_f32_e32 v84, 0x4b800000, v113
	v_cmp_gt_f32_e32 vcc, s12, v113
	v_mul_f32_e32 v80, v80, v112
	v_max_f32_e32 v80, 0, v80
	v_cndmask_b32_e32 v84, v113, v84, vcc
	v_rsq_f32_e32 v84, v84
	v_mul_f32_e32 v80, v80, v80
	v_cvt_pk_bf16_f32 v80, v80, s0
	ds_write_b16 v211, v80 offset:49376
	v_mul_f32_e32 v80, 0x45800000, v84
	v_cndmask_b32_e32 v80, v84, v80, vcc
	v_mul_f32_e32 v84, v109, v80
	v_max_f32_e32 v84, 0, v84
	v_mul_f32_e32 v84, v84, v84
	v_cvt_pk_bf16_f32 v84, v84, s0
	ds_write_b16 v211, v84 offset:49424
	v_mul_f32_e32 v84, v105, v80
	v_max_f32_e32 v84, 0, v84
	v_mul_f32_e32 v84, v84, v84
	v_cvt_pk_bf16_f32 v84, v84, s0
	ds_write_b16 v211, v84 offset:49456
	v_mul_f32_e32 v84, v101, v80
	v_max_f32_e32 v84, 0, v84
	v_mul_f32_e32 v84, v84, v84
	v_cvt_pk_bf16_f32 v84, v84, s0
	ds_write_b16 v211, v84 offset:49488
	v_mul_f32_e32 v84, v97, v80
	v_max_f32_e32 v84, 0, v84
	v_mul_f32_e32 v84, v84, v84
	v_cvt_pk_bf16_f32 v84, v84, s0
	ds_write_b16 v211, v84 offset:49520
	v_mul_f32_e32 v84, v93, v80
	v_max_f32_e32 v84, 0, v84
	v_mul_f32_e32 v84, v84, v84
	v_cvt_pk_bf16_f32 v84, v84, s0
	ds_write_b16 v211, v84 offset:49552
	v_mul_f32_e32 v84, v89, v80
	v_max_f32_e32 v84, 0, v84
	v_mul_f32_e32 v84, v84, v84
	v_cvt_pk_bf16_f32 v84, v84, s0
	ds_write_b16 v211, v84 offset:49584
	v_mul_f32_e32 v84, v85, v80
	v_max_f32_e32 v84, 0, v84
	v_mul_f32_e32 v84, v84, v84
	v_cvt_pk_bf16_f32 v84, v84, s0
	v_mul_f32_e32 v80, v81, v80
	ds_write_b16 v211, v84 offset:49616
	v_max_f32_e32 v84, 0, v80
	v_pk_fma_f32 v[80:81], v[114:115], s[14:15], v[206:207] op_sel_hi:[1,0,0]
	v_mul_f32_e32 v84, v84, v84
	v_mul_f32_e32 v85, 0x4b800000, v80
	v_cmp_gt_f32_e32 vcc, s12, v80
	v_cvt_pk_bf16_f32 v84, v84, s0
	ds_write_b16 v211, v84 offset:49648
	v_cndmask_b32_e32 v80, v80, v85, vcc
	v_rsq_f32_e32 v80, v80
	v_mul_f32_e32 v108, v108, v112
	v_mul_f32_e32 v104, v104, v112
	v_mul_f32_e32 v100, v100, v112
	v_mul_f32_e32 v84, 0x45800000, v80
	v_cndmask_b32_e32 v80, v80, v84, vcc
	v_mul_f32_e32 v84, v110, v80
	v_max_f32_e32 v84, 0, v84
	v_mul_f32_e32 v84, v84, v84
	v_cvt_pk_bf16_f32 v84, v84, s0
	ds_write_b16 v211, v84 offset:49696
	v_mul_f32_e32 v84, v106, v80
	v_max_f32_e32 v84, 0, v84
	v_mul_f32_e32 v84, v84, v84
	v_cvt_pk_bf16_f32 v84, v84, s0
	ds_write_b16 v211, v84 offset:49728
	v_mul_f32_e32 v84, v102, v80
	v_max_f32_e32 v84, 0, v84
	v_mul_f32_e32 v84, v84, v84
	v_cvt_pk_bf16_f32 v84, v84, s0
	ds_write_b16 v211, v84 offset:49760
	v_mul_f32_e32 v84, v98, v80
	v_max_f32_e32 v84, 0, v84
	v_mul_f32_e32 v84, v84, v84
	v_cvt_pk_bf16_f32 v84, v84, s0
	ds_write_b16 v211, v84 offset:49792
	v_mul_f32_e32 v84, v94, v80
	v_max_f32_e32 v84, 0, v84
	v_mul_f32_e32 v84, v84, v84
	v_cvt_pk_bf16_f32 v84, v84, s0
	ds_write_b16 v211, v84 offset:49824
	v_mul_f32_e32 v84, v90, v80
	v_max_f32_e32 v84, 0, v84
	v_mul_f32_e32 v84, v84, v84
	v_cvt_pk_bf16_f32 v84, v84, s0
	ds_write_b16 v211, v84 offset:49856
	v_mul_f32_e32 v84, v86, v80
	v_mul_f32_e32 v80, v82, v80
	v_mul_f32_e32 v82, 0x4b800000, v81
	v_cmp_gt_f32_e32 vcc, s12, v81
	v_max_f32_e32 v80, 0, v80
	v_mul_f32_e32 v80, v80, v80
	v_cndmask_b32_e32 v81, v81, v82, vcc
	v_rsq_f32_e32 v81, v81
	v_cvt_pk_bf16_f32 v80, v80, s0
	ds_write_b16 v211, v80 offset:49920
	v_mul_f32_e32 v96, v96, v112
	v_mul_f32_e32 v80, 0x45800000, v81
	v_cndmask_b32_e32 v80, v81, v80, vcc
	v_mul_f32_e32 v81, v111, v80
	v_max_f32_e32 v81, 0, v81
	v_mul_f32_e32 v81, v81, v81
	v_cvt_pk_bf16_f32 v81, v81, s0
	ds_write_b16 v211, v81 offset:49968
	v_mul_f32_e32 v81, v107, v80
	v_max_f32_e32 v81, 0, v81
	v_mul_f32_e32 v81, v81, v81
	v_cvt_pk_bf16_f32 v81, v81, s0
	ds_write_b16 v211, v81 offset:50000
	v_mul_f32_e32 v81, v103, v80
	v_max_f32_e32 v81, 0, v81
	v_mul_f32_e32 v81, v81, v81
	v_cvt_pk_bf16_f32 v81, v81, s0
	ds_write_b16 v211, v81 offset:50032
	v_mul_f32_e32 v81, v99, v80
	v_max_f32_e32 v81, 0, v81
	v_mul_f32_e32 v81, v81, v81
	v_cvt_pk_bf16_f32 v81, v81, s0
	ds_write_b16 v211, v81 offset:50064
	v_mul_f32_e32 v81, v95, v80
	v_max_f32_e32 v81, 0, v81
	v_mul_f32_e32 v81, v81, v81
	v_cvt_pk_bf16_f32 v81, v81, s0
	ds_write_b16 v211, v81 offset:50096
	v_mul_f32_e32 v81, v91, v80
	v_max_f32_e32 v81, 0, v81
	v_mul_f32_e32 v81, v81, v81
	v_cvt_pk_bf16_f32 v81, v81, s0
	v_mul_f32_e32 v92, v92, v112
	v_mul_f32_e32 v88, v88, v112
	ds_write_b16 v211, v81 offset:50128
	v_mul_f32_e32 v81, v87, v80
	v_mul_f32_e32 v80, v83, v80
	v_max_f32_e32 v108, 0, v108
	v_max_f32_e32 v104, 0, v104
	v_max_f32_e32 v100, 0, v100
	v_max_f32_e32 v96, 0, v96
	v_max_f32_e32 v92, 0, v92
	v_max_f32_e32 v88, 0, v88
	v_max_f32_e32 v84, 0, v84
	v_max_f32_e32 v81, 0, v81
	v_max_f32_e32 v80, 0, v80
	v_mul_f32_e32 v108, v108, v108
	v_mul_f32_e32 v104, v104, v104
	v_mul_f32_e32 v100, v100, v100
	v_mul_f32_e32 v96, v96, v96
	v_mul_f32_e32 v92, v92, v92
	v_mul_f32_e32 v88, v88, v88
	v_mul_f32_e32 v84, v84, v84
	v_mul_f32_e32 v81, v81, v81
	v_mul_f32_e32 v80, v80, v80
	v_cvt_pk_bf16_f32 v108, v108, s0
	v_cvt_pk_bf16_f32 v104, v104, s0
	v_cvt_pk_bf16_f32 v100, v100, s0
	v_cvt_pk_bf16_f32 v96, v96, s0
	v_cvt_pk_bf16_f32 v92, v92, s0
	v_cvt_pk_bf16_f32 v88, v88, s0
	v_cvt_pk_bf16_f32 v84, v84, s0
	v_cvt_pk_bf16_f32 v81, v81, s0
	v_cvt_pk_bf16_f32 v80, v80, s0
	ds_write_b16 v211, v108 offset:49152
	ds_write_b16 v211, v104 offset:49184
	ds_write_b16 v211, v100 offset:49216
	ds_write_b16 v211, v96 offset:49248
	ds_write_b16 v211, v92 offset:49280
	ds_write_b16 v211, v88 offset:49312
	ds_write_b16 v211, v84 offset:49888
	ds_write_b16 v211, v81 offset:50160
	ds_write_b16 v211, v80 offset:50192
	v_or_b32_e32 v90, 32, v202
	ds_read_b128 v[80:83], v176 offset:49152
	v_or_b32_e32 v84, v90, v184
	v_mov_b32_e32 v85, v203
	v_lshlrev_b64 v[84:85], 12, v[84:85]
	v_lshl_add_u64 v[88:89], v[204:205], 0, v[84:85]
	ds_read_b128 v[84:87], v176 offset:50240
	s_waitcnt lgkmcnt(1)
; template <int MODE, int HALF>
; __device__ void gemm_phase(const P& p, int layer, char* smem) {
;     ...
; #pragma unroll
;         for (int it = 0; it < 4; ++it) {
;           int idx = it * 64 + lane, r = idx >> 4, ch = idx & 15;
;           uint4 o4 = *(const uint4*)(pb + r * 136 + ch * 8);
;           *(uint4*)(Hp + (row0 + wm * 64 + mi * 16 + r) * 2048 + nt * 128 + ch * 8) = o4;
;         }
	global_store_dwordx4 v[88:89], v[80:83], off
	s_nop 1
	v_or_b32_e32 v80, v90, v188
	v_mov_b32_e32 v81, v203
	v_lshlrev_b64 v[80:81], 12, v[80:81]
	v_lshl_add_u64 v[80:81], v[204:205], 0, v[80:81]
	s_waitcnt lgkmcnt(0)
	global_store_dwordx4 v[80:81], v[84:87], off
	ds_read_b128 v[80:83], v176 offset:51328
	s_nop 0
	v_or_b32_e32 v84, v90, v190
	v_mov_b32_e32 v85, v203
	v_lshlrev_b64 v[84:85], 12, v[84:85]
	v_lshl_add_u64 v[88:89], v[204:205], 0, v[84:85]
	ds_read_b128 v[84:87], v176 offset:52416
	s_waitcnt lgkmcnt(1)
	global_store_dwordx4 v[88:89], v[80:83], off
	s_nop 1
	v_or_b32_e32 v80, v90, v192
	v_mov_b32_e32 v81, v203
	v_lshlrev_b64 v[80:81], 12, v[80:81]
	v_lshl_add_u64 v[80:81], v[204:205], 0, v[80:81]
	s_waitcnt lgkmcnt(0)
; template <int MODE, int HALF>
; __device__ void gemm_phase(const P& p, int layer, char* smem) {
;     ...
;       for (int mi = 0; mi < 4; ++mi) {
; #pragma unroll
;         for (int j = 0; j < 4; ++j) {
;           size_t grow = row0 + wm * 64 + mi * 16 + lqe * 4 + j;
;           float rstd = rsqrtf(RSa[grow] * (1.f / 1024.f) + 1e-6f);
; #pragma unroll
;           for (int ni = 0; ni < 8; ++ni) {
;             float v = fmaxf(acc[mi][ni][j] * rstd, 0.f);
;             pb[(lqe * 4 + j) * 136 + ni * 16 + lre] = f2bf(v * v);
;           }
;         }
;         asm volatile("" ::: "memory");
; #pragma unroll
;         for (int it = 0; it < 4; ++it) {
;           int idx = it * 64 + lane, r = idx >> 4, ch = idx & 15;
;           uint4 o4 = *(const uint4*)(pb + r * 136 + ch * 8);
;           *(uint4*)(Hp + (row0 + wm * 64 + mi * 16 + r) * 2048 + nt * 128 + ch * 8) = o4;
;         }
;         asm volatile("" ::: "memory");
;       }
;     ...
;     if (t_next >= total) break;
;     t = t_next;
	global_store_dwordx4 v[80:81], v[84:87], off
	v_mov_b32_e32 v80, v8
	v_mov_b32_e32 v81, v9
	v_mov_b32_e32 v82, v10
	v_mov_b32_e32 v83, v11
	v_pk_fma_f32 v[80:81], v[80:81], s[14:15], v[206:207] op_sel_hi:[1,0,0]
	s_nop 0
	v_mul_f32_e32 v84, 0x4b800000, v80
	v_cmp_gt_f32_e32 vcc, s12, v80
	s_nop 1
	v_cndmask_b32_e32 v80, v80, v84, vcc
	v_rsq_f32_e32 v80, v80
	s_nop 0
	v_mul_f32_e32 v84, 0x45800000, v80
	v_cndmask_b32_e32 v80, v80, v84, vcc
	v_mul_f32_e32 v52, v52, v80
	v_max_f32_e32 v52, 0, v52
	v_mul_f32_e32 v52, v52, v52
	v_cvt_pk_bf16_f32 v52, v52, s0
	ds_write_b16 v211, v52 offset:49344
	v_mul_f32_e32 v52, 0x4b800000, v81
	v_cmp_gt_f32_e32 vcc, s12, v81
	v_mul_f32_e32 v48, v48, v80
	v_max_f32_e32 v48, 0, v48
	v_cndmask_b32_e32 v52, v81, v52, vcc
	v_rsq_f32_e32 v52, v52
	v_mul_f32_e32 v48, v48, v48
	v_cvt_pk_bf16_f32 v48, v48, s0
	ds_write_b16 v211, v48 offset:49376
	v_mul_f32_e32 v48, 0x45800000, v52
	v_cndmask_b32_e32 v48, v52, v48, vcc
	v_mul_f32_e32 v52, v77, v48
	v_max_f32_e32 v52, 0, v52
	v_mul_f32_e32 v52, v52, v52
	v_cvt_pk_bf16_f32 v52, v52, s0
	ds_write_b16 v211, v52 offset:49424
	v_mul_f32_e32 v52, v73, v48
	v_max_f32_e32 v52, 0, v52
	v_mul_f32_e32 v52, v52, v52
	v_cvt_pk_bf16_f32 v52, v52, s0
	ds_write_b16 v211, v52 offset:49456
	v_mul_f32_e32 v52, v69, v48
	v_max_f32_e32 v52, 0, v52
	v_mul_f32_e32 v52, v52, v52
	v_cvt_pk_bf16_f32 v52, v52, s0
	ds_write_b16 v211, v52 offset:49488
	v_mul_f32_e32 v52, v65, v48
	v_max_f32_e32 v52, 0, v52
	v_mul_f32_e32 v52, v52, v52
	v_cvt_pk_bf16_f32 v52, v52, s0
	ds_write_b16 v211, v52 offset:49520
	v_mul_f32_e32 v52, v61, v48
	v_max_f32_e32 v52, 0, v52
	v_mul_f32_e32 v52, v52, v52
	v_cvt_pk_bf16_f32 v52, v52, s0
	ds_write_b16 v211, v52 offset:49552
	v_mul_f32_e32 v52, v57, v48
	v_max_f32_e32 v52, 0, v52
	v_mul_f32_e32 v52, v52, v52
	v_cvt_pk_bf16_f32 v52, v52, s0
	ds_write_b16 v211, v52 offset:49584
	v_mul_f32_e32 v52, v53, v48
	v_max_f32_e32 v52, 0, v52
	v_mul_f32_e32 v52, v52, v52
	v_cvt_pk_bf16_f32 v52, v52, s0
	v_mul_f32_e32 v48, v49, v48
	ds_write_b16 v211, v52 offset:49616
	v_max_f32_e32 v52, 0, v48
	v_pk_fma_f32 v[48:49], v[82:83], s[14:15], v[206:207] op_sel_hi:[1,0,0]
	v_mul_f32_e32 v52, v52, v52
	v_mul_f32_e32 v53, 0x4b800000, v48
	v_cmp_gt_f32_e32 vcc, s12, v48
	v_cvt_pk_bf16_f32 v52, v52, s0
	ds_write_b16 v211, v52 offset:49648
	v_cndmask_b32_e32 v48, v48, v53, vcc
	v_rsq_f32_e32 v48, v48
	v_mul_f32_e32 v76, v76, v80
	v_mul_f32_e32 v72, v72, v80
	v_mul_f32_e32 v68, v68, v80
	v_mul_f32_e32 v52, 0x45800000, v48
	v_cndmask_b32_e32 v48, v48, v52, vcc
	v_mul_f32_e32 v52, v78, v48
	v_max_f32_e32 v52, 0, v52
	v_mul_f32_e32 v52, v52, v52
	v_cvt_pk_bf16_f32 v52, v52, s0
	ds_write_b16 v211, v52 offset:49696
	v_mul_f32_e32 v52, v74, v48
	v_max_f32_e32 v52, 0, v52
	v_mul_f32_e32 v52, v52, v52
	v_cvt_pk_bf16_f32 v52, v52, s0
	ds_write_b16 v211, v52 offset:49728
	v_mul_f32_e32 v52, v70, v48
	v_max_f32_e32 v52, 0, v52
	v_mul_f32_e32 v52, v52, v52
	v_cvt_pk_bf16_f32 v52, v52, s0
	ds_write_b16 v211, v52 offset:49760
	v_mul_f32_e32 v52, v66, v48
	v_max_f32_e32 v52, 0, v52
	v_mul_f32_e32 v52, v52, v52
	v_cvt_pk_bf16_f32 v52, v52, s0
	ds_write_b16 v211, v52 offset:49792
	v_mul_f32_e32 v52, v62, v48
	v_max_f32_e32 v52, 0, v52
	v_mul_f32_e32 v52, v52, v52
	v_cvt_pk_bf16_f32 v52, v52, s0
	ds_write_b16 v211, v52 offset:49824
	v_mul_f32_e32 v52, v58, v48
	v_max_f32_e32 v52, 0, v52
	v_mul_f32_e32 v52, v52, v52
	v_cvt_pk_bf16_f32 v52, v52, s0
	ds_write_b16 v211, v52 offset:49856
	v_mul_f32_e32 v52, v54, v48
	v_mul_f32_e32 v48, v50, v48
	v_mul_f32_e32 v50, 0x4b800000, v49
	v_cmp_gt_f32_e32 vcc, s12, v49
	v_max_f32_e32 v48, 0, v48
	v_mul_f32_e32 v48, v48, v48
	v_cndmask_b32_e32 v49, v49, v50, vcc
	v_rsq_f32_e32 v49, v49
	v_cvt_pk_bf16_f32 v48, v48, s0
	ds_write_b16 v211, v48 offset:49920
	v_mul_f32_e32 v64, v64, v80
	v_mul_f32_e32 v48, 0x45800000, v49
	v_cndmask_b32_e32 v48, v49, v48, vcc
	v_mul_f32_e32 v49, v79, v48
	v_max_f32_e32 v49, 0, v49
	v_mul_f32_e32 v49, v49, v49
	v_cvt_pk_bf16_f32 v49, v49, s0
	ds_write_b16 v211, v49 offset:49968
	v_mul_f32_e32 v49, v75, v48
	v_max_f32_e32 v49, 0, v49
	v_mul_f32_e32 v49, v49, v49
	v_cvt_pk_bf16_f32 v49, v49, s0
	ds_write_b16 v211, v49 offset:50000
	v_mul_f32_e32 v49, v71, v48
	v_max_f32_e32 v49, 0, v49
	v_mul_f32_e32 v49, v49, v49
	v_cvt_pk_bf16_f32 v49, v49, s0
	ds_write_b16 v211, v49 offset:50032
	v_mul_f32_e32 v49, v67, v48
	v_max_f32_e32 v49, 0, v49
	v_mul_f32_e32 v49, v49, v49
	v_cvt_pk_bf16_f32 v49, v49, s0
	ds_write_b16 v211, v49 offset:50064
	v_mul_f32_e32 v49, v63, v48
	v_max_f32_e32 v49, 0, v49
	v_mul_f32_e32 v49, v49, v49
	v_cvt_pk_bf16_f32 v49, v49, s0
	ds_write_b16 v211, v49 offset:50096
	v_mul_f32_e32 v49, v59, v48
	v_max_f32_e32 v49, 0, v49
	v_mul_f32_e32 v49, v49, v49
	v_cvt_pk_bf16_f32 v49, v49, s0
	v_mul_f32_e32 v60, v60, v80
	v_mul_f32_e32 v56, v56, v80
	ds_write_b16 v211, v49 offset:50128
	v_mul_f32_e32 v49, v55, v48
	v_mul_f32_e32 v48, v51, v48
	v_max_f32_e32 v76, 0, v76
	v_max_f32_e32 v72, 0, v72
	v_max_f32_e32 v68, 0, v68
	v_max_f32_e32 v64, 0, v64
	v_max_f32_e32 v60, 0, v60
	v_max_f32_e32 v56, 0, v56
	v_max_f32_e32 v52, 0, v52
	v_max_f32_e32 v49, 0, v49
	v_max_f32_e32 v48, 0, v48
	v_mul_f32_e32 v76, v76, v76
	v_mul_f32_e32 v72, v72, v72
	v_mul_f32_e32 v68, v68, v68
	v_mul_f32_e32 v64, v64, v64
	v_mul_f32_e32 v60, v60, v60
	v_mul_f32_e32 v56, v56, v56
	v_mul_f32_e32 v52, v52, v52
	v_mul_f32_e32 v49, v49, v49
	v_mul_f32_e32 v48, v48, v48
	v_cvt_pk_bf16_f32 v76, v76, s0
	v_cvt_pk_bf16_f32 v72, v72, s0
	v_cvt_pk_bf16_f32 v68, v68, s0
	v_cvt_pk_bf16_f32 v64, v64, s0
	v_cvt_pk_bf16_f32 v60, v60, s0
	v_cvt_pk_bf16_f32 v56, v56, s0
	v_cvt_pk_bf16_f32 v52, v52, s0
	v_cvt_pk_bf16_f32 v49, v49, s0
	v_cvt_pk_bf16_f32 v48, v48, s0
	ds_write_b16 v211, v76 offset:49152
	ds_write_b16 v211, v72 offset:49184
	ds_write_b16 v211, v68 offset:49216
	ds_write_b16 v211, v64 offset:49248
	ds_write_b16 v211, v60 offset:49280
	ds_write_b16 v211, v56 offset:49312
	ds_write_b16 v211, v52 offset:49888
	ds_write_b16 v211, v49 offset:50160
	ds_write_b16 v211, v48 offset:50192
	v_or_b32_e32 v58, 48, v202
	ds_read_b128 v[48:51], v176 offset:49152
	v_or_b32_e32 v202, v58, v184
	v_lshlrev_b64 v[52:53], 12, v[202:203]
	v_lshl_add_u64 v[56:57], v[204:205], 0, v[52:53]
	ds_read_b128 v[52:55], v176 offset:50240
	v_or_b32_e32 v202, v58, v188
	s_waitcnt lgkmcnt(1)
	global_store_dwordx4 v[56:57], v[48:51], off
	s_nop 1
	v_lshlrev_b64 v[48:49], 12, v[202:203]
	v_lshl_add_u64 v[48:49], v[204:205], 0, v[48:49]
	s_waitcnt lgkmcnt(0)
	global_store_dwordx4 v[48:49], v[52:55], off
	ds_read_b128 v[48:51], v176 offset:51328
	v_or_b32_e32 v202, v58, v190
	v_lshlrev_b64 v[52:53], 12, v[202:203]
	v_lshl_add_u64 v[56:57], v[204:205], 0, v[52:53]
	ds_read_b128 v[52:55], v176 offset:52416
	v_or_b32_e32 v202, v58, v192
	s_waitcnt lgkmcnt(1)
	global_store_dwordx4 v[56:57], v[48:51], off
	s_nop 1
	v_lshlrev_b64 v[48:49], 12, v[202:203]
	v_lshl_add_u64 v[48:49], v[204:205], 0, v[48:49]
	s_waitcnt lgkmcnt(0)
	global_store_dwordx4 v[48:49], v[52:55], off
	s_cbranch_scc1 .LBB0_168

; template <int MODE, int HALF>
; __device__ void gemm_phase(const P& p, int layer, char* smem) {
;     ...
;       if (DIST == 2) {
;         LOAD_STAGE(X)
;         COMPUTE_STAGE(0)
;         STORE_STAGE(Y, 1)
;         lds_barrier();
;         LOAD_STAGE(Y)
.Lw_skipx_1:
	s_waitcnt vmcnt(0)
	s_branch .LBB0_159

; template <int MODE, int HALF>
; __device__ void gemm_phase(const P& p, int layer, char* smem) {
;     ...
;         LOAD_STAGE(Y)
;         COMPUTE_STAGE(1)
;         STORE_STAGE(X, 0)
.LBB0_156:
	ds_read_b128 v[202:205], v193 offset:8192
	ds_read_b128 v[206:209], v193 offset:9216
	ds_read_b128 v[212:215], v193 offset:10240
	ds_read_b128 v[216:219], v193 offset:11264
	ds_read_b128 v[234:237], v210 offset:32768
	ds_read_b128 v[238:241], v210 offset:33792
	ds_read_b128 v[242:245], v210 offset:34816
	ds_read_b128 v[246:249], v210 offset:35840
	s_setprio 1
	s_waitcnt lgkmcnt(3)
	v_mfma_f32_16x16x32_bf16 v[172:175], v[202:205], v[234:237], v[172:175]
	s_waitcnt lgkmcnt(2)
	v_mfma_f32_16x16x32_bf16 v[168:171], v[202:205], v[238:241], v[168:171]
	s_waitcnt lgkmcnt(1)
	v_mfma_f32_16x16x32_bf16 v[164:167], v[202:205], v[242:245], v[164:167]
	s_waitcnt lgkmcnt(0)
	v_mfma_f32_16x16x32_bf16 v[160:163], v[202:205], v[246:249], v[160:163]
	v_mfma_f32_16x16x32_bf16 v[140:143], v[206:209], v[234:237], v[140:143]
	s_waitcnt vmcnt(11)
	ds_write_b128 v191, v[0:3]
	v_mfma_f32_16x16x32_bf16 v[136:139], v[206:209], v[238:241], v[136:139]
	v_mfma_f32_16x16x32_bf16 v[132:135], v[206:209], v[242:245], v[132:135]
	s_waitcnt vmcnt(10)
	ds_write_b128 v191, v[4:7] offset:4096
	v_mfma_f32_16x16x32_bf16 v[128:131], v[206:209], v[246:249], v[128:131]
	v_mfma_f32_16x16x32_bf16 v[108:111], v[212:215], v[234:237], v[108:111]
	s_waitcnt vmcnt(9)
	ds_write_b128 v191, v[8:11] offset:16384
	v_mfma_f32_16x16x32_bf16 v[104:107], v[212:215], v[238:241], v[104:107]
	v_mfma_f32_16x16x32_bf16 v[100:103], v[212:215], v[242:245], v[100:103]
	s_waitcnt vmcnt(8)
	ds_write_b128 v191, v[12:15] offset:20480
	v_mfma_f32_16x16x32_bf16 v[96:99], v[212:215], v[246:249], v[96:99]
	v_mfma_f32_16x16x32_bf16 v[76:79], v[216:219], v[234:237], v[76:79]
	s_waitcnt vmcnt(7)
	ds_write_b128 v191, v[32:35] offset:24576
	v_mfma_f32_16x16x32_bf16 v[72:75], v[216:219], v[238:241], v[72:75]
	v_mfma_f32_16x16x32_bf16 v[68:71], v[216:219], v[242:245], v[68:71]
	s_waitcnt vmcnt(6)
	ds_write_b128 v191, v[36:39] offset:28672
	v_mfma_f32_16x16x32_bf16 v[64:67], v[216:219], v[246:249], v[64:67]
	s_setprio 0
	ds_read_b128 v[234:237], v210 offset:36864
	ds_read_b128 v[238:241], v210 offset:37888
	ds_read_b128 v[242:245], v210 offset:38912
	ds_read_b128 v[246:249], v210 offset:39936
	s_setprio 1
	s_waitcnt lgkmcnt(3)
	v_mfma_f32_16x16x32_bf16 v[156:159], v[202:205], v[234:237], v[156:159]
	s_waitcnt lgkmcnt(2)
	v_mfma_f32_16x16x32_bf16 v[152:155], v[202:205], v[238:241], v[152:155]
	s_waitcnt lgkmcnt(1)
	v_mfma_f32_16x16x32_bf16 v[148:151], v[202:205], v[242:245], v[148:151]
	s_waitcnt lgkmcnt(0)
	v_mfma_f32_16x16x32_bf16 v[144:147], v[202:205], v[246:249], v[144:147]
	v_mfma_f32_16x16x32_bf16 v[124:127], v[206:209], v[234:237], v[124:127]
	v_mfma_f32_16x16x32_bf16 v[120:123], v[206:209], v[238:241], v[120:123]
	v_mfma_f32_16x16x32_bf16 v[116:119], v[206:209], v[242:245], v[116:119]
	v_mfma_f32_16x16x32_bf16 v[112:115], v[206:209], v[246:249], v[112:115]
	v_mfma_f32_16x16x32_bf16 v[92:95], v[212:215], v[234:237], v[92:95]
	v_mfma_f32_16x16x32_bf16 v[88:91], v[212:215], v[238:241], v[88:91]
	v_mfma_f32_16x16x32_bf16 v[84:87], v[212:215], v[242:245], v[84:87]
	v_mfma_f32_16x16x32_bf16 v[80:83], v[212:215], v[246:249], v[80:83]
	v_mfma_f32_16x16x32_bf16 v[60:63], v[216:219], v[234:237], v[60:63]
	v_mfma_f32_16x16x32_bf16 v[56:59], v[216:219], v[238:241], v[56:59]
	v_mfma_f32_16x16x32_bf16 v[52:55], v[216:219], v[242:245], v[52:55]
	v_mfma_f32_16x16x32_bf16 v[48:51], v[216:219], v[246:249], v[48:51]
	s_setprio 0
	s_waitcnt lgkmcnt(0)
	s_barrier
	s_add_i32 s0, s0, 2
	s_cmp_gt_u32 s0, 29
	s_cbranch_scc1 .LBB0_153

; template <int MODE, int HALF>
; __device__ void gemm_phase(const P& p, int layer, char* smem) {
;     ...
;         LOAD_STAGE(X)
;         COMPUTE_STAGE(0)
;         STORE_STAGE(Y, 1)
.LBB0_163:
	ds_read_b128 v[202:205], v193
	ds_read_b128 v[206:209], v193 offset:1024
	ds_read_b128 v[212:215], v193 offset:2048
	ds_read_b128 v[216:219], v193 offset:3072
	ds_read_b128 v[234:237], v210 offset:16384
	ds_read_b128 v[238:241], v210 offset:17408
	ds_read_b128 v[242:245], v210 offset:18432
	ds_read_b128 v[246:249], v210 offset:19456
	s_setprio 1
	s_waitcnt lgkmcnt(3)
	v_mfma_f32_16x16x32_bf16 v[172:175], v[202:205], v[234:237], v[172:175]
	s_waitcnt lgkmcnt(2)
	v_mfma_f32_16x16x32_bf16 v[168:171], v[202:205], v[238:241], v[168:171]
	s_waitcnt lgkmcnt(1)
	v_mfma_f32_16x16x32_bf16 v[164:167], v[202:205], v[242:245], v[164:167]
	s_waitcnt lgkmcnt(0)
	v_mfma_f32_16x16x32_bf16 v[160:163], v[202:205], v[246:249], v[160:163]
	v_mfma_f32_16x16x32_bf16 v[140:143], v[206:209], v[234:237], v[140:143]
	s_waitcnt vmcnt(11)
	ds_write_b128 v191, v[16:19] offset:8192
	v_mfma_f32_16x16x32_bf16 v[136:139], v[206:209], v[238:241], v[136:139]
	v_mfma_f32_16x16x32_bf16 v[132:135], v[206:209], v[242:245], v[132:135]
	s_waitcnt vmcnt(10)
	ds_write_b128 v191, v[20:23] offset:12288
	v_mfma_f32_16x16x32_bf16 v[128:131], v[206:209], v[246:249], v[128:131]
	v_mfma_f32_16x16x32_bf16 v[108:111], v[212:215], v[234:237], v[108:111]
	s_waitcnt vmcnt(9)
	ds_write_b128 v191, v[24:27] offset:32768
	v_mfma_f32_16x16x32_bf16 v[104:107], v[212:215], v[238:241], v[104:107]
	v_mfma_f32_16x16x32_bf16 v[100:103], v[212:215], v[242:245], v[100:103]
	s_waitcnt vmcnt(8)
	ds_write_b128 v191, v[28:31] offset:36864
	v_mfma_f32_16x16x32_bf16 v[96:99], v[212:215], v[246:249], v[96:99]
	v_mfma_f32_16x16x32_bf16 v[76:79], v[216:219], v[234:237], v[76:79]
	s_waitcnt vmcnt(7)
	ds_write_b128 v191, v[40:43] offset:40960
	v_mfma_f32_16x16x32_bf16 v[72:75], v[216:219], v[238:241], v[72:75]
	v_mfma_f32_16x16x32_bf16 v[68:71], v[216:219], v[242:245], v[68:71]
	s_waitcnt vmcnt(6)
	ds_write_b128 v191, v[44:47] offset:45056
	v_mfma_f32_16x16x32_bf16 v[64:67], v[216:219], v[246:249], v[64:67]
	s_setprio 0
	ds_read_b128 v[234:237], v210 offset:20480
	ds_read_b128 v[238:241], v210 offset:21504
	ds_read_b128 v[242:245], v210 offset:22528
	ds_read_b128 v[246:249], v210 offset:23552
	s_setprio 1
	s_waitcnt lgkmcnt(3)
	v_mfma_f32_16x16x32_bf16 v[156:159], v[202:205], v[234:237], v[156:159]
	s_waitcnt lgkmcnt(2)
	v_mfma_f32_16x16x32_bf16 v[152:155], v[202:205], v[238:241], v[152:155]
	s_waitcnt lgkmcnt(1)
	v_mfma_f32_16x16x32_bf16 v[148:151], v[202:205], v[242:245], v[148:151]
	s_waitcnt lgkmcnt(0)
	v_mfma_f32_16x16x32_bf16 v[144:147], v[202:205], v[246:249], v[144:147]
	v_mfma_f32_16x16x32_bf16 v[124:127], v[206:209], v[234:237], v[124:127]
	v_mfma_f32_16x16x32_bf16 v[120:123], v[206:209], v[238:241], v[120:123]
	v_mfma_f32_16x16x32_bf16 v[116:119], v[206:209], v[242:245], v[116:119]
	v_mfma_f32_16x16x32_bf16 v[112:115], v[206:209], v[246:249], v[112:115]
	v_mfma_f32_16x16x32_bf16 v[92:95], v[212:215], v[234:237], v[92:95]
	v_mfma_f32_16x16x32_bf16 v[88:91], v[212:215], v[238:241], v[88:91]
	v_mfma_f32_16x16x32_bf16 v[84:87], v[212:215], v[242:245], v[84:87]
	v_mfma_f32_16x16x32_bf16 v[80:83], v[212:215], v[246:249], v[80:83]
	v_mfma_f32_16x16x32_bf16 v[60:63], v[216:219], v[234:237], v[60:63]
	v_mfma_f32_16x16x32_bf16 v[56:59], v[216:219], v[238:241], v[56:59]
	v_mfma_f32_16x16x32_bf16 v[52:55], v[216:219], v[242:245], v[52:55]
	v_mfma_f32_16x16x32_bf16 v[48:51], v[216:219], v[246:249], v[48:51]
	s_setprio 0
	s_waitcnt lgkmcnt(0)
	s_barrier
	s_andn2_b64 vcc, exec, s[4:5]
	s_cbranch_vccnz .Lw_skipy_1
	s_lshl_b32 s12, s1, 5
	s_ashr_i32 s13, s12, 31
	s_lshl_b64 s[12:13], s[12:13], 1
	v_lshl_add_u64 v[16:17], v[180:181], 0, s[12:13]
	v_add_co_u32_e32 v20, vcc, 0x20000, v16
	v_lshl_add_u64 v[40:41], v[182:183], 0, s[12:13]
	s_nop 0
	v_addc_co_u32_e32 v21, vcc, 0, v17, vcc
	v_add_co_u32_e32 v28, vcc, 0x20000, v40
	global_load_dwordx4 v[16:19], v[16:17], off
	s_nop 0
	global_load_dwordx4 v[20:23], v[20:21], off
	v_addc_co_u32_e32 v29, vcc, 0, v41, vcc
	v_add_co_u32_e32 v42, vcc, 0x40000, v40
	global_load_dwordx4 v[24:27], v[40:41], off
	s_nop 0
	global_load_dwordx4 v[28:31], v[28:29], off
	v_addc_co_u32_e32 v43, vcc, 0, v41, vcc
	v_add_co_u32_e32 v44, vcc, 0x60000, v40
	s_nop 1
	v_addc_co_u32_e32 v45, vcc, 0, v41, vcc
	global_load_dwordx4 v[40:43], v[42:43], off
	s_nop 0
	global_load_dwordx4 v[44:47], v[44:45], off

; template <int MODE, int HALF>
; __device__ void gemm_phase(const P& p, int layer, char* smem) {
;     ...
;         LOAD_STAGE(Y)
;         COMPUTE_STAGE(1)
;         STORE_STAGE(X, 0)
.LBB0_257:
	ds_read_b128 v[194:197], v176 offset:8192
	ds_read_b128 v[198:201], v176 offset:9216
	ds_read_b128 v[202:205], v176 offset:10240
	ds_read_b128 v[206:209], v176 offset:11264
	ds_read_b128 v[210:213], v234 offset:32768
	ds_read_b128 v[214:217], v234 offset:33792
	ds_read_b128 v[236:239], v234 offset:34816
	ds_read_b128 v[240:243], v234 offset:35840
	s_setprio 1
	s_waitcnt lgkmcnt(3)
	v_mfma_f32_16x16x32_bf16 v[172:175], v[194:197], v[210:213], v[172:175]
	s_waitcnt lgkmcnt(2)
	v_mfma_f32_16x16x32_bf16 v[168:171], v[194:197], v[214:217], v[168:171]
	s_waitcnt lgkmcnt(1)
	v_mfma_f32_16x16x32_bf16 v[164:167], v[194:197], v[236:239], v[164:167]
	s_waitcnt lgkmcnt(0)
	v_mfma_f32_16x16x32_bf16 v[160:163], v[194:197], v[240:243], v[160:163]
	v_mfma_f32_16x16x32_bf16 v[140:143], v[198:201], v[210:213], v[140:143]
	s_waitcnt vmcnt(11)
	ds_write_b128 v233, v[0:3]
	v_mfma_f32_16x16x32_bf16 v[136:139], v[198:201], v[214:217], v[136:139]
	v_mfma_f32_16x16x32_bf16 v[132:135], v[198:201], v[236:239], v[132:135]
	s_waitcnt vmcnt(10)
	ds_write_b128 v233, v[4:7] offset:4096
	v_mfma_f32_16x16x32_bf16 v[128:131], v[198:201], v[240:243], v[128:131]
	v_mfma_f32_16x16x32_bf16 v[108:111], v[202:205], v[210:213], v[108:111]
	s_waitcnt vmcnt(9)
	ds_write_b128 v233, v[8:11] offset:16384
	v_mfma_f32_16x16x32_bf16 v[104:107], v[202:205], v[214:217], v[104:107]
	v_mfma_f32_16x16x32_bf16 v[100:103], v[202:205], v[236:239], v[100:103]
	s_waitcnt vmcnt(8)
	ds_write_b128 v233, v[12:15] offset:20480
	v_mfma_f32_16x16x32_bf16 v[96:99], v[202:205], v[240:243], v[96:99]
	v_mfma_f32_16x16x32_bf16 v[76:79], v[206:209], v[210:213], v[76:79]
	s_waitcnt vmcnt(7)
	ds_write_b128 v233, v[20:23] offset:24576
	v_mfma_f32_16x16x32_bf16 v[72:75], v[206:209], v[214:217], v[72:75]
	v_mfma_f32_16x16x32_bf16 v[68:71], v[206:209], v[236:239], v[68:71]
	s_waitcnt vmcnt(6)
	ds_write_b128 v233, v[36:39] offset:28672
	v_mfma_f32_16x16x32_bf16 v[64:67], v[206:209], v[240:243], v[64:67]
	s_setprio 0
	ds_read_b128 v[210:213], v234 offset:36864
	ds_read_b128 v[214:217], v234 offset:37888
	ds_read_b128 v[236:239], v234 offset:38912
	ds_read_b128 v[240:243], v234 offset:39936
	s_setprio 1
	s_waitcnt lgkmcnt(3)
	v_mfma_f32_16x16x32_bf16 v[156:159], v[194:197], v[210:213], v[156:159]
	s_waitcnt lgkmcnt(2)
	v_mfma_f32_16x16x32_bf16 v[152:155], v[194:197], v[214:217], v[152:155]
	s_waitcnt lgkmcnt(1)
	v_mfma_f32_16x16x32_bf16 v[148:151], v[194:197], v[236:239], v[148:151]
	s_waitcnt lgkmcnt(0)
	v_mfma_f32_16x16x32_bf16 v[144:147], v[194:197], v[240:243], v[144:147]
	v_mfma_f32_16x16x32_bf16 v[124:127], v[198:201], v[210:213], v[124:127]
	v_mfma_f32_16x16x32_bf16 v[120:123], v[198:201], v[214:217], v[120:123]
	v_mfma_f32_16x16x32_bf16 v[116:119], v[198:201], v[236:239], v[116:119]
	v_mfma_f32_16x16x32_bf16 v[112:115], v[198:201], v[240:243], v[112:115]
	v_mfma_f32_16x16x32_bf16 v[92:95], v[202:205], v[210:213], v[92:95]
	v_mfma_f32_16x16x32_bf16 v[88:91], v[202:205], v[214:217], v[88:91]
	v_mfma_f32_16x16x32_bf16 v[84:87], v[202:205], v[236:239], v[84:87]
	v_mfma_f32_16x16x32_bf16 v[80:83], v[202:205], v[240:243], v[80:83]
	v_mfma_f32_16x16x32_bf16 v[60:63], v[206:209], v[210:213], v[60:63]
	v_mfma_f32_16x16x32_bf16 v[56:59], v[206:209], v[214:217], v[56:59]
	v_mfma_f32_16x16x32_bf16 v[52:55], v[206:209], v[236:239], v[52:55]
	v_mfma_f32_16x16x32_bf16 v[48:51], v[206:209], v[240:243], v[48:51]
	s_setprio 0
	s_waitcnt lgkmcnt(0)
	s_barrier
	s_add_i32 s1, s1, 2
	s_cmp_gt_u32 s1, 5
	s_cbranch_scc1 .LBB0_255

; template <int MODE, int HALF>
; __device__ void gemm_phase(const P& p, int layer, char* smem) {
;     ...
;         LOAD_STAGE(X)
;         COMPUTE_STAGE(0)
;         STORE_STAGE(Y, 1)
;         lds_barrier();
;         LOAD_STAGE(Y)
.LBB0_262:
	ds_read_b128 v[194:197], v176
	ds_read_b128 v[198:201], v176 offset:1024
	ds_read_b128 v[202:205], v176 offset:2048
	ds_read_b128 v[206:209], v176 offset:3072
	ds_read_b128 v[210:213], v234 offset:16384
	ds_read_b128 v[214:217], v234 offset:17408
	ds_read_b128 v[236:239], v234 offset:18432
	ds_read_b128 v[240:243], v234 offset:19456
	s_setprio 1
	s_waitcnt lgkmcnt(3)
	v_mfma_f32_16x16x32_bf16 v[172:175], v[194:197], v[210:213], v[172:175]
	s_waitcnt lgkmcnt(2)
	v_mfma_f32_16x16x32_bf16 v[168:171], v[194:197], v[214:217], v[168:171]
	s_waitcnt lgkmcnt(1)
	v_mfma_f32_16x16x32_bf16 v[164:167], v[194:197], v[236:239], v[164:167]
	s_waitcnt lgkmcnt(0)
	v_mfma_f32_16x16x32_bf16 v[160:163], v[194:197], v[240:243], v[160:163]
	v_mfma_f32_16x16x32_bf16 v[140:143], v[198:201], v[210:213], v[140:143]
	s_waitcnt vmcnt(11)
	ds_write_b128 v233, v[16:19] offset:8192
	v_mfma_f32_16x16x32_bf16 v[136:139], v[198:201], v[214:217], v[136:139]
	v_mfma_f32_16x16x32_bf16 v[132:135], v[198:201], v[236:239], v[132:135]
	s_waitcnt vmcnt(10)
	ds_write_b128 v233, v[24:27] offset:12288
	v_mfma_f32_16x16x32_bf16 v[128:131], v[198:201], v[240:243], v[128:131]
	v_mfma_f32_16x16x32_bf16 v[108:111], v[202:205], v[210:213], v[108:111]
	s_waitcnt vmcnt(9)
	ds_write_b128 v233, v[28:31] offset:32768
	v_mfma_f32_16x16x32_bf16 v[104:107], v[202:205], v[214:217], v[104:107]
	v_mfma_f32_16x16x32_bf16 v[100:103], v[202:205], v[236:239], v[100:103]
	s_waitcnt vmcnt(8)
	ds_write_b128 v233, v[32:35] offset:36864
	v_mfma_f32_16x16x32_bf16 v[96:99], v[202:205], v[240:243], v[96:99]
	v_mfma_f32_16x16x32_bf16 v[76:79], v[206:209], v[210:213], v[76:79]
	s_waitcnt vmcnt(7)
	ds_write_b128 v233, v[40:43] offset:40960
	v_mfma_f32_16x16x32_bf16 v[72:75], v[206:209], v[214:217], v[72:75]
	v_mfma_f32_16x16x32_bf16 v[68:71], v[206:209], v[236:239], v[68:71]
	s_waitcnt vmcnt(6)
	ds_write_b128 v233, v[44:47] offset:45056
	v_mfma_f32_16x16x32_bf16 v[64:67], v[206:209], v[240:243], v[64:67]
	s_setprio 0
	ds_read_b128 v[210:213], v234 offset:20480
	ds_read_b128 v[214:217], v234 offset:21504
	ds_read_b128 v[236:239], v234 offset:22528
	ds_read_b128 v[240:243], v234 offset:23552
	s_setprio 1
	s_waitcnt lgkmcnt(3)
	v_mfma_f32_16x16x32_bf16 v[156:159], v[194:197], v[210:213], v[156:159]
	s_waitcnt lgkmcnt(2)
	v_mfma_f32_16x16x32_bf16 v[152:155], v[194:197], v[214:217], v[152:155]
	s_waitcnt lgkmcnt(1)
	v_mfma_f32_16x16x32_bf16 v[148:151], v[194:197], v[236:239], v[148:151]
	s_waitcnt lgkmcnt(0)
	v_mfma_f32_16x16x32_bf16 v[144:147], v[194:197], v[240:243], v[144:147]
	v_mfma_f32_16x16x32_bf16 v[124:127], v[198:201], v[210:213], v[124:127]
	v_mfma_f32_16x16x32_bf16 v[120:123], v[198:201], v[214:217], v[120:123]
	v_mfma_f32_16x16x32_bf16 v[116:119], v[198:201], v[236:239], v[116:119]
	v_mfma_f32_16x16x32_bf16 v[112:115], v[198:201], v[240:243], v[112:115]
	v_mfma_f32_16x16x32_bf16 v[92:95], v[202:205], v[210:213], v[92:95]
	v_mfma_f32_16x16x32_bf16 v[88:91], v[202:205], v[214:217], v[88:91]
	v_mfma_f32_16x16x32_bf16 v[84:87], v[202:205], v[236:239], v[84:87]
	v_mfma_f32_16x16x32_bf16 v[80:83], v[202:205], v[240:243], v[80:83]
	v_mfma_f32_16x16x32_bf16 v[60:63], v[206:209], v[210:213], v[60:63]
	v_mfma_f32_16x16x32_bf16 v[56:59], v[206:209], v[214:217], v[56:59]
	v_mfma_f32_16x16x32_bf16 v[52:55], v[206:209], v[236:239], v[52:55]
	v_mfma_f32_16x16x32_bf16 v[48:51], v[206:209], v[240:243], v[48:51]
	s_setprio 0
	s_waitcnt lgkmcnt(0)
	s_barrier
	s_andn2_b64 vcc, exec, s[4:5]
	s_cbranch_vccnz .Lw_skipy_3
	s_lshl_b32 s12, s7, 5
	s_ashr_i32 s13, s12, 31
	s_lshl_b64 s[12:13], s[12:13], 1
	v_lshl_add_u64 v[16:17], v[180:181], 0, s[12:13]
	v_add_co_u32_e32 v24, vcc, 0x8000, v16
	v_lshl_add_u64 v[28:29], v[182:183], 0, s[12:13]
	s_nop 0
	v_addc_co_u32_e32 v25, vcc, 0, v17, vcc
	v_lshl_add_u64 v[32:33], v[188:189], 0, s[12:13]
	v_lshl_add_u64 v[40:41], v[190:191], 0, s[12:13]
	v_lshl_add_u64 v[44:45], v[192:193], 0, s[12:13]
	global_load_dwordx4 v[16:19], v[16:17], off
	s_nop 0
	global_load_dwordx4 v[24:27], v[24:25], off
	s_nop 0
	global_load_dwordx4 v[28:31], v[28:29], off
	s_nop 0
	global_load_dwordx4 v[32:35], v[32:33], off
	s_nop 0
	global_load_dwordx4 v[40:43], v[40:41], off
	s_nop 0
	global_load_dwordx4 v[44:47], v[44:45], off

; __device__ __forceinline__ float bf2f(bf16_t h) { return __uint_as_float(((unsigned)h) << 16); }
; __device__ void dn_scan(const P& p, int item, char* smem) {
;     ...
;   auto scan_compute = [&](int step) {
;     const int c = dir ? chunk0 + nch - 1 - step : chunk0 + step;
;     const size_t tok0 = (size_t)c * 64;
;     const char* b = smem + (step & 1) * BUF;
;     const bf16_t* sW = (const bf16_t*)b;
;     const bf16_t* sK = (const bf16_t*)(b + 64 * RS * 2);
;     const bf16_t* sU = (const bf16_t*)(b + 2 * 64 * RS * 2);
;     const float* sG = (const float*)(b + 3 * 64 * RS * 2);
;     const float glog = sG[dir ? 0 : 63];
;     const float gl = __expf(glog);
;     f32x4 vn[4];
;     bf16x4 sb[4];
; #pragma unroll
;     for (int dt = 0; dt < 4; ++dt) {
;       unsigned u0 = pack2(-S[dt][0], -S[dt][1]), u1 = pack2(-S[dt][2], -S[dt][3]);
;       sb[dt] = (bf16x4){(short)(u0 & 0xffff), (short)(u0 >> 16), (short)(u1 & 0xffff), (short)(u1 >> 16)};
;     }
; #pragma unroll
;     for (int tt = 0; tt < 4; ++tt) {
; #pragma unroll
;       for (int j = 0; j < 4; ++j) vn[tt][j] = bf2f(sU[(tt * 16 + quad * 4 + j) * RS + w * 16 + lr]);
; #pragma unroll
;       for (int dt = 0; dt < 4; ++dt) {
;         bf16x4 a = *(const bf16x4*)(sW + (tt * 16 + lr) * RS + dt * 16 + quad * 4);
;         vn[tt] = __builtin_amdgcn_mfma_f32_16x16x16bf16_1k(a, sb[dt], vn[tt], 0, 0, 0);
;       }
;     }
.LBB0_533:
	s_or_b64 exec, exec, s[0:1]
	v_add_u32_e32 v242, 0x9000, v161
	v_add_u32_e32 v243, 0x9800, v161
	v_add_u32_e32 v244, 0xa000, v161
	v_add_u32_e32 v245, 0xa800, v161
	ds_read2_b64 v[196:199], v242 offset0:64 offset1:68
	ds_read2_b64 v[200:203], v242 offset0:72 offset1:76
	ds_read2_b64 v[204:207], v243 offset0:96 offset1:100
	ds_read2_b64 v[208:211], v243 offset0:104 offset1:108
	ds_read2_b64 v[212:215], v244 offset0:128 offset1:132
	ds_read2_b64 v[216:219], v244 offset0:136 offset1:140
	ds_read2_b64 v[234:237], v245 offset0:160 offset1:164
	ds_read2_b64 v[238:241], v245 offset0:168 offset1:172
	s_add_i32 s0, s9, 8
	s_min_i32 s0, s0, s8
	s_not_b32 s1, s0
	s_add_i32 s13, s16, s1
	s_add_i32 s18, s0, s14
	s_and_b64 s[0:1], s[2:3], exec
	s_cselect_b32 s18, s18, s13
	s_ashr_i32 s19, s18, 31
	s_lshl_b64 s[20:21], s[18:19], 6
	v_lshl_add_u64 v[72:73], s[20:21], 0, v[128:129]
	v_lshlrev_b64 v[72:73], 10, v[72:73]
	v_lshl_add_u64 v[72:73], s[4:5], 0, v[72:73]
	v_lshl_add_u64 v[72:73], v[72:73], 0, s[82:83]
	v_lshl_add_u64 v[76:77], v[72:73], 0, v[176:177]
	v_add_co_u32_e64 v80, s[0:1], s41, v76
	v_mov_b32_e32 v105, s21
	s_nop 0
	v_addc_co_u32_e64 v81, s[0:1], 0, v77, s[0:1]
	s_lshl_b32 s0, s18, 2
	s_or_b32 s0, s0, s17
	s_ashr_i32 s1, s0, 31
	s_lshl_b64 s[0:1], s[0:1], 13
	v_or_b32_e32 v104, s20, v154
	v_lshl_add_u64 v[88:89], v[130:131], 0, s[0:1]
	v_lshlrev_b64 v[104:105], 6, v[104:105]
	v_lshl_add_u64 v[92:93], v[88:89], 0, v[176:177]
	s_movk_i32 s0, 0x1000
	v_lshl_add_u64 v[104:105], s[6:7], 0, v[104:105]
	global_load_dwordx4 v[72:75], v[76:77], off offset:512
	global_load_dwordx4 v[84:87], v[80:81], off offset:512
	s_nop 0
	global_load_dwordx4 v[76:79], v[76:77], off
	s_nop 0
	global_load_dwordx4 v[80:83], v[80:81], off
	s_add_i32 s12, s12, 3
	global_load_dwordx4 v[88:91], v[92:93], off
	global_load_dword v165, v[104:105], off
	v_add_co_u32_e64 v92, s[0:1], s0, v92
	v_mov_b32_e32 v104, s10
	s_nop 0
	v_addc_co_u32_e64 v93, s[0:1], 0, v93, s[0:1]
	s_xor_b32 s0, s9, -4
	s_add_i32 s13, s0, s16
	s_and_b64 s[0:1], s[2:3], exec
	s_cselect_b32 s0, s12, s13
	ds_read_b32 v169, v104 offset:55808
	ds_read_u16 v106, v160 offset:46880
	ds_read_u16 v142, v160 offset:53504
	v_cvt_pk_bf16_f32 v104, v108, s0
	v_cvt_pk_bf16_f32 v105, v109, s0
	v_xor_b32_e32 v104, 0x8000, v104
	v_xor_b32_e32 v105, 0x8000, v105
	s_mov_b32 s20, 0x5040100
	v_perm_b32 v150, v105, v104, s20
	v_cvt_pk_bf16_f32 v104, v96, s0
	v_cvt_pk_bf16_f32 v105, v97, s0
	v_xor_b32_e32 v104, 0x8000, v104
	v_xor_b32_e32 v105, 0x8000, v105
	v_perm_b32 v152, v105, v104, s20
	v_cvt_pk_bf16_f32 v104, v100, s0
	v_cvt_pk_bf16_f32 v105, v101, s0
	v_xor_b32_e32 v104, 0x8000, v104
	v_xor_b32_e32 v105, 0x8000, v105
	ds_read2_b64 v[116:119], v183 offset0:192 offset1:196
	v_perm_b32 v126, v105, v104, s20
	v_cvt_pk_bf16_f32 v104, v112, s0
	v_cvt_pk_bf16_f32 v105, v113, s0
	v_xor_b32_e32 v104, 0x8000, v104
	v_xor_b32_e32 v105, 0x8000, v105
	v_perm_b32 v124, v105, v104, s20
	ds_read_u16 v104, v160 offset:46592
	ds_read_u16 v105, v160 offset:46736
	ds_read_u16 v107, v160 offset:47024
	v_cvt_pk_bf16_f32 v143, v110, v111
	v_xor_b32_e32 v151, 0x80008000, v143
	s_waitcnt lgkmcnt(2)
	v_lshlrev_b32_e32 v104, 16, v104
	s_waitcnt lgkmcnt(1)
	v_lshlrev_b32_e32 v105, 16, v105
	v_lshlrev_b32_e32 v106, 16, v106
	s_waitcnt lgkmcnt(0)
	v_lshlrev_b32_e32 v107, 16, v107
	v_cvt_pk_bf16_f32 v145, v98, v99
	v_xor_b32_e32 v153, 0x80008000, v145
	v_mfma_f32_16x16x16_bf16 v[104:107], v[116:117], v[150:151], v[104:107]
	v_cvt_pk_bf16_f32 v147, v102, v103
	v_xor_b32_e32 v127, 0x80008000, v147
	ds_read2_b64 v[120:123], v171 offset0:224 offset1:228
	v_mfma_f32_16x16x16_bf16 v[104:107], v[118:119], v[152:153], v[104:107]
	ds_read2_b64 v[116:119], v183 offset0:200 offset1:204
	v_cvt_pk_bf16_f32 v149, v114, v115
	v_xor_b32_e32 v125, 0x80008000, v149
	s_waitcnt lgkmcnt(0)
	v_mfma_f32_16x16x16_bf16 v[104:107], v[116:117], v[126:127], v[104:107]
	ds_read_u16 v116, v160 offset:48896
	ds_read_u16 v117, v160 offset:49040
	ds_read2_b64 v[186:189], v185 offset1:4
	v_mfma_f32_16x16x16_bf16 v[104:107], v[118:119], v[124:125], v[104:107]
	ds_read_u16 v118, v160 offset:49184
	ds_read_u16 v119, v160 offset:49328
	s_waitcnt lgkmcnt(4)
	v_lshlrev_b32_e32 v116, 16, v116
	s_waitcnt lgkmcnt(3)
	v_lshlrev_b32_e32 v117, 16, v117
	ds_read2_b64 v[190:193], v172 offset0:32 offset1:36
	s_waitcnt lgkmcnt(2)
	v_lshlrev_b32_e32 v118, 16, v118
	s_waitcnt lgkmcnt(1)
	v_lshlrev_b32_e32 v119, 16, v119
	s_lshl_b32 s12, s0, 2
	s_or_b32 s12, s12, s17
	v_mfma_f32_16x16x16_bf16 v[116:119], v[120:121], v[150:151], v[116:119]
	s_ashr_i32 s13, s12, 31
	s_lshl_b64 s[12:13], s[12:13], 14
	v_cvt_pk_bf16_f32 v144, v96, v97
	v_mfma_f32_16x16x16_bf16 v[116:119], v[122:123], v[152:153], v[116:119]
	ds_read2_b64 v[120:123], v171 offset0:232 offset1:236
	global_load_dwordx4 v[92:95], v[92:93], off
	v_cvt_pk_bf16_f32 v104, v104, v105
	s_waitcnt lgkmcnt(0)
	v_mfma_f32_16x16x16_bf16 v[116:119], v[120:121], v[126:127], v[116:119]
	v_lshrrev_b32_e32 v105, 16, v104
	s_ashr_i32 s1, s0, 31
	v_cvt_pk_bf16_f32 v146, v100, v101
	v_mfma_f32_16x16x16_bf16 v[120:123], v[122:123], v[124:125], v[116:119]
	v_cvt_pk_bf16_f32 v148, v112, v113
	s_lshl_b64 s[0:1], s[0:1], 16
	s_add_u32 s0, s4, s0
	s_nop 0
	ds_read_u16 v116, v160 offset:51200
	ds_read_u16 v117, v160 offset:51344
	ds_read_u16 v118, v160 offset:51488
	ds_read_u16 v119, v160 offset:51632
	v_cvt_pk_bf16_f32 v120, v120, v121
	s_waitcnt lgkmcnt(3)
	v_lshlrev_b32_e32 v116, 16, v116
	s_waitcnt lgkmcnt(2)
	v_lshlrev_b32_e32 v117, 16, v117
	s_waitcnt lgkmcnt(1)
	v_lshlrev_b32_e32 v118, 16, v118
	s_waitcnt lgkmcnt(0)
; __device__ __forceinline__ float bf2f(bf16_t h) { return __uint_as_float(((unsigned)h) << 16); }
; __device__ void dn_scan(const P& p, int item, char* smem) {
;     ...
;     for (int tt = 0; tt < 4; ++tt) {
; #pragma unroll
;       for (int j = 0; j < 4; ++j) vn[tt][j] = bf2f(sU[(tt * 16 + quad * 4 + j) * RS + w * 16 + lr]);
; #pragma unroll
;       for (int dt = 0; dt < 4; ++dt) {
;         bf16x4 a = *(const bf16x4*)(sW + (tt * 16 + lr) * RS + dt * 16 + quad * 4);
;         vn[tt] = __builtin_amdgcn_mfma_f32_16x16x16bf16_1k(a, sb[dt], vn[tt], 0, 0, 0);
;       }
;     }
;     bf16_t* hs = HST + ((size_t)(c * 4 + h) * 2 + dir) * 4096 + (w * 16 + lr) * 64;
; #pragma unroll
;     for (int dt = 0; dt < 4; ++dt) {
;       uint2 o2; o2.x = pack2(S[dt][0], S[dt][1]); o2.y = pack2(S[dt][2], S[dt][3]);
;       *(uint2*)(hs + dt * 16 + quad * 4) = o2;
;     }
;     bf16x4 vs[4];
; #pragma unroll
;     for (int tt = 0; tt < 4; ++tt) {
;       float4 g4 = *(const float4*)(sG + tt * 16 + quad * 4);
;       float sc[4] = {__expf(glog - g4.x), __expf(glog - g4.y), __expf(glog - g4.z), __expf(glog - g4.w)};
;       bf16_t vb[4];
; #pragma unroll
;       for (int j = 0; j < 4; ++j) {
;         vb[j] = f2bf(vn[tt][j]);
;         vpatch[(tt * 16 + quad * 4 + j) * 24 + lr] = vb[j];
;       }
;       unsigned u0 = pack2(bf2f(vb[0]) * sc[0], bf2f(vb[1]) * sc[1]), u1 = pack2(bf2f(vb[2]) * sc[2], bf2f(vb[3]) * sc[3]);
;       vs[tt] = (bf16x4){(short)(u0 & 0xffff), (short)(u0 >> 16), (short)(u1 & 0xffff), (short)(u1 >> 16)};
;     }
	v_lshlrev_b32_e32 v119, 16, v119
	v_lshrrev_b32_e32 v121, 16, v120
	s_addc_u32 s1, s5, s1
	v_mfma_f32_16x16x16_bf16 v[116:119], v[186:187], v[150:151], v[116:119]
	v_mul_f32_e32 v168, 0x3fb8aa3b, v169
	s_add_i32 s9, s9, 4
	s_add_i32 s11, s11, -4
	v_mfma_f32_16x16x16_bf16 v[116:119], v[188:189], v[152:153], v[116:119]
	ds_read2_b64 v[186:189], v185 offset0:8 offset1:12
	s_cmp_ge_u32 s9, s15
	s_waitcnt lgkmcnt(0)
	v_mfma_f32_16x16x16_bf16 v[116:119], v[186:187], v[126:127], v[116:119]
	v_lshlrev_b32_e32 v186, 16, v142
	ds_read_u16 v142, v160 offset:53648
	s_waitcnt lgkmcnt(0)
	v_lshlrev_b32_e32 v187, 16, v142
	ds_read_u16 v142, v160 offset:53792
	v_mfma_f32_16x16x16_bf16 v[116:119], v[188:189], v[124:125], v[116:119]
	s_waitcnt lgkmcnt(0)
	v_lshlrev_b32_e32 v188, 16, v142
	ds_read_u16 v142, v160 offset:53936
	s_nop 4
	v_cvt_pk_bf16_f32 v116, v116, v117
	v_lshrrev_b32_e32 v117, 16, v116
	s_waitcnt lgkmcnt(0)
	v_lshlrev_b32_e32 v189, 16, v142
	s_nop 1
	v_mfma_f32_16x16x16_bf16 v[186:189], v[190:191], v[150:151], v[186:189]
	v_cvt_pk_bf16_f32 v142, v108, v109
	v_mfma_f32_16x16x16_bf16 v[150:153], v[192:193], v[152:153], v[186:189]
	s_nop 5
	ds_read2_b64 v[186:189], v172 offset0:40 offset1:44
	s_waitcnt lgkmcnt(0)
	v_mfma_f32_16x16x16_bf16 v[150:153], v[186:187], v[126:127], v[150:153]
	v_mfma_f32_16x16x16_bf16 v[124:127], v[188:189], v[124:125], v[150:153]
	s_nop 6
	v_lshl_add_u64 v[150:151], v[136:137], 0, s[12:13]
	global_store_dwordx2 v[150:151], v[142:143], off
	global_store_dwordx2 v[150:151], v[144:145], off offset:32
	ds_read_b128 v[142:145], v162 offset:55808
	ds_write_b16 v163, v104 offset:56320
	ds_write_b16 v164, v105 offset:56368
	v_and_b32_e32 v105, 0xffff0000, v104
	v_lshlrev_b32_e32 v104, 16, v104
	s_waitcnt lgkmcnt(2)
	v_sub_f32_e32 v142, v169, v142
	v_sub_f32_e32 v143, v169, v143
	v_mul_f32_e32 v142, 0x3fb8aa3b, v142
	v_mul_f32_e32 v143, 0x3fb8aa3b, v143
	v_exp_f32_e32 v142, v142
	v_exp_f32_e32 v143, v143
	v_sub_f32_e32 v144, v169, v144
	v_sub_f32_e32 v145, v169, v145
	v_mul_f32_e32 v144, 0x3fb8aa3b, v144
	v_mul_f32_e32 v145, 0x3fb8aa3b, v145
	v_exp_f32_e32 v144, v144
	v_exp_f32_e32 v145, v145
	v_pk_mul_f32 v[104:105], v[142:143], v[104:105]
	global_store_dwordx2 v[150:151], v[146:147], off offset:64
	v_cvt_pk_bf16_f32 v142, v104, v105
	v_cvt_pk_bf16_f32 v104, v106, v107
	v_lshrrev_b32_e32 v105, 16, v104
	ds_write_b16 v163, v104 offset:56416
	ds_write_b16 v164, v105 offset:56464
	v_and_b32_e32 v105, 0xffff0000, v104
	v_lshlrev_b32_e32 v104, 16, v104
	v_pk_mul_f32 v[104:105], v[144:145], v[104:105]
	global_store_dwordx2 v[150:151], v[148:149], off offset:96
	v_cvt_pk_bf16_f32 v143, v104, v105
	ds_read_b128 v[104:107], v162 offset:55872
	ds_write_b16 v163, v120 offset:57088
	ds_write_b16 v164, v121 offset:57136
	v_and_b32_e32 v121, 0xffff0000, v120
	v_lshlrev_b32_e32 v120, 16, v120
	s_waitcnt lgkmcnt(2)
	v_sub_f32_e32 v104, v169, v104
	v_sub_f32_e32 v105, v169, v105
	v_mul_f32_e32 v104, 0x3fb8aa3b, v104
	v_mul_f32_e32 v105, 0x3fb8aa3b, v105
	v_exp_f32_e32 v104, v104
	v_exp_f32_e32 v105, v105
	v_sub_f32_e32 v106, v169, v106
	v_sub_f32_e32 v107, v169, v107
	v_mul_f32_e32 v106, 0x3fb8aa3b, v106
	v_mul_f32_e32 v107, 0x3fb8aa3b, v107
	v_exp_f32_e32 v106, v106
	v_exp_f32_e32 v107, v107
	v_pk_mul_f32 v[104:105], v[104:105], v[120:121]
	s_nop 0
	v_cvt_pk_bf16_f32 v120, v104, v105
	v_cvt_pk_bf16_f32 v104, v122, v123
	v_lshrrev_b32_e32 v105, 16, v104
	ds_write_b16 v163, v104 offset:57184
	ds_write_b16 v164, v105 offset:57232
	v_and_b32_e32 v105, 0xffff0000, v104
	v_lshlrev_b32_e32 v104, 16, v104
	v_pk_mul_f32 v[104:105], v[106:107], v[104:105]
	v_lshl_add_u64 v[122:123], s[0:1], 0, v[132:133]
	v_cvt_pk_bf16_f32 v121, v104, v105
	ds_read_b128 v[104:107], v162 offset:55936
	ds_write_b16 v163, v116 offset:57856
	ds_write_b16 v164, v117 offset:57904
	v_and_b32_e32 v117, 0xffff0000, v116
	v_lshlrev_b32_e32 v116, 16, v116
	s_waitcnt lgkmcnt(2)
; __device__ __forceinline__ float bf2f(bf16_t h) { return __uint_as_float(((unsigned)h) << 16); }
; __device__ void dn_scan(const P& p, int item, char* smem) {
;     ...
;     for (int tt = 0; tt < 4; ++tt) {
;       float4 g4 = *(const float4*)(sG + tt * 16 + quad * 4);
;       float sc[4] = {__expf(glog - g4.x), __expf(glog - g4.y), __expf(glog - g4.z), __expf(glog - g4.w)};
;       bf16_t vb[4];
; #pragma unroll
;       for (int j = 0; j < 4; ++j) {
;         vb[j] = f2bf(vn[tt][j]);
;         vpatch[(tt * 16 + quad * 4 + j) * 24 + lr] = vb[j];
;       }
;       unsigned u0 = pack2(bf2f(vb[0]) * sc[0], bf2f(vb[1]) * sc[1]), u1 = pack2(bf2f(vb[2]) * sc[2], bf2f(vb[3]) * sc[3]);
;       vs[tt] = (bf16x4){(short)(u0 & 0xffff), (short)(u0 >> 16), (short)(u1 & 0xffff), (short)(u1 >> 16)};
;     }
;     asm volatile("" ::: "memory");
; #pragma unroll
;     for (int i = 0; i < 2; ++i) {
;       const int idx = i * 64 + lane, t = idx >> 1, hf = idx & 1;
;       uint4 v4 = *(const uint4*)(vpatch + t * 24 + hf * 8);
;       *(uint4*)(UW + (tok0 + t) * 512 + h * 64 + w * 16 + hf * 8) = v4;
;     }
;     asm volatile("" ::: "memory");
; #pragma unroll
;     for (int dt = 0; dt < 4; ++dt) {
;       S[dt][0] *= gl; S[dt][1] *= gl; S[dt][2] *= gl; S[dt][3] *= gl;
; #pragma unroll
;       for (int tt = 0; tt < 4; ++tt) {
;         bf16x4 a = *(const bf16x4*)(sK + (dt * 16 + lr) * RS + tt * 16 + quad * 4);
;         S[dt] = __builtin_amdgcn_mfma_f32_16x16x16bf16_1k(a, vs[tt], S[dt], 0, 0, 0);
;       }
;     }
	v_sub_f32_e32 v104, v169, v104
	v_sub_f32_e32 v105, v169, v105
	v_mul_f32_e32 v104, 0x3fb8aa3b, v104
	v_mul_f32_e32 v105, 0x3fb8aa3b, v105
	v_exp_f32_e32 v104, v104
	v_exp_f32_e32 v105, v105
	v_sub_f32_e32 v106, v169, v106
	v_sub_f32_e32 v107, v169, v107
	v_mul_f32_e32 v106, 0x3fb8aa3b, v106
	v_mul_f32_e32 v107, 0x3fb8aa3b, v107
	v_exp_f32_e32 v106, v106
	v_exp_f32_e32 v107, v107
	v_pk_mul_f32 v[104:105], v[104:105], v[116:117]
	v_lshl_add_u64 v[122:123], v[122:123], 0, s[82:83]
	v_cvt_pk_bf16_f32 v116, v104, v105
	v_cvt_pk_bf16_f32 v104, v118, v119
	v_lshrrev_b32_e32 v105, 16, v104
	ds_write_b16 v163, v104 offset:57952
	ds_write_b16 v164, v105 offset:58000
	v_and_b32_e32 v105, 0xffff0000, v104
	v_lshlrev_b32_e32 v104, 16, v104
	v_pk_mul_f32 v[104:105], v[106:107], v[104:105]
	v_cvt_pk_bf16_f32 v118, v124, v125
	v_cvt_pk_bf16_f32 v117, v104, v105
	ds_read_b128 v[104:107], v162 offset:56000
	v_lshrrev_b32_e32 v119, 16, v118
	ds_write_b16 v163, v118 offset:58624
	ds_write_b16 v164, v119 offset:58672
	v_and_b32_e32 v119, 0xffff0000, v118
	s_waitcnt lgkmcnt(2)
	v_sub_f32_e32 v104, v169, v104
	v_sub_f32_e32 v105, v169, v105
	v_mul_f32_e32 v104, 0x3fb8aa3b, v104
	v_mul_f32_e32 v105, 0x3fb8aa3b, v105
	v_exp_f32_e32 v104, v104
	v_exp_f32_e32 v105, v105
	v_sub_f32_e32 v106, v169, v106
	v_sub_f32_e32 v107, v169, v107
	v_mul_f32_e32 v106, 0x3fb8aa3b, v106
	v_mul_f32_e32 v107, 0x3fb8aa3b, v107
	v_lshlrev_b32_e32 v118, 16, v118
	v_exp_f32_e32 v106, v106
	v_exp_f32_e32 v107, v107
	v_pk_mul_f32 v[104:105], v[104:105], v[118:119]
	v_lshl_add_u64 v[122:123], v[122:123], 0, v[140:141]
	v_cvt_pk_bf16_f32 v118, v104, v105
	v_cvt_pk_bf16_f32 v104, v126, v127
	v_lshrrev_b32_e32 v105, 16, v104
	ds_write_b16 v163, v104 offset:58720
	ds_write_b16 v164, v105 offset:58768
	v_and_b32_e32 v105, 0xffff0000, v104
	v_lshlrev_b32_e32 v104, 16, v104
	v_pk_mul_f32 v[104:105], v[106:107], v[104:105]
	v_lshl_add_u64 v[122:123], v[122:123], 0, v[138:139]
	v_cvt_pk_bf16_f32 v119, v104, v105
	ds_read_b128 v[104:107], v166 offset:56320
	s_waitcnt lgkmcnt(0)
	global_store_dwordx4 v[122:123], v[104:107], off
	ds_read_b128 v[104:107], v167 offset:56320
	v_lshl_add_u64 v[122:123], s[0:1], 0, v[134:135]
	v_lshl_add_u64 v[122:123], v[122:123], 0, s[82:83]
	v_lshl_add_u64 v[122:123], v[122:123], 0, v[140:141]
	v_lshl_add_u64 v[122:123], v[122:123], 0, v[138:139]
	s_waitcnt lgkmcnt(0)
	global_store_dwordx4 v[122:123], v[104:107], off
	v_exp_f32_e32 v122, v168
	s_nop 0
	v_pk_mul_f32 v[106:107], v[110:111], v[122:123] op_sel_hi:[1,0]
	v_pk_mul_f32 v[104:105], v[108:109], v[122:123] op_sel_hi:[1,0]
	v_pk_mul_f32 v[98:99], v[98:99], v[122:123] op_sel_hi:[1,0]
	s_waitcnt lgkmcnt(0)
	v_mfma_f32_16x16x16_bf16 v[104:107], v[196:197], v[142:143], v[104:107]
	v_mul_f32_e64 v96, v96, v122
	v_mul_f32_e64 v97, v97, v122
	v_mfma_f32_16x16x16_bf16 v[104:107], v[198:199], v[120:121], v[104:107]
	s_nop 1
	v_mfma_f32_16x16x16_bf16 v[104:107], v[200:201], v[116:117], v[104:107]
	v_mfma_f32_16x16x16_bf16 v[108:111], v[202:203], v[118:119], v[104:107]
	s_nop 6
	s_nop 1
	v_mfma_f32_16x16x16_bf16 v[96:99], v[204:205], v[142:143], v[96:99]
	v_mfma_f32_16x16x16_bf16 v[96:99], v[206:207], v[120:121], v[96:99]
	s_nop 1
	v_mfma_f32_16x16x16_bf16 v[96:99], v[208:209], v[116:117], v[96:99]
	v_mfma_f32_16x16x16_bf16 v[104:107], v[210:211], v[118:119], v[96:99]
	s_nop 6
	v_mul_f32_e64 v98, v102, v122
	v_mul_f32_e64 v99, v103, v122
	v_pk_mul_f32 v[96:97], v[100:101], v[122:123] op_sel_hi:[1,0]
	s_nop 1
	v_mfma_f32_16x16x16_bf16 v[96:99], v[212:213], v[142:143], v[96:99]
	v_mfma_f32_16x16x16_bf16 v[96:99], v[214:215], v[120:121], v[96:99]
	s_nop 1
	v_mfma_f32_16x16x16_bf16 v[96:99], v[216:217], v[116:117], v[96:99]
	v_mfma_f32_16x16x16_bf16 v[100:103], v[218:219], v[118:119], v[96:99]
	s_nop 6
	v_mul_f32_e64 v98, v114, v122
	v_mul_f32_e64 v99, v115, v122
	v_pk_mul_f32 v[96:97], v[112:113], v[122:123] op_sel_hi:[1,0]
	s_nop 1
	v_mfma_f32_16x16x16_bf16 v[96:99], v[234:235], v[142:143], v[96:99]
	v_mfma_f32_16x16x16_bf16 v[96:99], v[236:237], v[120:121], v[96:99]
	s_waitcnt lgkmcnt(0)
	s_barrier
	s_waitcnt lgkmcnt(0)
	v_mfma_f32_16x16x16_bf16 v[96:99], v[238:239], v[116:117], v[96:99]
	v_mfma_f32_16x16x16_bf16 v[96:99], v[240:241], v[118:119], v[96:99]
	s_cbranch_scc1 .LBB0_542

; __device__ __forceinline__ float bf2f(bf16_t h) { return __uint_as_float(((unsigned)h) << 16); }
; __device__ void dn_scan(const P& p, int item, char* smem) {
;     ...
;     const int c = dir ? chunk0 + nch - 1 - step : chunk0 + step;
;     const size_t tok0 = (size_t)c * 64;
;     const char* b = smem + (step & 1) * BUF;
;     const bf16_t* sW = (const bf16_t*)b;
;     const bf16_t* sK = (const bf16_t*)(b + 64 * RS * 2);
;     const bf16_t* sU = (const bf16_t*)(b + 2 * 64 * RS * 2);
;     const float* sG = (const float*)(b + 3 * 64 * RS * 2);
;     const float glog = sG[dir ? 0 : 63];
;     const float gl = __expf(glog);
;     f32x4 vn[4];
;     bf16x4 sb[4];
; #pragma unroll
;     for (int dt = 0; dt < 4; ++dt) {
;       unsigned u0 = pack2(-S[dt][0], -S[dt][1]), u1 = pack2(-S[dt][2], -S[dt][3]);
;       sb[dt] = (bf16x4){(short)(u0 & 0xffff), (short)(u0 >> 16), (short)(u1 & 0xffff), (short)(u1 >> 16)};
;     }
; #pragma unroll
;     for (int tt = 0; tt < 4; ++tt) {
; #pragma unroll
;       for (int j = 0; j < 4; ++j) vn[tt][j] = bf2f(sU[(tt * 16 + quad * 4 + j) * RS + w * 16 + lr]);
; #pragma unroll
;       for (int dt = 0; dt < 4; ++dt) {
;         bf16x4 a = *(const bf16x4*)(sW + (tt * 16 + lr) * RS + dt * 16 + quad * 4);
;         vn[tt] = __builtin_amdgcn_mfma_f32_16x16x16bf16_1k(a, sb[dt], vn[tt], 0, 0, 0);
;       }
;     }
.LBB0_536:
	s_or_b64 exec, exec, s[0:1]
	v_add_u32_e32 v242, 0x2000, v161
	v_add_u32_e32 v243, 0x2800, v161
	v_add_u32_e32 v244, 0x3000, v161
	v_add_u32_e32 v245, 0x3800, v161
	ds_read2_b64 v[196:199], v242 offset0:128 offset1:132
	ds_read2_b64 v[200:203], v242 offset0:136 offset1:140
	ds_read2_b64 v[204:207], v243 offset0:160 offset1:164
	ds_read2_b64 v[208:211], v243 offset0:168 offset1:172
	ds_read2_b64 v[212:215], v244 offset0:192 offset1:196
	ds_read2_b64 v[216:219], v244 offset0:200 offset1:204
	ds_read2_b64 v[234:237], v245 offset0:224 offset1:228
	ds_read2_b64 v[238:241], v245 offset0:232 offset1:236
	s_add_i32 s0, s9, 5
	s_min_i32 s0, s0, s8
	s_not_b32 s1, s0
	s_add_i32 s12, s16, s1
	s_add_i32 s13, s0, s14
	s_and_b64 s[0:1], s[2:3], exec
	s_cselect_b32 s12, s13, s12
	s_ashr_i32 s13, s12, 31
	s_lshl_b64 s[18:19], s[12:13], 6
	v_lshl_add_u64 v[0:1], s[18:19], 0, v[128:129]
	v_lshlrev_b64 v[0:1], 10, v[0:1]
	v_lshl_add_u64 v[0:1], s[4:5], 0, v[0:1]
	s_mov_b64 s[62:63], s[82:83]
	v_lshl_add_u64 v[0:1], v[0:1], 0, s[62:63]
	v_lshl_add_u64 v[4:5], v[0:1], 0, v[176:177]
	v_add_co_u32_e64 v8, s[0:1], s41, v4
	v_mov_b32_e32 v113, s19
	s_nop 0
	v_addc_co_u32_e64 v9, s[0:1], 0, v5, s[0:1]
	s_lshl_b32 s0, s12, 2
	s_or_b32 s0, s0, s17
	s_ashr_i32 s1, s0, 31
	s_lshl_b64 s[0:1], s[0:1], 13
	v_or_b32_e32 v112, s18, v154
	v_lshl_add_u64 v[16:17], v[130:131], 0, s[0:1]
	v_lshlrev_b64 v[112:113], 6, v[112:113]
	v_lshl_add_u64 v[20:21], v[16:17], 0, v[176:177]
	s_movk_i32 s0, 0x1000
	v_lshl_add_u64 v[112:113], s[6:7], 0, v[112:113]
	global_load_dwordx4 v[0:3], v[4:5], off offset:512
	global_load_dwordx4 v[12:15], v[8:9], off offset:512
	s_nop 0
	global_load_dwordx4 v[4:7], v[4:5], off
	s_nop 0
	global_load_dwordx4 v[8:11], v[8:9], off
	s_add_i32 s13, s14, s11
	global_load_dwordx4 v[16:19], v[20:21], off
	global_load_dword v155, v[112:113], off
	v_add_co_u32_e64 v20, s[0:1], s0, v20
	s_add_i32 s12, s14, s9
	s_nop 0
	v_addc_co_u32_e64 v21, s[0:1], 0, v21, s[0:1]
	s_and_b64 s[0:1], s[2:3], exec
	s_cselect_b32 s0, s12, s13
	v_mov_b32_e32 v112, s10
	ds_read_b32 v139, v112 offset:27648
	ds_read_u16 v114, v160 offset:18720
	ds_read_u16 v142, v160 offset:25344
	v_cvt_pk_bf16_f32 v112, v108, s0
	v_cvt_pk_bf16_f32 v113, v109, s0
	v_xor_b32_e32 v112, 0x8000, v112
	v_xor_b32_e32 v113, 0x8000, v113
	v_perm_b32 v150, v113, v112, s20
	v_cvt_pk_bf16_f32 v112, v104, s0
	v_cvt_pk_bf16_f32 v113, v105, s0
	v_xor_b32_e32 v112, 0x8000, v112
	v_xor_b32_e32 v113, 0x8000, v113
	v_perm_b32 v152, v113, v112, s20
	v_cvt_pk_bf16_f32 v112, v100, s0
	v_cvt_pk_bf16_f32 v113, v101, s0
	v_xor_b32_e32 v112, 0x8000, v112
	v_xor_b32_e32 v113, 0x8000, v113
	ds_read2_b64 v[116:119], v161 offset1:4
	v_perm_b32 v126, v113, v112, s20
	v_cvt_pk_bf16_f32 v112, v96, s0
	v_cvt_pk_bf16_f32 v113, v97, s0
	v_xor_b32_e32 v112, 0x8000, v112
	v_xor_b32_e32 v113, 0x8000, v113
	v_perm_b32 v124, v113, v112, s20
	ds_read_u16 v112, v160 offset:18432
	ds_read_u16 v113, v160 offset:18576
	ds_read_u16 v115, v160 offset:18864
	v_cvt_pk_bf16_f32 v143, v110, v111
	v_xor_b32_e32 v151, 0x80008000, v143
	s_waitcnt lgkmcnt(2)
	v_lshlrev_b32_e32 v112, 16, v112
	s_waitcnt lgkmcnt(1)
	v_lshlrev_b32_e32 v113, 16, v113
	v_lshlrev_b32_e32 v114, 16, v114
	s_waitcnt lgkmcnt(0)
	v_lshlrev_b32_e32 v115, 16, v115
	v_cvt_pk_bf16_f32 v145, v106, v107
	v_xor_b32_e32 v153, 0x80008000, v145
	v_mfma_f32_16x16x16_bf16 v[112:115], v[116:117], v[150:151], v[112:115]
	v_cvt_pk_bf16_f32 v147, v102, v103
	v_xor_b32_e32 v127, 0x80008000, v147
	v_add_u32_e32 v169, 0x800, v161
	v_mfma_f32_16x16x16_bf16 v[112:115], v[118:119], v[152:153], v[112:115]
	ds_read2_b64 v[116:119], v161 offset0:8 offset1:12
	ds_read2_b64 v[120:123], v169 offset0:32 offset1:36
	v_cvt_pk_bf16_f32 v149, v98, v99
	s_waitcnt lgkmcnt(1)
	v_mfma_f32_16x16x16_bf16 v[112:115], v[116:117], v[126:127], v[112:115]
	v_xor_b32_e32 v125, 0x80008000, v149
	ds_read_u16 v116, v160 offset:20736
	ds_read_u16 v117, v160 offset:20880
	v_mfma_f32_16x16x16_bf16 v[112:115], v[118:119], v[124:125], v[112:115]
	ds_read_u16 v118, v160 offset:21024
	ds_read_u16 v119, v160 offset:21168
	s_waitcnt lgkmcnt(3)
	v_lshlrev_b32_e32 v116, 16, v116
	s_waitcnt lgkmcnt(2)
	v_lshlrev_b32_e32 v117, 16, v117
	v_add_u32_e32 v179, 0x1000, v161
	s_waitcnt lgkmcnt(1)
	v_lshlrev_b32_e32 v118, 16, v118
	s_waitcnt lgkmcnt(0)
	v_lshlrev_b32_e32 v119, 16, v119
	ds_read2_b64 v[172:175], v179 offset0:64 offset1:68
	v_add_u32_e32 v168, 0x1800, v161
	v_mfma_f32_16x16x16_bf16 v[116:119], v[120:121], v[150:151], v[116:119]
	ds_read2_b64 v[180:183], v168 offset0:96 offset1:100
	s_lshl_b32 s13, s0, 2
	s_or_b32 s18, s13, s17
	v_mfma_f32_16x16x16_bf16 v[116:119], v[122:123], v[152:153], v[116:119]
	ds_read2_b64 v[120:123], v169 offset0:40 offset1:44
	s_ashr_i32 s19, s18, 31
	s_lshl_b64 s[18:19], s[18:19], 14
	s_waitcnt lgkmcnt(0)
	v_mfma_f32_16x16x16_bf16 v[116:119], v[120:121], v[126:127], v[116:119]
	v_cvt_pk_bf16_f32 v144, v104, v105
	global_load_dwordx4 v[20:23], v[20:21], off
	v_cvt_pk_bf16_f32 v112, v112, v113
	v_mfma_f32_16x16x16_bf16 v[120:123], v[122:123], v[124:125], v[116:119]
	v_lshrrev_b32_e32 v113, 16, v112
	s_ashr_i32 s1, s0, 31
	v_cvt_pk_bf16_f32 v146, v100, v101
	s_nop 0
	ds_read_u16 v116, v160 offset:23040
	ds_read_u16 v117, v160 offset:23184
	ds_read_u16 v118, v160 offset:23328
	ds_read_u16 v119, v160 offset:23472
	v_cvt_pk_bf16_f32 v120, v120, v121
	s_waitcnt lgkmcnt(3)
	v_lshlrev_b32_e32 v116, 16, v116
	s_waitcnt lgkmcnt(2)
	v_lshlrev_b32_e32 v117, 16, v117
	s_waitcnt lgkmcnt(1)
	v_lshlrev_b32_e32 v118, 16, v118
	s_waitcnt lgkmcnt(0)
; __device__ __forceinline__ float bf2f(bf16_t h) { return __uint_as_float(((unsigned)h) << 16); }
; __device__ void dn_scan(const P& p, int item, char* smem) {
;     ...
;     for (int tt = 0; tt < 4; ++tt) {
; #pragma unroll
;       for (int j = 0; j < 4; ++j) vn[tt][j] = bf2f(sU[(tt * 16 + quad * 4 + j) * RS + w * 16 + lr]);
; #pragma unroll
;       for (int dt = 0; dt < 4; ++dt) {
;         bf16x4 a = *(const bf16x4*)(sW + (tt * 16 + lr) * RS + dt * 16 + quad * 4);
;         vn[tt] = __builtin_amdgcn_mfma_f32_16x16x16bf16_1k(a, sb[dt], vn[tt], 0, 0, 0);
;       }
;     }
;     bf16_t* hs = HST + ((size_t)(c * 4 + h) * 2 + dir) * 4096 + (w * 16 + lr) * 64;
; #pragma unroll
;     for (int dt = 0; dt < 4; ++dt) {
;       uint2 o2; o2.x = pack2(S[dt][0], S[dt][1]); o2.y = pack2(S[dt][2], S[dt][3]);
;       *(uint2*)(hs + dt * 16 + quad * 4) = o2;
;     }
;     bf16x4 vs[4];
; #pragma unroll
;     for (int tt = 0; tt < 4; ++tt) {
;       float4 g4 = *(const float4*)(sG + tt * 16 + quad * 4);
;       float sc[4] = {__expf(glog - g4.x), __expf(glog - g4.y), __expf(glog - g4.z), __expf(glog - g4.w)};
;       bf16_t vb[4];
; #pragma unroll
;       for (int j = 0; j < 4; ++j) {
;         vb[j] = f2bf(vn[tt][j]);
;         vpatch[(tt * 16 + quad * 4 + j) * 24 + lr] = vb[j];
;       }
;       unsigned u0 = pack2(bf2f(vb[0]) * sc[0], bf2f(vb[1]) * sc[1]), u1 = pack2(bf2f(vb[2]) * sc[2], bf2f(vb[3]) * sc[3]);
;       vs[tt] = (bf16x4){(short)(u0 & 0xffff), (short)(u0 >> 16), (short)(u1 & 0xffff), (short)(u1 >> 16)};
;     }
;     asm volatile("" ::: "memory");
; #pragma unroll
;     for (int i = 0; i < 2; ++i) {
;       const int idx = i * 64 + lane, t = idx >> 1, hf = idx & 1;
;       uint4 v4 = *(const uint4*)(vpatch + t * 24 + hf * 8);
;       *(uint4*)(UW + (tok0 + t) * 512 + h * 64 + w * 16 + hf * 8) = v4;
;     }
	v_lshlrev_b32_e32 v119, 16, v119
	v_lshrrev_b32_e32 v121, 16, v120
	v_cvt_pk_bf16_f32 v148, v96, v97
	v_mfma_f32_16x16x16_bf16 v[116:119], v[172:173], v[150:151], v[116:119]
	s_lshl_b64 s[0:1], s[0:1], 16
	s_add_u32 s0, s4, s0
	s_addc_u32 s1, s5, s1
	v_mfma_f32_16x16x16_bf16 v[116:119], v[174:175], v[152:153], v[116:119]
	ds_read2_b64 v[172:175], v179 offset0:72 offset1:76
	v_mul_f32_e32 v170, 0x3fb8aa3b, v139
	s_waitcnt lgkmcnt(0)
	v_mfma_f32_16x16x16_bf16 v[116:119], v[172:173], v[126:127], v[116:119]
	v_lshlrev_b32_e32 v172, 16, v142
	ds_read_u16 v142, v160 offset:25488
	s_waitcnt lgkmcnt(0)
	v_lshlrev_b32_e32 v173, 16, v142
	ds_read_u16 v142, v160 offset:25632
	v_mfma_f32_16x16x16_bf16 v[116:119], v[174:175], v[124:125], v[116:119]
	s_waitcnt lgkmcnt(0)
	v_lshlrev_b32_e32 v174, 16, v142
	ds_read_u16 v142, v160 offset:25776
	s_nop 4
	v_cvt_pk_bf16_f32 v116, v116, v117
	v_lshrrev_b32_e32 v117, 16, v116
	s_waitcnt lgkmcnt(0)
	v_lshlrev_b32_e32 v175, 16, v142
	s_nop 1
	v_mfma_f32_16x16x16_bf16 v[172:175], v[180:181], v[150:151], v[172:175]
	v_cvt_pk_bf16_f32 v142, v108, v109
	v_add_u32_e32 v180, 0x3800, v161
	v_mfma_f32_16x16x16_bf16 v[150:153], v[182:183], v[152:153], v[172:175]
	s_nop 4
	ds_read2_b64 v[172:175], v168 offset0:104 offset1:108
	s_waitcnt lgkmcnt(0)
	v_mfma_f32_16x16x16_bf16 v[150:153], v[172:173], v[126:127], v[150:153]
	v_mfma_f32_16x16x16_bf16 v[124:127], v[174:175], v[124:125], v[150:153]
	v_add_u32_e32 v174, 0x2800, v161
	v_add_u32_e32 v175, 0x3000, v161
	s_nop 4
	v_lshl_add_u64 v[150:151], v[136:137], 0, s[18:19]
	global_store_dwordx2 v[150:151], v[142:143], off
	global_store_dwordx2 v[150:151], v[144:145], off offset:32
	ds_read_b128 v[142:145], v162 offset:27648
	ds_write_b16 v163, v112 offset:56320
	ds_write_b16 v164, v113 offset:56368
	v_and_b32_e32 v113, 0xffff0000, v112
	v_lshlrev_b32_e32 v112, 16, v112
	s_waitcnt lgkmcnt(2)
	v_sub_f32_e32 v142, v139, v142
	v_sub_f32_e32 v143, v139, v143
	v_mul_f32_e32 v142, 0x3fb8aa3b, v142
	v_mul_f32_e32 v143, 0x3fb8aa3b, v143
	v_exp_f32_e32 v142, v142
	v_exp_f32_e32 v143, v143
	v_sub_f32_e32 v144, v139, v144
	v_sub_f32_e32 v145, v139, v145
	v_mul_f32_e32 v144, 0x3fb8aa3b, v144
	v_mul_f32_e32 v145, 0x3fb8aa3b, v145
	v_exp_f32_e32 v144, v144
	v_exp_f32_e32 v145, v145
	v_pk_mul_f32 v[112:113], v[142:143], v[112:113]
	global_store_dwordx2 v[150:151], v[146:147], off offset:64
	v_cvt_pk_bf16_f32 v142, v112, v113
	v_cvt_pk_bf16_f32 v112, v114, v115
	v_lshrrev_b32_e32 v113, 16, v112
	ds_write_b16 v163, v112 offset:56416
	ds_write_b16 v164, v113 offset:56464
	v_and_b32_e32 v113, 0xffff0000, v112
	v_lshlrev_b32_e32 v112, 16, v112
	v_pk_mul_f32 v[112:113], v[144:145], v[112:113]
	global_store_dwordx2 v[150:151], v[148:149], off offset:96
	v_cvt_pk_bf16_f32 v143, v112, v113
	ds_read_b128 v[112:115], v162 offset:27712
	ds_write_b16 v163, v120 offset:57088
	ds_write_b16 v164, v121 offset:57136
	v_and_b32_e32 v121, 0xffff0000, v120
	v_lshlrev_b32_e32 v120, 16, v120
	s_waitcnt lgkmcnt(2)
	v_sub_f32_e32 v112, v139, v112
	v_sub_f32_e32 v113, v139, v113
	v_mul_f32_e32 v112, 0x3fb8aa3b, v112
	v_mul_f32_e32 v113, 0x3fb8aa3b, v113
	v_exp_f32_e32 v112, v112
	v_exp_f32_e32 v113, v113
	v_sub_f32_e32 v114, v139, v114
	v_sub_f32_e32 v115, v139, v115
	v_mul_f32_e32 v114, 0x3fb8aa3b, v114
	v_mul_f32_e32 v115, 0x3fb8aa3b, v115
	v_exp_f32_e32 v114, v114
	v_exp_f32_e32 v115, v115
	v_pk_mul_f32 v[112:113], v[112:113], v[120:121]
	s_nop 0
	v_cvt_pk_bf16_f32 v120, v112, v113
	v_cvt_pk_bf16_f32 v112, v122, v123
	v_lshrrev_b32_e32 v113, 16, v112
	ds_write_b16 v163, v112 offset:57184
	ds_write_b16 v164, v113 offset:57232
	v_and_b32_e32 v113, 0xffff0000, v112
	v_lshlrev_b32_e32 v112, 16, v112
	v_pk_mul_f32 v[112:113], v[114:115], v[112:113]
	v_lshl_add_u64 v[122:123], s[0:1], 0, v[132:133]
	v_cvt_pk_bf16_f32 v121, v112, v113
	ds_read_b128 v[112:115], v162 offset:27776
	ds_write_b16 v163, v116 offset:57856
	ds_write_b16 v164, v117 offset:57904
	v_and_b32_e32 v117, 0xffff0000, v116
	v_lshlrev_b32_e32 v116, 16, v116
	s_waitcnt lgkmcnt(2)
	v_sub_f32_e32 v112, v139, v112
	v_sub_f32_e32 v113, v139, v113
	v_mul_f32_e32 v112, 0x3fb8aa3b, v112
	v_mul_f32_e32 v113, 0x3fb8aa3b, v113
	v_exp_f32_e32 v112, v112
	v_exp_f32_e32 v113, v113
	v_sub_f32_e32 v114, v139, v114
	v_sub_f32_e32 v115, v139, v115
	v_mul_f32_e32 v114, 0x3fb8aa3b, v114
	v_mul_f32_e32 v115, 0x3fb8aa3b, v115
	v_exp_f32_e32 v114, v114
	v_exp_f32_e32 v115, v115
	v_pk_mul_f32 v[112:113], v[112:113], v[116:117]
	v_lshl_add_u64 v[122:123], v[122:123], 0, s[62:63]
	v_cvt_pk_bf16_f32 v116, v112, v113
	v_cvt_pk_bf16_f32 v112, v118, v119
	v_lshrrev_b32_e32 v113, 16, v112
	ds_write_b16 v163, v112 offset:57952
	ds_write_b16 v164, v113 offset:58000
	v_and_b32_e32 v113, 0xffff0000, v112
	v_lshlrev_b32_e32 v112, 16, v112
	v_pk_mul_f32 v[112:113], v[114:115], v[112:113]
	v_cvt_pk_bf16_f32 v118, v124, v125
	v_cvt_pk_bf16_f32 v117, v112, v113
	ds_read_b128 v[112:115], v162 offset:27840
	v_lshrrev_b32_e32 v119, 16, v118
	ds_write_b16 v163, v118 offset:58624
	ds_write_b16 v164, v119 offset:58672
	v_and_b32_e32 v119, 0xffff0000, v118
	s_waitcnt lgkmcnt(2)
	v_sub_f32_e32 v112, v139, v112
	v_sub_f32_e32 v113, v139, v113
	v_mul_f32_e32 v112, 0x3fb8aa3b, v112
	v_mul_f32_e32 v113, 0x3fb8aa3b, v113
	v_exp_f32_e32 v112, v112
	v_exp_f32_e32 v113, v113
	v_sub_f32_e32 v114, v139, v114
	v_sub_f32_e32 v115, v139, v115
	v_mul_f32_e32 v114, 0x3fb8aa3b, v114
	v_mul_f32_e32 v115, 0x3fb8aa3b, v115
	v_lshlrev_b32_e32 v118, 16, v118
	v_exp_f32_e32 v114, v114
	v_exp_f32_e32 v115, v115
	v_pk_mul_f32 v[112:113], v[112:113], v[118:119]
	v_lshl_add_u64 v[122:123], v[122:123], 0, v[140:141]
	v_cvt_pk_bf16_f32 v118, v112, v113
	v_cvt_pk_bf16_f32 v112, v126, v127
	v_lshrrev_b32_e32 v113, 16, v112
	ds_write_b16 v163, v112 offset:58720
	ds_write_b16 v164, v113 offset:58768
	v_and_b32_e32 v113, 0xffff0000, v112
	v_lshlrev_b32_e32 v112, 16, v112
	v_pk_mul_f32 v[112:113], v[114:115], v[112:113]
	v_mov_b32_e32 v139, v177
	v_cvt_pk_bf16_f32 v119, v112, v113
	ds_read_b128 v[112:115], v166 offset:56320
	v_lshl_add_u64 v[122:123], v[122:123], 0, v[138:139]
	s_waitcnt lgkmcnt(0)
; __device__ void dn_scan(const P& p, int item, char* smem) {
;     ...
;   bf16_t* vpatch = (bf16_t*)(smem + 2 * BUF) + w * 64 * 24;
;   auto scan_compute = [&](int step) {
;     const int c = dir ? chunk0 + nch - 1 - step : chunk0 + step;
;     const size_t tok0 = (size_t)c * 64;
;     const char* b = smem + (step & 1) * BUF;
;     const bf16_t* sW = (const bf16_t*)b;
;     const bf16_t* sK = (const bf16_t*)(b + 64 * RS * 2);
;     const bf16_t* sU = (const bf16_t*)(b + 2 * 64 * RS * 2);
;     const float* sG = (const float*)(b + 3 * 64 * RS * 2);
;     const float glog = sG[dir ? 0 : 63];
;     const float gl = __expf(glog);
;     f32x4 vn[4];
;     bf16x4 sb[4];
; #pragma unroll
;     for (int dt = 0; dt < 4; ++dt) {
;       unsigned u0 = pack2(-S[dt][0], -S[dt][1]), u1 = pack2(-S[dt][2], -S[dt][3]);
;       sb[dt] = (bf16x4){(short)(u0 & 0xffff), (short)(u0 >> 16), (short)(u1 & 0xffff), (short)(u1 >> 16)};
;     }
;     ...
;     for (int i = 0; i < 2; ++i) {
;       const int idx = i * 64 + lane, t = idx >> 1, hf = idx & 1;
;       uint4 v4 = *(const uint4*)(vpatch + t * 24 + hf * 8);
;       *(uint4*)(UW + (tok0 + t) * 512 + h * 64 + w * 16 + hf * 8) = v4;
;     }
;     asm volatile("" ::: "memory");
; #pragma unroll
;     for (int dt = 0; dt < 4; ++dt) {
;       S[dt][0] *= gl; S[dt][1] *= gl; S[dt][2] *= gl; S[dt][3] *= gl;
; #pragma unroll
;       for (int tt = 0; tt < 4; ++tt) {
;         bf16x4 a = *(const bf16x4*)(sK + (dt * 16 + lr) * RS + tt * 16 + quad * 4);
;         S[dt] = __builtin_amdgcn_mfma_f32_16x16x16bf16_1k(a, vs[tt], S[dt], 0, 0, 0);
;       }
;     }
	global_store_dwordx4 v[122:123], v[112:115], off
	ds_read_b128 v[112:115], v167 offset:56320
	v_lshl_add_u64 v[122:123], s[0:1], 0, v[134:135]
	v_lshl_add_u64 v[122:123], v[122:123], 0, s[62:63]
	v_lshl_add_u64 v[122:123], v[122:123], 0, v[140:141]
	v_lshl_add_u64 v[122:123], v[122:123], 0, v[138:139]
	s_waitcnt lgkmcnt(0)
	global_store_dwordx4 v[122:123], v[112:115], off
	v_exp_f32_e32 v122, v170
	v_add_u32_e32 v170, 0x2000, v161
	v_pk_mul_f32 v[110:111], v[110:111], v[122:123] op_sel_hi:[1,0]
	v_pk_mul_f32 v[108:109], v[108:109], v[122:123] op_sel_hi:[1,0]
	v_pk_mul_f32 v[106:107], v[106:107], v[122:123] op_sel_hi:[1,0]
	v_pk_mul_f32 v[104:105], v[104:105], v[122:123] op_sel_hi:[1,0]
	s_waitcnt lgkmcnt(0)
	v_mfma_f32_16x16x16_bf16 v[108:111], v[196:197], v[142:143], v[108:111]
	v_mul_f32_e64 v102, v102, v122
	v_mul_f32_e64 v103, v103, v122
	v_pk_mul_f32 v[100:101], v[100:101], v[122:123] op_sel_hi:[1,0]
	v_pk_mul_f32 v[98:99], v[98:99], v[122:123] op_sel_hi:[1,0]
	v_mfma_f32_16x16x16_bf16 v[108:111], v[198:199], v[120:121], v[108:111]
	v_pk_mul_f32 v[96:97], v[96:97], v[122:123] op_sel_hi:[1,0]
	s_nop 1
	v_mfma_f32_16x16x16_bf16 v[108:111], v[200:201], v[116:117], v[108:111]
	v_mfma_f32_16x16x16_bf16 v[112:115], v[202:203], v[118:119], v[108:111]
	s_nop 6
	s_nop 1
	v_mfma_f32_16x16x16_bf16 v[104:107], v[204:205], v[142:143], v[104:107]
	v_mfma_f32_16x16x16_bf16 v[104:107], v[206:207], v[120:121], v[104:107]
	s_nop 1
	v_mfma_f32_16x16x16_bf16 v[104:107], v[208:209], v[116:117], v[104:107]
	v_mfma_f32_16x16x16_bf16 v[104:107], v[210:211], v[118:119], v[104:107]
	s_nop 1
	v_mfma_f32_16x16x16_bf16 v[100:103], v[212:213], v[142:143], v[100:103]
	v_mfma_f32_16x16x16_bf16 v[100:103], v[214:215], v[120:121], v[100:103]
	s_nop 1
	v_mfma_f32_16x16x16_bf16 v[100:103], v[216:217], v[116:117], v[100:103]
	v_mfma_f32_16x16x16_bf16 v[100:103], v[218:219], v[118:119], v[100:103]
	s_nop 1
	v_mfma_f32_16x16x16_bf16 v[96:99], v[234:235], v[142:143], v[96:99]
	v_mfma_f32_16x16x16_bf16 v[96:99], v[236:237], v[120:121], v[96:99]
	s_waitcnt lgkmcnt(0)
	s_barrier
	s_waitcnt lgkmcnt(0)
	v_mfma_f32_16x16x16_bf16 v[96:99], v[238:239], v[116:117], v[96:99]
	s_waitcnt vmcnt(32)
	ds_write_b128 v157, v[24:27]
	s_waitcnt vmcnt(30)
	ds_write_b128 v157, v[36:39] offset:4608
	s_waitcnt vmcnt(29)
	ds_write_b128 v157, v[40:43] offset:9216
	s_waitcnt vmcnt(28)
	ds_write_b128 v157, v[44:47] offset:13824
	ds_write_b128 v157, v[28:31] offset:18432
	ds_write_b128 v157, v[32:35] offset:23040
	v_mfma_f32_16x16x16_bf16 v[108:111], v[240:241], v[118:119], v[96:99]
	s_and_saveexec_b64 s[0:1], vcc
	s_cbranch_execz .LBB0_538
	s_waitcnt vmcnt(27)
	ds_write_b32 v158, v156 offset:27648
.LBB0_538:
	s_or_b64 exec, exec, s[0:1]
	v_add_u32_e32 v242, 0x9000, v161
	v_add_u32_e32 v243, 0x9800, v161
	v_add_u32_e32 v244, 0xa000, v161
	v_add_u32_e32 v245, 0xa800, v161
	ds_read2_b64 v[196:199], v242 offset0:64 offset1:68
	ds_read2_b64 v[200:203], v242 offset0:72 offset1:76
	ds_read2_b64 v[204:207], v243 offset0:96 offset1:100
	ds_read2_b64 v[208:211], v243 offset0:104 offset1:108
	ds_read2_b64 v[212:215], v244 offset0:128 offset1:132
	ds_read2_b64 v[216:219], v244 offset0:136 offset1:140
	ds_read2_b64 v[234:237], v245 offset0:160 offset1:164
	ds_read2_b64 v[238:241], v245 offset0:168 offset1:172
	s_add_i32 s0, s9, 6
	s_min_i32 s0, s0, s8
	s_not_b32 s1, s0
	s_add_i32 s13, s16, s1
	s_add_i32 s18, s0, s14
	s_and_b64 s[0:1], s[2:3], exec
	s_cselect_b32 s18, s18, s13
	s_ashr_i32 s19, s18, 31
	s_lshl_b64 s[20:21], s[18:19], 6
	v_lshl_add_u64 v[24:25], s[20:21], 0, v[128:129]
	v_lshlrev_b64 v[24:25], 10, v[24:25]
	v_lshl_add_u64 v[24:25], s[4:5], 0, v[24:25]
	s_mov_b64 s[62:63], s[82:83]
	v_lshl_add_u64 v[24:25], v[24:25], 0, s[62:63]
	v_lshl_add_u64 v[28:29], v[24:25], 0, v[176:177]
	v_add_co_u32_e64 v32, s[0:1], s41, v28
	v_mov_b32_e32 v97, s21
	s_nop 0
	v_addc_co_u32_e64 v33, s[0:1], 0, v29, s[0:1]
	s_lshl_b32 s0, s18, 2
	s_or_b32 s0, s0, s17
	s_ashr_i32 s1, s0, 31
	s_lshl_b64 s[0:1], s[0:1], 13
	v_or_b32_e32 v96, s20, v154
	v_lshl_add_u64 v[40:41], v[130:131], 0, s[0:1]
	v_lshlrev_b64 v[96:97], 6, v[96:97]
	v_lshl_add_u64 v[44:45], v[40:41], 0, v[176:177]
	s_movk_i32 s0, 0x1000
	v_lshl_add_u64 v[96:97], s[6:7], 0, v[96:97]
	global_load_dwordx4 v[24:27], v[28:29], off offset:512
	global_load_dwordx4 v[36:39], v[32:33], off offset:512
	s_nop 0
	global_load_dwordx4 v[28:31], v[28:29], off
	s_nop 0
	global_load_dwordx4 v[32:35], v[32:33], off
	s_add_i32 s18, s12, 1
	global_load_dwordx4 v[40:43], v[44:45], off
	global_load_dword v156, v[96:97], off
	v_add_co_u32_e64 v44, s[0:1], s0, v44
	v_mov_b32_e32 v96, s10
	s_nop 0
	v_addc_co_u32_e64 v45, s[0:1], 0, v45, s[0:1]
	s_xor_b32 s0, s9, -2
	s_add_i32 s13, s0, s16
	s_and_b64 s[0:1], s[2:3], exec
	s_cselect_b32 s0, s18, s13
	ds_read_b32 v181, v96 offset:55808
	ds_read_u16 v98, v160 offset:46880
	ds_read_u16 v142, v160 offset:53504
	v_cvt_pk_bf16_f32 v96, v112, s0
	v_cvt_pk_bf16_f32 v97, v113, s0
	v_xor_b32_e32 v96, 0x8000, v96
	v_xor_b32_e32 v97, 0x8000, v97
	s_mov_b32 s1, 0x5040100
	v_perm_b32 v150, v97, v96, s1
	v_cvt_pk_bf16_f32 v96, v104, s0
	v_cvt_pk_bf16_f32 v97, v105, s0
	v_xor_b32_e32 v96, 0x8000, v96
	v_xor_b32_e32 v97, 0x8000, v97
	v_perm_b32 v152, v97, v96, s1
	v_cvt_pk_bf16_f32 v96, v100, s0
	v_cvt_pk_bf16_f32 v97, v101, s0
	v_add_u32_e32 v183, 0x6800, v161
	v_xor_b32_e32 v96, 0x8000, v96
	v_xor_b32_e32 v97, 0x8000, v97
	ds_read2_b64 v[116:119], v183 offset0:192 offset1:196
	v_perm_b32 v126, v97, v96, s1
	v_cvt_pk_bf16_f32 v96, v108, s0
	v_cvt_pk_bf16_f32 v97, v109, s0
	v_xor_b32_e32 v96, 0x8000, v96
	v_xor_b32_e32 v97, 0x8000, v97
	v_perm_b32 v124, v97, v96, s1
	ds_read_u16 v96, v160 offset:46592
	ds_read_u16 v97, v160 offset:46736
	ds_read_u16 v99, v160 offset:47024
	v_cvt_pk_bf16_f32 v143, v114, v115
	v_xor_b32_e32 v151, 0x80008000, v143
	s_waitcnt lgkmcnt(2)
; __device__ __forceinline__ float bf2f(bf16_t h) { return __uint_as_float(((unsigned)h) << 16); }
; __device__ void dn_scan(const P& p, int item, char* smem) {
;     ...
;     for (int tt = 0; tt < 4; ++tt) {
; #pragma unroll
;       for (int j = 0; j < 4; ++j) vn[tt][j] = bf2f(sU[(tt * 16 + quad * 4 + j) * RS + w * 16 + lr]);
; #pragma unroll
;       for (int dt = 0; dt < 4; ++dt) {
;         bf16x4 a = *(const bf16x4*)(sW + (tt * 16 + lr) * RS + dt * 16 + quad * 4);
;         vn[tt] = __builtin_amdgcn_mfma_f32_16x16x16bf16_1k(a, sb[dt], vn[tt], 0, 0, 0);
;       }
;     }
;     bf16_t* hs = HST + ((size_t)(c * 4 + h) * 2 + dir) * 4096 + (w * 16 + lr) * 64;
; #pragma unroll
;     for (int dt = 0; dt < 4; ++dt) {
;       uint2 o2; o2.x = pack2(S[dt][0], S[dt][1]); o2.y = pack2(S[dt][2], S[dt][3]);
;       *(uint2*)(hs + dt * 16 + quad * 4) = o2;
;     }
;     bf16x4 vs[4];
; #pragma unroll
;     for (int tt = 0; tt < 4; ++tt) {
;       float4 g4 = *(const float4*)(sG + tt * 16 + quad * 4);
;       float sc[4] = {__expf(glog - g4.x), __expf(glog - g4.y), __expf(glog - g4.z), __expf(glog - g4.w)};
;       bf16_t vb[4];
; #pragma unroll
;       for (int j = 0; j < 4; ++j) {
;         vb[j] = f2bf(vn[tt][j]);
;         vpatch[(tt * 16 + quad * 4 + j) * 24 + lr] = vb[j];
;       }
;       unsigned u0 = pack2(bf2f(vb[0]) * sc[0], bf2f(vb[1]) * sc[1]), u1 = pack2(bf2f(vb[2]) * sc[2], bf2f(vb[3]) * sc[3]);
;       vs[tt] = (bf16x4){(short)(u0 & 0xffff), (short)(u0 >> 16), (short)(u1 & 0xffff), (short)(u1 >> 16)};
;     }
	v_lshlrev_b32_e32 v96, 16, v96
	s_waitcnt lgkmcnt(1)
	v_lshlrev_b32_e32 v97, 16, v97
	v_lshlrev_b32_e32 v98, 16, v98
	s_waitcnt lgkmcnt(0)
	v_lshlrev_b32_e32 v99, 16, v99
	v_cvt_pk_bf16_f32 v145, v106, v107
	v_xor_b32_e32 v153, 0x80008000, v145
	v_mfma_f32_16x16x16_bf16 v[96:99], v[116:117], v[150:151], v[96:99]
	v_cvt_pk_bf16_f32 v147, v102, v103
	v_xor_b32_e32 v127, 0x80008000, v147
	v_add_u32_e32 v171, 0x7000, v161
	v_mfma_f32_16x16x16_bf16 v[96:99], v[118:119], v[152:153], v[96:99]
	ds_read2_b64 v[116:119], v183 offset0:200 offset1:204
	ds_read2_b64 v[120:123], v171 offset0:224 offset1:228
	v_cvt_pk_bf16_f32 v149, v110, v111
	s_waitcnt lgkmcnt(1)
	v_mfma_f32_16x16x16_bf16 v[96:99], v[116:117], v[126:127], v[96:99]
	v_xor_b32_e32 v125, 0x80008000, v149
	ds_read_u16 v116, v160 offset:48896
	ds_read_u16 v117, v160 offset:49040
	v_mfma_f32_16x16x16_bf16 v[96:99], v[118:119], v[124:125], v[96:99]
	ds_read_u16 v118, v160 offset:49184
	ds_read_u16 v119, v160 offset:49328
	s_waitcnt lgkmcnt(3)
	v_lshlrev_b32_e32 v116, 16, v116
	s_waitcnt lgkmcnt(2)
	v_lshlrev_b32_e32 v117, 16, v117
	v_add_u32_e32 v185, 0x8000, v161
	s_waitcnt lgkmcnt(1)
	v_lshlrev_b32_e32 v118, 16, v118
	s_waitcnt lgkmcnt(0)
	v_lshlrev_b32_e32 v119, 16, v119
	ds_read2_b64 v[186:189], v185 offset1:4
	v_add_u32_e32 v172, 0x8800, v161
	v_mfma_f32_16x16x16_bf16 v[116:119], v[120:121], v[150:151], v[116:119]
	ds_read2_b64 v[190:193], v172 offset0:32 offset1:36
	s_lshl_b32 s13, s0, 2
	s_or_b32 s18, s13, s17
	v_mfma_f32_16x16x16_bf16 v[116:119], v[122:123], v[152:153], v[116:119]
	ds_read2_b64 v[120:123], v171 offset0:232 offset1:236
	s_ashr_i32 s19, s18, 31
	s_lshl_b64 s[18:19], s[18:19], 14
	s_waitcnt lgkmcnt(0)
	v_mfma_f32_16x16x16_bf16 v[116:119], v[120:121], v[126:127], v[116:119]
	v_cvt_pk_bf16_f32 v144, v104, v105
	global_load_dwordx4 v[44:47], v[44:45], off
	v_cvt_pk_bf16_f32 v96, v96, v97
	v_mfma_f32_16x16x16_bf16 v[120:123], v[122:123], v[124:125], v[116:119]
	v_lshrrev_b32_e32 v97, 16, v96
	s_ashr_i32 s1, s0, 31
	v_cvt_pk_bf16_f32 v146, v100, v101
	s_nop 0
	ds_read_u16 v116, v160 offset:51200
	ds_read_u16 v117, v160 offset:51344
	ds_read_u16 v118, v160 offset:51488
	ds_read_u16 v119, v160 offset:51632
	v_cvt_pk_bf16_f32 v120, v120, v121
	s_waitcnt lgkmcnt(3)
	v_lshlrev_b32_e32 v116, 16, v116
	s_waitcnt lgkmcnt(2)
	v_lshlrev_b32_e32 v117, 16, v117
	s_waitcnt lgkmcnt(1)
	v_lshlrev_b32_e32 v118, 16, v118
	s_waitcnt lgkmcnt(0)
	v_lshlrev_b32_e32 v119, 16, v119
	v_lshrrev_b32_e32 v121, 16, v120
	v_cvt_pk_bf16_f32 v148, v108, v109
	v_mfma_f32_16x16x16_bf16 v[116:119], v[186:187], v[150:151], v[116:119]
	s_lshl_b64 s[0:1], s[0:1], 16
	s_add_u32 s0, s4, s0
	s_addc_u32 s1, s5, s1
	v_mfma_f32_16x16x16_bf16 v[116:119], v[188:189], v[152:153], v[116:119]
	ds_read2_b64 v[186:189], v185 offset0:8 offset1:12
	v_mul_f32_e32 v173, 0x3fb8aa3b, v181
	v_add_u32_e32 v182, 0xa000, v161
	s_waitcnt lgkmcnt(0)
	v_mfma_f32_16x16x16_bf16 v[116:119], v[186:187], v[126:127], v[116:119]
	v_lshlrev_b32_e32 v186, 16, v142
	ds_read_u16 v142, v160 offset:53648
	v_add_u32_e32 v184, 0xa800, v161
	v_mfma_f32_16x16x16_bf16 v[116:119], v[188:189], v[124:125], v[116:119]
	s_waitcnt lgkmcnt(0)
	v_lshlrev_b32_e32 v187, 16, v142
	ds_read_u16 v142, v160 offset:53792
	s_waitcnt lgkmcnt(0)
	v_lshlrev_b32_e32 v188, 16, v142
	ds_read_u16 v142, v160 offset:53936
	s_nop 1
	v_cvt_pk_bf16_f32 v116, v116, v117
	v_lshrrev_b32_e32 v117, 16, v116
	s_waitcnt lgkmcnt(0)
	v_lshlrev_b32_e32 v189, 16, v142
	s_nop 1
	v_mfma_f32_16x16x16_bf16 v[186:189], v[190:191], v[150:151], v[186:189]
	v_cvt_pk_bf16_f32 v142, v112, v113
	v_mfma_f32_16x16x16_bf16 v[150:153], v[192:193], v[152:153], v[186:189]
	s_nop 5
	ds_read2_b64 v[186:189], v172 offset0:40 offset1:44
	s_waitcnt lgkmcnt(0)
	v_mfma_f32_16x16x16_bf16 v[150:153], v[186:187], v[126:127], v[150:153]
	v_mfma_f32_16x16x16_bf16 v[124:127], v[188:189], v[124:125], v[150:153]
	s_nop 6
	v_lshl_add_u64 v[150:151], v[136:137], 0, s[18:19]
	global_store_dwordx2 v[150:151], v[142:143], off
	global_store_dwordx2 v[150:151], v[144:145], off offset:32
	ds_read_b128 v[142:145], v162 offset:55808
	ds_write_b16 v163, v96 offset:56320
	ds_write_b16 v164, v97 offset:56368
	v_and_b32_e32 v97, 0xffff0000, v96
	v_lshlrev_b32_e32 v96, 16, v96
	s_waitcnt lgkmcnt(2)
	v_sub_f32_e32 v142, v181, v142
	v_sub_f32_e32 v143, v181, v143
	v_mul_f32_e32 v142, 0x3fb8aa3b, v142
	v_mul_f32_e32 v143, 0x3fb8aa3b, v143
	v_exp_f32_e32 v142, v142
	v_exp_f32_e32 v143, v143
	v_sub_f32_e32 v144, v181, v144
	v_sub_f32_e32 v145, v181, v145
	v_mul_f32_e32 v144, 0x3fb8aa3b, v144
	v_mul_f32_e32 v145, 0x3fb8aa3b, v145
	v_exp_f32_e32 v144, v144
	v_exp_f32_e32 v145, v145
	v_pk_mul_f32 v[96:97], v[142:143], v[96:97]
	global_store_dwordx2 v[150:151], v[146:147], off offset:64
	v_cvt_pk_bf16_f32 v142, v96, v97
	v_cvt_pk_bf16_f32 v96, v98, v99
	v_lshrrev_b32_e32 v97, 16, v96
	ds_write_b16 v163, v96 offset:56416
	ds_write_b16 v164, v97 offset:56464
	v_and_b32_e32 v97, 0xffff0000, v96
	v_lshlrev_b32_e32 v96, 16, v96
	v_pk_mul_f32 v[96:97], v[144:145], v[96:97]
	global_store_dwordx2 v[150:151], v[148:149], off offset:96
	v_cvt_pk_bf16_f32 v143, v96, v97
	ds_read_b128 v[96:99], v162 offset:55872
	ds_write_b16 v163, v120 offset:57088
	ds_write_b16 v164, v121 offset:57136
	v_and_b32_e32 v121, 0xffff0000, v120
	v_lshlrev_b32_e32 v120, 16, v120
	s_waitcnt lgkmcnt(2)
; __device__ __forceinline__ float bf2f(bf16_t h) { return __uint_as_float(((unsigned)h) << 16); }
; __device__ void dn_scan(const P& p, int item, char* smem) {
;     ...
;     for (int tt = 0; tt < 4; ++tt) {
;       float4 g4 = *(const float4*)(sG + tt * 16 + quad * 4);
;       float sc[4] = {__expf(glog - g4.x), __expf(glog - g4.y), __expf(glog - g4.z), __expf(glog - g4.w)};
;       bf16_t vb[4];
; #pragma unroll
;       for (int j = 0; j < 4; ++j) {
;         vb[j] = f2bf(vn[tt][j]);
;         vpatch[(tt * 16 + quad * 4 + j) * 24 + lr] = vb[j];
;       }
;       unsigned u0 = pack2(bf2f(vb[0]) * sc[0], bf2f(vb[1]) * sc[1]), u1 = pack2(bf2f(vb[2]) * sc[2], bf2f(vb[3]) * sc[3]);
;       vs[tt] = (bf16x4){(short)(u0 & 0xffff), (short)(u0 >> 16), (short)(u1 & 0xffff), (short)(u1 >> 16)};
;     }
;     asm volatile("" ::: "memory");
; #pragma unroll
;     for (int i = 0; i < 2; ++i) {
;       const int idx = i * 64 + lane, t = idx >> 1, hf = idx & 1;
;       uint4 v4 = *(const uint4*)(vpatch + t * 24 + hf * 8);
;       *(uint4*)(UW + (tok0 + t) * 512 + h * 64 + w * 16 + hf * 8) = v4;
;     }
;     asm volatile("" ::: "memory");
; #pragma unroll
;     for (int dt = 0; dt < 4; ++dt) {
;       S[dt][0] *= gl; S[dt][1] *= gl; S[dt][2] *= gl; S[dt][3] *= gl;
; #pragma unroll
;       for (int tt = 0; tt < 4; ++tt) {
;         bf16x4 a = *(const bf16x4*)(sK + (dt * 16 + lr) * RS + tt * 16 + quad * 4);
;         S[dt] = __builtin_amdgcn_mfma_f32_16x16x16bf16_1k(a, vs[tt], S[dt], 0, 0, 0);
;       }
;     }
	v_sub_f32_e32 v96, v181, v96
	v_sub_f32_e32 v97, v181, v97
	v_mul_f32_e32 v96, 0x3fb8aa3b, v96
	v_mul_f32_e32 v97, 0x3fb8aa3b, v97
	v_exp_f32_e32 v96, v96
	v_exp_f32_e32 v97, v97
	v_sub_f32_e32 v98, v181, v98
	v_sub_f32_e32 v99, v181, v99
	v_mul_f32_e32 v98, 0x3fb8aa3b, v98
	v_mul_f32_e32 v99, 0x3fb8aa3b, v99
	v_exp_f32_e32 v98, v98
	v_exp_f32_e32 v99, v99
	v_pk_mul_f32 v[96:97], v[96:97], v[120:121]
	s_nop 0
	v_cvt_pk_bf16_f32 v120, v96, v97
	v_cvt_pk_bf16_f32 v96, v122, v123
	v_lshrrev_b32_e32 v97, 16, v96
	ds_write_b16 v163, v96 offset:57184
	ds_write_b16 v164, v97 offset:57232
	v_and_b32_e32 v97, 0xffff0000, v96
	v_lshlrev_b32_e32 v96, 16, v96
	v_pk_mul_f32 v[96:97], v[98:99], v[96:97]
	v_lshl_add_u64 v[122:123], s[0:1], 0, v[132:133]
	v_cvt_pk_bf16_f32 v121, v96, v97
	ds_read_b128 v[96:99], v162 offset:55936
	ds_write_b16 v163, v116 offset:57856
	ds_write_b16 v164, v117 offset:57904
	v_and_b32_e32 v117, 0xffff0000, v116
	v_lshlrev_b32_e32 v116, 16, v116
	s_waitcnt lgkmcnt(2)
	v_sub_f32_e32 v96, v181, v96
	v_sub_f32_e32 v97, v181, v97
	v_mul_f32_e32 v96, 0x3fb8aa3b, v96
	v_mul_f32_e32 v97, 0x3fb8aa3b, v97
	v_exp_f32_e32 v96, v96
	v_exp_f32_e32 v97, v97
	v_sub_f32_e32 v98, v181, v98
	v_sub_f32_e32 v99, v181, v99
	v_mul_f32_e32 v98, 0x3fb8aa3b, v98
	v_mul_f32_e32 v99, 0x3fb8aa3b, v99
	v_exp_f32_e32 v98, v98
	v_exp_f32_e32 v99, v99
	v_pk_mul_f32 v[96:97], v[96:97], v[116:117]
	v_lshl_add_u64 v[122:123], v[122:123], 0, s[62:63]
	v_cvt_pk_bf16_f32 v116, v96, v97
	v_cvt_pk_bf16_f32 v96, v118, v119
	v_lshrrev_b32_e32 v97, 16, v96
	ds_write_b16 v163, v96 offset:57952
	ds_write_b16 v164, v97 offset:58000
	v_and_b32_e32 v97, 0xffff0000, v96
	v_lshlrev_b32_e32 v96, 16, v96
	v_pk_mul_f32 v[96:97], v[98:99], v[96:97]
	v_cvt_pk_bf16_f32 v118, v124, v125
	v_cvt_pk_bf16_f32 v117, v96, v97
	ds_read_b128 v[96:99], v162 offset:56000
	v_lshrrev_b32_e32 v119, 16, v118
	ds_write_b16 v163, v118 offset:58624
	ds_write_b16 v164, v119 offset:58672
	v_and_b32_e32 v119, 0xffff0000, v118
	s_waitcnt lgkmcnt(2)
	v_sub_f32_e32 v96, v181, v96
	v_sub_f32_e32 v97, v181, v97
	v_mul_f32_e32 v96, 0x3fb8aa3b, v96
	v_mul_f32_e32 v97, 0x3fb8aa3b, v97
	v_exp_f32_e32 v96, v96
	v_exp_f32_e32 v97, v97
	v_sub_f32_e32 v98, v181, v98
	v_sub_f32_e32 v99, v181, v99
	v_mul_f32_e32 v98, 0x3fb8aa3b, v98
	v_mul_f32_e32 v99, 0x3fb8aa3b, v99
	v_lshlrev_b32_e32 v118, 16, v118
	v_exp_f32_e32 v98, v98
	v_exp_f32_e32 v99, v99
	v_pk_mul_f32 v[96:97], v[96:97], v[118:119]
	v_lshl_add_u64 v[122:123], v[122:123], 0, v[140:141]
	v_cvt_pk_bf16_f32 v118, v96, v97
	v_cvt_pk_bf16_f32 v96, v126, v127
	v_lshrrev_b32_e32 v97, 16, v96
	ds_write_b16 v163, v96 offset:58720
	ds_write_b16 v164, v97 offset:58768
	v_and_b32_e32 v97, 0xffff0000, v96
	v_lshlrev_b32_e32 v96, 16, v96
	v_pk_mul_f32 v[96:97], v[98:99], v[96:97]
	v_lshl_add_u64 v[122:123], v[122:123], 0, v[138:139]
	v_cvt_pk_bf16_f32 v119, v96, v97
	ds_read_b128 v[96:99], v166 offset:56320
	v_add_u32_e32 v181, 0x9800, v161
	s_waitcnt lgkmcnt(0)
	global_store_dwordx4 v[122:123], v[96:99], off
	ds_read_b128 v[96:99], v167 offset:56320
	v_lshl_add_u64 v[122:123], s[0:1], 0, v[134:135]
	v_lshl_add_u64 v[122:123], v[122:123], 0, s[62:63]
	v_lshl_add_u64 v[122:123], v[122:123], 0, v[140:141]
	v_lshl_add_u64 v[122:123], v[122:123], 0, v[138:139]
	s_waitcnt lgkmcnt(0)
	global_store_dwordx4 v[122:123], v[96:99], off
	v_exp_f32_e32 v122, v173
	v_add_u32_e32 v173, 0x9000, v161
	v_pk_mul_f32 v[98:99], v[114:115], v[122:123] op_sel_hi:[1,0]
	v_pk_mul_f32 v[96:97], v[112:113], v[122:123] op_sel_hi:[1,0]
	v_pk_mul_f32 v[102:103], v[102:103], v[122:123] op_sel_hi:[1,0]
	s_waitcnt lgkmcnt(0)
	v_mfma_f32_16x16x16_bf16 v[96:99], v[196:197], v[142:143], v[96:99]
	v_mul_f32_e64 v100, v100, v122
	v_mul_f32_e64 v101, v101, v122
	v_mfma_f32_16x16x16_bf16 v[96:99], v[198:199], v[120:121], v[96:99]
	s_nop 1
	v_mfma_f32_16x16x16_bf16 v[96:99], v[200:201], v[116:117], v[96:99]
	v_mfma_f32_16x16x16_bf16 v[112:115], v[202:203], v[118:119], v[96:99]
	s_nop 6
	v_mul_f32_e64 v98, v106, v122
	v_mul_f32_e64 v99, v107, v122
	v_pk_mul_f32 v[96:97], v[104:105], v[122:123] op_sel_hi:[1,0]
	s_nop 1
	v_mfma_f32_16x16x16_bf16 v[96:99], v[204:205], v[142:143], v[96:99]
	v_mfma_f32_16x16x16_bf16 v[96:99], v[206:207], v[120:121], v[96:99]
	s_nop 1
	v_mfma_f32_16x16x16_bf16 v[96:99], v[208:209], v[116:117], v[96:99]
	v_mfma_f32_16x16x16_bf16 v[96:99], v[210:211], v[118:119], v[96:99]
	s_nop 1
	v_mfma_f32_16x16x16_bf16 v[100:103], v[212:213], v[142:143], v[100:103]
	v_mfma_f32_16x16x16_bf16 v[100:103], v[214:215], v[120:121], v[100:103]
	s_nop 1
	v_mfma_f32_16x16x16_bf16 v[100:103], v[216:217], v[116:117], v[100:103]
	v_mul_f32_e64 v104, v108, v122
	v_mul_f32_e64 v105, v109, v122
	v_mfma_f32_16x16x16_bf16 v[100:103], v[218:219], v[118:119], v[100:103]
	v_mul_f32_e64 v106, v110, v122
	v_mul_f32_e64 v107, v111, v122
	s_nop 1
	v_mfma_f32_16x16x16_bf16 v[104:107], v[234:235], v[142:143], v[104:107]
	v_mfma_f32_16x16x16_bf16 v[104:107], v[236:237], v[120:121], v[104:107]
	s_waitcnt lgkmcnt(0)
	s_barrier
	s_waitcnt lgkmcnt(0)
	v_mfma_f32_16x16x16_bf16 v[104:107], v[238:239], v[116:117], v[104:107]
	s_waitcnt vmcnt(39)
	ds_write_b128 v157, v[48:51] offset:28160
	s_waitcnt vmcnt(37)
	ds_write_b128 v157, v[60:63] offset:32768
	s_waitcnt vmcnt(35)
	ds_write_b128 v157, v[64:67] offset:37376
	s_waitcnt vmcnt(34)
	ds_write_b128 v157, v[68:71] offset:41984
	ds_write_b128 v157, v[52:55] offset:46592
	ds_write_b128 v157, v[56:59] offset:51200
	v_mfma_f32_16x16x16_bf16 v[104:107], v[240:241], v[118:119], v[104:107]
	s_and_saveexec_b64 s[0:1], vcc
	s_cbranch_execz .LBB0_540
	s_waitcnt vmcnt(33)
	ds_write_b32 v158, v159 offset:55808
; __device__ __forceinline__ float bf2f(bf16_t h) { return __uint_as_float(((unsigned)h) << 16); }
; __device__ void dn_scan(const P& p, int item, char* smem) {
;     ...
;     const int c = dir ? chunk0 + nch - 1 - step : chunk0 + step;
;     const size_t tok0 = (size_t)c * 64;
;     const char* b = smem + (step & 1) * BUF;
;     const bf16_t* sW = (const bf16_t*)b;
;     const bf16_t* sK = (const bf16_t*)(b + 64 * RS * 2);
;     const bf16_t* sU = (const bf16_t*)(b + 2 * 64 * RS * 2);
;     const float* sG = (const float*)(b + 3 * 64 * RS * 2);
;     const float glog = sG[dir ? 0 : 63];
;     const float gl = __expf(glog);
;     f32x4 vn[4];
;     bf16x4 sb[4];
; #pragma unroll
;     for (int dt = 0; dt < 4; ++dt) {
;       unsigned u0 = pack2(-S[dt][0], -S[dt][1]), u1 = pack2(-S[dt][2], -S[dt][3]);
;       sb[dt] = (bf16x4){(short)(u0 & 0xffff), (short)(u0 >> 16), (short)(u1 & 0xffff), (short)(u1 >> 16)};
;     }
; #pragma unroll
;     for (int tt = 0; tt < 4; ++tt) {
; #pragma unroll
;       for (int j = 0; j < 4; ++j) vn[tt][j] = bf2f(sU[(tt * 16 + quad * 4 + j) * RS + w * 16 + lr]);
; #pragma unroll
;       for (int dt = 0; dt < 4; ++dt) {
;         bf16x4 a = *(const bf16x4*)(sW + (tt * 16 + lr) * RS + dt * 16 + quad * 4);
;         vn[tt] = __builtin_amdgcn_mfma_f32_16x16x16bf16_1k(a, sb[dt], vn[tt], 0, 0, 0);
;       }
;     }
.LBB0_540:
	s_or_b64 exec, exec, s[0:1]
	v_add_u32_e32 v242, 0x2000, v161
	v_add_u32_e32 v243, 0x2800, v161
	v_add_u32_e32 v244, 0x3000, v161
	v_add_u32_e32 v245, 0x3800, v161
	ds_read2_b64 v[196:199], v242 offset0:128 offset1:132
	ds_read2_b64 v[200:203], v242 offset0:136 offset1:140
	ds_read2_b64 v[204:207], v243 offset0:160 offset1:164
	ds_read2_b64 v[208:211], v243 offset0:168 offset1:172
	ds_read2_b64 v[212:215], v244 offset0:192 offset1:196
	ds_read2_b64 v[216:219], v244 offset0:200 offset1:204
	ds_read2_b64 v[234:237], v245 offset0:224 offset1:228
	ds_read2_b64 v[238:241], v245 offset0:232 offset1:236
	s_add_i32 s0, s9, 7
	s_min_i32 s0, s0, s8
	s_not_b32 s1, s0
	s_add_i32 s13, s16, s1
	s_add_i32 s18, s0, s14
	s_and_b64 s[0:1], s[2:3], exec
	s_cselect_b32 s18, s18, s13
	s_ashr_i32 s19, s18, 31
	s_lshl_b64 s[20:21], s[18:19], 6
	v_lshl_add_u64 v[48:49], s[20:21], 0, v[128:129]
	v_lshlrev_b64 v[48:49], 10, v[48:49]
	v_lshl_add_u64 v[48:49], s[4:5], 0, v[48:49]
	s_mov_b64 s[62:63], s[82:83]
	v_lshl_add_u64 v[48:49], v[48:49], 0, s[62:63]
	v_lshl_add_u64 v[52:53], v[48:49], 0, v[176:177]
	v_add_co_u32_e64 v56, s[0:1], s41, v52
	v_mov_b32_e32 v109, s21
	s_nop 0
	v_addc_co_u32_e64 v57, s[0:1], 0, v53, s[0:1]
	s_lshl_b32 s0, s18, 2
	s_or_b32 s0, s0, s17
	s_ashr_i32 s1, s0, 31
	s_lshl_b64 s[0:1], s[0:1], 13
	v_or_b32_e32 v108, s20, v154
	v_lshl_add_u64 v[64:65], v[130:131], 0, s[0:1]
	v_lshlrev_b64 v[108:109], 6, v[108:109]
	v_lshl_add_u64 v[68:69], v[64:65], 0, v[176:177]
	s_movk_i32 s0, 0x1000
	v_lshl_add_u64 v[108:109], s[6:7], 0, v[108:109]
	global_load_dwordx4 v[48:51], v[52:53], off offset:512
	global_load_dwordx4 v[60:63], v[56:57], off offset:512
	s_nop 0
	global_load_dwordx4 v[52:55], v[52:53], off
	s_nop 0
	global_load_dwordx4 v[56:59], v[56:57], off
	s_add_i32 s18, s12, 2
	global_load_dwordx4 v[64:67], v[68:69], off
	global_load_dword v159, v[108:109], off
	v_add_co_u32_e64 v68, s[0:1], s0, v68
	v_mov_b32_e32 v108, s10
	s_nop 0
	v_addc_co_u32_e64 v69, s[0:1], 0, v69, s[0:1]
	s_xor_b32 s0, s9, -3
	s_add_i32 s13, s0, s16
	s_and_b64 s[0:1], s[2:3], exec
	s_cselect_b32 s0, s18, s13
	ds_read_b32 v139, v108 offset:27648
	ds_read_u16 v110, v160 offset:18720
	ds_read_u16 v142, v160 offset:25344
	v_cvt_pk_bf16_f32 v108, v112, s0
	v_cvt_pk_bf16_f32 v109, v113, s0
	v_xor_b32_e32 v108, 0x8000, v108
	v_xor_b32_e32 v109, 0x8000, v109
	s_mov_b32 s1, 0x5040100
	v_perm_b32 v150, v109, v108, s1
	v_cvt_pk_bf16_f32 v108, v96, s0
	v_cvt_pk_bf16_f32 v109, v97, s0
	v_xor_b32_e32 v108, 0x8000, v108
	v_xor_b32_e32 v109, 0x8000, v109
	v_perm_b32 v152, v109, v108, s1
	v_cvt_pk_bf16_f32 v108, v100, s0
	v_cvt_pk_bf16_f32 v109, v101, s0
	v_xor_b32_e32 v108, 0x8000, v108
	v_xor_b32_e32 v109, 0x8000, v109
	ds_read2_b64 v[116:119], v161 offset1:4
	v_perm_b32 v126, v109, v108, s1
	v_cvt_pk_bf16_f32 v108, v104, s0
	v_cvt_pk_bf16_f32 v109, v105, s0
	v_xor_b32_e32 v108, 0x8000, v108
	v_xor_b32_e32 v109, 0x8000, v109
	v_perm_b32 v124, v109, v108, s1
	ds_read_u16 v108, v160 offset:18432
	ds_read_u16 v109, v160 offset:18576
	ds_read_u16 v111, v160 offset:18864
	v_cvt_pk_bf16_f32 v143, v114, v115
	v_xor_b32_e32 v151, 0x80008000, v143
	s_waitcnt lgkmcnt(2)
	v_lshlrev_b32_e32 v108, 16, v108
	s_waitcnt lgkmcnt(1)
	v_lshlrev_b32_e32 v109, 16, v109
	v_lshlrev_b32_e32 v110, 16, v110
	s_waitcnt lgkmcnt(0)
	v_lshlrev_b32_e32 v111, 16, v111
	v_cvt_pk_bf16_f32 v145, v98, v99
	v_xor_b32_e32 v153, 0x80008000, v145
	v_mfma_f32_16x16x16_bf16 v[108:111], v[116:117], v[150:151], v[108:111]
	v_cvt_pk_bf16_f32 v147, v102, v103
	v_xor_b32_e32 v127, 0x80008000, v147
	ds_read2_b64 v[120:123], v169 offset0:32 offset1:36
	v_mfma_f32_16x16x16_bf16 v[108:111], v[118:119], v[152:153], v[108:111]
	ds_read2_b64 v[116:119], v161 offset0:8 offset1:12
	v_cvt_pk_bf16_f32 v149, v106, v107
	v_xor_b32_e32 v125, 0x80008000, v149
	s_waitcnt lgkmcnt(0)
	v_mfma_f32_16x16x16_bf16 v[108:111], v[116:117], v[126:127], v[108:111]
	ds_read_u16 v116, v160 offset:20736
	ds_read_u16 v117, v160 offset:20880
	ds_read2_b64 v[188:191], v179 offset0:64 offset1:68
	v_mfma_f32_16x16x16_bf16 v[108:111], v[118:119], v[124:125], v[108:111]
	ds_read_u16 v118, v160 offset:21024
	ds_read_u16 v119, v160 offset:21168
	s_waitcnt lgkmcnt(4)
	v_lshlrev_b32_e32 v116, 16, v116
	s_waitcnt lgkmcnt(3)
	v_lshlrev_b32_e32 v117, 16, v117
	ds_read2_b64 v[192:195], v168 offset0:96 offset1:100
	s_waitcnt lgkmcnt(2)
	v_lshlrev_b32_e32 v118, 16, v118
	s_waitcnt lgkmcnt(1)
	v_lshlrev_b32_e32 v119, 16, v119
	s_lshl_b32 s13, s0, 2
	s_or_b32 s18, s13, s17
	v_mfma_f32_16x16x16_bf16 v[116:119], v[120:121], v[150:151], v[116:119]
	s_ashr_i32 s19, s18, 31
	s_lshl_b64 s[18:19], s[18:19], 14
	v_cvt_pk_bf16_f32 v144, v96, v97
	v_mfma_f32_16x16x16_bf16 v[116:119], v[122:123], v[152:153], v[116:119]
	ds_read2_b64 v[120:123], v169 offset0:40 offset1:44
	global_load_dwordx4 v[68:71], v[68:69], off
	v_cvt_pk_bf16_f32 v108, v108, v109
	s_waitcnt lgkmcnt(0)
	v_mfma_f32_16x16x16_bf16 v[116:119], v[120:121], v[126:127], v[116:119]
	v_lshrrev_b32_e32 v109, 16, v108
	s_ashr_i32 s1, s0, 31
	v_cvt_pk_bf16_f32 v146, v100, v101
	v_mfma_f32_16x16x16_bf16 v[120:123], v[122:123], v[124:125], v[116:119]
	v_cvt_pk_bf16_f32 v148, v104, v105
	s_lshl_b64 s[0:1], s[0:1], 16
	s_add_u32 s0, s4, s0
	s_nop 0
	ds_read_u16 v116, v160 offset:23040
	ds_read_u16 v117, v160 offset:23184
	ds_read_u16 v118, v160 offset:23328
	ds_read_u16 v119, v160 offset:23472
	v_cvt_pk_bf16_f32 v120, v120, v121
	s_waitcnt lgkmcnt(3)
	v_lshlrev_b32_e32 v116, 16, v116
	s_waitcnt lgkmcnt(2)
	v_lshlrev_b32_e32 v117, 16, v117
	s_waitcnt lgkmcnt(1)
	v_lshlrev_b32_e32 v118, 16, v118
	s_waitcnt lgkmcnt(0)
; __device__ __forceinline__ float bf2f(bf16_t h) { return __uint_as_float(((unsigned)h) << 16); }
; __device__ void dn_scan(const P& p, int item, char* smem) {
;     ...
;     for (int tt = 0; tt < 4; ++tt) {
; #pragma unroll
;       for (int j = 0; j < 4; ++j) vn[tt][j] = bf2f(sU[(tt * 16 + quad * 4 + j) * RS + w * 16 + lr]);
; #pragma unroll
;       for (int dt = 0; dt < 4; ++dt) {
;         bf16x4 a = *(const bf16x4*)(sW + (tt * 16 + lr) * RS + dt * 16 + quad * 4);
;         vn[tt] = __builtin_amdgcn_mfma_f32_16x16x16bf16_1k(a, sb[dt], vn[tt], 0, 0, 0);
;       }
;     }
;     bf16_t* hs = HST + ((size_t)(c * 4 + h) * 2 + dir) * 4096 + (w * 16 + lr) * 64;
; #pragma unroll
;     for (int dt = 0; dt < 4; ++dt) {
;       uint2 o2; o2.x = pack2(S[dt][0], S[dt][1]); o2.y = pack2(S[dt][2], S[dt][3]);
;       *(uint2*)(hs + dt * 16 + quad * 4) = o2;
;     }
;     bf16x4 vs[4];
; #pragma unroll
;     for (int tt = 0; tt < 4; ++tt) {
;       float4 g4 = *(const float4*)(sG + tt * 16 + quad * 4);
;       float sc[4] = {__expf(glog - g4.x), __expf(glog - g4.y), __expf(glog - g4.z), __expf(glog - g4.w)};
;       bf16_t vb[4];
; #pragma unroll
;       for (int j = 0; j < 4; ++j) {
;         vb[j] = f2bf(vn[tt][j]);
;         vpatch[(tt * 16 + quad * 4 + j) * 24 + lr] = vb[j];
;       }
;       unsigned u0 = pack2(bf2f(vb[0]) * sc[0], bf2f(vb[1]) * sc[1]), u1 = pack2(bf2f(vb[2]) * sc[2], bf2f(vb[3]) * sc[3]);
;       vs[tt] = (bf16x4){(short)(u0 & 0xffff), (short)(u0 >> 16), (short)(u1 & 0xffff), (short)(u1 >> 16)};
;     }
	v_lshlrev_b32_e32 v119, 16, v119
	v_lshrrev_b32_e32 v121, 16, v120
	s_addc_u32 s1, s5, s1
	v_mfma_f32_16x16x16_bf16 v[116:119], v[188:189], v[150:151], v[116:119]
	v_mul_f32_e32 v186, 0x3fb8aa3b, v139
	v_mfma_f32_16x16x16_bf16 v[116:119], v[190:191], v[152:153], v[116:119]
	ds_read2_b64 v[188:191], v179 offset0:72 offset1:76
	s_waitcnt lgkmcnt(0)
	v_mfma_f32_16x16x16_bf16 v[116:119], v[188:189], v[126:127], v[116:119]
	v_lshlrev_b32_e32 v188, 16, v142
	ds_read_u16 v142, v160 offset:25488
	s_waitcnt lgkmcnt(0)
	v_lshlrev_b32_e32 v189, 16, v142
	ds_read_u16 v142, v160 offset:25632
	v_mfma_f32_16x16x16_bf16 v[116:119], v[190:191], v[124:125], v[116:119]
	s_waitcnt lgkmcnt(0)
	v_lshlrev_b32_e32 v190, 16, v142
	ds_read_u16 v142, v160 offset:25776
	s_nop 4
	v_cvt_pk_bf16_f32 v116, v116, v117
	v_lshrrev_b32_e32 v117, 16, v116
	s_waitcnt lgkmcnt(0)
	v_lshlrev_b32_e32 v191, 16, v142
	s_nop 1
	v_mfma_f32_16x16x16_bf16 v[188:191], v[192:193], v[150:151], v[188:191]
	v_cvt_pk_bf16_f32 v142, v112, v113
	v_mfma_f32_16x16x16_bf16 v[150:153], v[194:195], v[152:153], v[188:191]
	s_nop 5
	ds_read2_b64 v[188:191], v168 offset0:104 offset1:108
	s_waitcnt lgkmcnt(0)
	v_mfma_f32_16x16x16_bf16 v[150:153], v[188:189], v[126:127], v[150:153]
	v_mfma_f32_16x16x16_bf16 v[124:127], v[190:191], v[124:125], v[150:153]
	s_nop 6
	v_lshl_add_u64 v[150:151], v[136:137], 0, s[18:19]
	global_store_dwordx2 v[150:151], v[142:143], off
	global_store_dwordx2 v[150:151], v[144:145], off offset:32
	ds_read_b128 v[142:145], v162 offset:27648
	ds_write_b16 v163, v108 offset:56320
	ds_write_b16 v164, v109 offset:56368
	v_and_b32_e32 v109, 0xffff0000, v108
	v_lshlrev_b32_e32 v108, 16, v108
	s_waitcnt lgkmcnt(2)
	v_sub_f32_e32 v142, v139, v142
	v_sub_f32_e32 v143, v139, v143
	v_mul_f32_e32 v142, 0x3fb8aa3b, v142
	v_mul_f32_e32 v143, 0x3fb8aa3b, v143
	v_exp_f32_e32 v142, v142
	v_exp_f32_e32 v143, v143
	v_sub_f32_e32 v144, v139, v144
	v_sub_f32_e32 v145, v139, v145
	v_mul_f32_e32 v144, 0x3fb8aa3b, v144
	v_mul_f32_e32 v145, 0x3fb8aa3b, v145
	v_exp_f32_e32 v144, v144
	v_exp_f32_e32 v145, v145
	v_pk_mul_f32 v[108:109], v[142:143], v[108:109]
	global_store_dwordx2 v[150:151], v[146:147], off offset:64
	v_cvt_pk_bf16_f32 v142, v108, v109
	v_cvt_pk_bf16_f32 v108, v110, v111
	v_lshrrev_b32_e32 v109, 16, v108
	ds_write_b16 v163, v108 offset:56416
	ds_write_b16 v164, v109 offset:56464
	v_and_b32_e32 v109, 0xffff0000, v108
	v_lshlrev_b32_e32 v108, 16, v108
	v_pk_mul_f32 v[108:109], v[144:145], v[108:109]
	global_store_dwordx2 v[150:151], v[148:149], off offset:96
	v_cvt_pk_bf16_f32 v143, v108, v109
	ds_read_b128 v[108:111], v162 offset:27712
	ds_write_b16 v163, v120 offset:57088
	ds_write_b16 v164, v121 offset:57136
	v_and_b32_e32 v121, 0xffff0000, v120
	v_lshlrev_b32_e32 v120, 16, v120
	s_waitcnt lgkmcnt(2)
	v_sub_f32_e32 v108, v139, v108
	v_sub_f32_e32 v109, v139, v109
	v_mul_f32_e32 v108, 0x3fb8aa3b, v108
	v_mul_f32_e32 v109, 0x3fb8aa3b, v109
	v_exp_f32_e32 v108, v108
	v_exp_f32_e32 v109, v109
	v_sub_f32_e32 v110, v139, v110
	v_sub_f32_e32 v111, v139, v111
	v_mul_f32_e32 v110, 0x3fb8aa3b, v110
	v_mul_f32_e32 v111, 0x3fb8aa3b, v111
	v_exp_f32_e32 v110, v110
	v_exp_f32_e32 v111, v111
	v_pk_mul_f32 v[108:109], v[108:109], v[120:121]
	s_nop 0
	v_cvt_pk_bf16_f32 v120, v108, v109
	v_cvt_pk_bf16_f32 v108, v122, v123
	v_lshrrev_b32_e32 v109, 16, v108
	ds_write_b16 v163, v108 offset:57184
	ds_write_b16 v164, v109 offset:57232
	v_and_b32_e32 v109, 0xffff0000, v108
	v_lshlrev_b32_e32 v108, 16, v108
	v_pk_mul_f32 v[108:109], v[110:111], v[108:109]
	v_lshl_add_u64 v[122:123], s[0:1], 0, v[132:133]
	v_cvt_pk_bf16_f32 v121, v108, v109
	ds_read_b128 v[108:111], v162 offset:27776
	ds_write_b16 v163, v116 offset:57856
	ds_write_b16 v164, v117 offset:57904
	v_and_b32_e32 v117, 0xffff0000, v116
	v_lshlrev_b32_e32 v116, 16, v116
	s_waitcnt lgkmcnt(2)
; __device__ __forceinline__ float bf2f(bf16_t h) { return __uint_as_float(((unsigned)h) << 16); }
; __device__ void dn_scan(const P& p, int item, char* smem) {
;     ...
;     for (int tt = 0; tt < 4; ++tt) {
;       float4 g4 = *(const float4*)(sG + tt * 16 + quad * 4);
;       float sc[4] = {__expf(glog - g4.x), __expf(glog - g4.y), __expf(glog - g4.z), __expf(glog - g4.w)};
;       bf16_t vb[4];
; #pragma unroll
;       for (int j = 0; j < 4; ++j) {
;         vb[j] = f2bf(vn[tt][j]);
;         vpatch[(tt * 16 + quad * 4 + j) * 24 + lr] = vb[j];
;       }
;       unsigned u0 = pack2(bf2f(vb[0]) * sc[0], bf2f(vb[1]) * sc[1]), u1 = pack2(bf2f(vb[2]) * sc[2], bf2f(vb[3]) * sc[3]);
;       vs[tt] = (bf16x4){(short)(u0 & 0xffff), (short)(u0 >> 16), (short)(u1 & 0xffff), (short)(u1 >> 16)};
;     }
;     asm volatile("" ::: "memory");
; #pragma unroll
;     for (int i = 0; i < 2; ++i) {
;       const int idx = i * 64 + lane, t = idx >> 1, hf = idx & 1;
;       uint4 v4 = *(const uint4*)(vpatch + t * 24 + hf * 8);
;       *(uint4*)(UW + (tok0 + t) * 512 + h * 64 + w * 16 + hf * 8) = v4;
;     }
;     asm volatile("" ::: "memory");
; #pragma unroll
;     for (int dt = 0; dt < 4; ++dt) {
;       S[dt][0] *= gl; S[dt][1] *= gl; S[dt][2] *= gl; S[dt][3] *= gl;
; #pragma unroll
;       for (int tt = 0; tt < 4; ++tt) {
;         bf16x4 a = *(const bf16x4*)(sK + (dt * 16 + lr) * RS + tt * 16 + quad * 4);
;         S[dt] = __builtin_amdgcn_mfma_f32_16x16x16bf16_1k(a, vs[tt], S[dt], 0, 0, 0);
;       }
;     }
	v_sub_f32_e32 v108, v139, v108
	v_sub_f32_e32 v109, v139, v109
	v_mul_f32_e32 v108, 0x3fb8aa3b, v108
	v_mul_f32_e32 v109, 0x3fb8aa3b, v109
	v_exp_f32_e32 v108, v108
	v_exp_f32_e32 v109, v109
	v_sub_f32_e32 v110, v139, v110
	v_sub_f32_e32 v111, v139, v111
	v_mul_f32_e32 v110, 0x3fb8aa3b, v110
	v_mul_f32_e32 v111, 0x3fb8aa3b, v111
	v_exp_f32_e32 v110, v110
	v_exp_f32_e32 v111, v111
	v_pk_mul_f32 v[108:109], v[108:109], v[116:117]
	v_lshl_add_u64 v[122:123], v[122:123], 0, s[62:63]
	v_cvt_pk_bf16_f32 v116, v108, v109
	v_cvt_pk_bf16_f32 v108, v118, v119
	v_lshrrev_b32_e32 v109, 16, v108
	ds_write_b16 v163, v108 offset:57952
	ds_write_b16 v164, v109 offset:58000
	v_and_b32_e32 v109, 0xffff0000, v108
	v_lshlrev_b32_e32 v108, 16, v108
	v_pk_mul_f32 v[108:109], v[110:111], v[108:109]
	v_cvt_pk_bf16_f32 v118, v124, v125
	v_cvt_pk_bf16_f32 v117, v108, v109
	ds_read_b128 v[108:111], v162 offset:27840
	v_lshrrev_b32_e32 v119, 16, v118
	ds_write_b16 v163, v118 offset:58624
	ds_write_b16 v164, v119 offset:58672
	v_and_b32_e32 v119, 0xffff0000, v118
	s_waitcnt lgkmcnt(2)
	v_sub_f32_e32 v108, v139, v108
	v_sub_f32_e32 v109, v139, v109
	v_mul_f32_e32 v108, 0x3fb8aa3b, v108
	v_mul_f32_e32 v109, 0x3fb8aa3b, v109
	v_exp_f32_e32 v108, v108
	v_exp_f32_e32 v109, v109
	v_sub_f32_e32 v110, v139, v110
	v_sub_f32_e32 v111, v139, v111
	v_mul_f32_e32 v110, 0x3fb8aa3b, v110
	v_mul_f32_e32 v111, 0x3fb8aa3b, v111
	v_lshlrev_b32_e32 v118, 16, v118
	v_exp_f32_e32 v110, v110
	v_exp_f32_e32 v111, v111
	v_pk_mul_f32 v[108:109], v[108:109], v[118:119]
	v_lshl_add_u64 v[122:123], v[122:123], 0, v[140:141]
	v_cvt_pk_bf16_f32 v118, v108, v109
	v_cvt_pk_bf16_f32 v108, v126, v127
	v_lshrrev_b32_e32 v109, 16, v108
	ds_write_b16 v163, v108 offset:58720
	ds_write_b16 v164, v109 offset:58768
	v_and_b32_e32 v109, 0xffff0000, v108
	v_lshlrev_b32_e32 v108, 16, v108
	v_pk_mul_f32 v[108:109], v[110:111], v[108:109]
	v_mov_b32_e32 v139, v177
	v_cvt_pk_bf16_f32 v119, v108, v109
	ds_read_b128 v[108:111], v166 offset:56320
	v_lshl_add_u64 v[122:123], v[122:123], 0, v[138:139]
	s_waitcnt lgkmcnt(0)
	global_store_dwordx4 v[122:123], v[108:111], off
	ds_read_b128 v[108:111], v167 offset:56320
	v_lshl_add_u64 v[122:123], s[0:1], 0, v[134:135]
	v_lshl_add_u64 v[122:123], v[122:123], 0, s[62:63]
	v_lshl_add_u64 v[122:123], v[122:123], 0, v[140:141]
	v_lshl_add_u64 v[122:123], v[122:123], 0, v[138:139]
	s_waitcnt lgkmcnt(0)
	global_store_dwordx4 v[122:123], v[108:111], off
	v_exp_f32_e32 v122, v186
	s_nop 0
	v_pk_mul_f32 v[110:111], v[114:115], v[122:123] op_sel_hi:[1,0]
	v_pk_mul_f32 v[108:109], v[112:113], v[122:123] op_sel_hi:[1,0]
	v_pk_mul_f32 v[98:99], v[98:99], v[122:123] op_sel_hi:[1,0]
	s_waitcnt lgkmcnt(0)
	v_mfma_f32_16x16x16_bf16 v[108:111], v[196:197], v[142:143], v[108:111]
	v_mul_f32_e64 v96, v96, v122
	v_mul_f32_e64 v97, v97, v122
	v_pk_mul_f32 v[102:103], v[102:103], v[122:123] op_sel_hi:[1,0]
	v_pk_mul_f32 v[100:101], v[100:101], v[122:123] op_sel_hi:[1,0]
	v_mfma_f32_16x16x16_bf16 v[108:111], v[198:199], v[120:121], v[108:111]
	v_pk_mul_f32 v[106:107], v[106:107], v[122:123] op_sel_hi:[1,0]
	v_pk_mul_f32 v[104:105], v[104:105], v[122:123] op_sel_hi:[1,0]
	s_nop 1
	v_mfma_f32_16x16x16_bf16 v[108:111], v[200:201], v[116:117], v[108:111]
	v_mfma_f32_16x16x16_bf16 v[108:111], v[202:203], v[118:119], v[108:111]
	s_nop 1
	v_mfma_f32_16x16x16_bf16 v[96:99], v[204:205], v[142:143], v[96:99]
	v_mfma_f32_16x16x16_bf16 v[96:99], v[206:207], v[120:121], v[96:99]
	s_nop 1
	v_mfma_f32_16x16x16_bf16 v[96:99], v[208:209], v[116:117], v[96:99]
	v_mfma_f32_16x16x16_bf16 v[96:99], v[210:211], v[118:119], v[96:99]
	s_nop 1
	v_mfma_f32_16x16x16_bf16 v[100:103], v[212:213], v[142:143], v[100:103]
	v_mfma_f32_16x16x16_bf16 v[100:103], v[214:215], v[120:121], v[100:103]
	s_nop 1
	v_mfma_f32_16x16x16_bf16 v[100:103], v[216:217], v[116:117], v[100:103]
	v_mfma_f32_16x16x16_bf16 v[100:103], v[218:219], v[118:119], v[100:103]
	s_nop 1
	v_mfma_f32_16x16x16_bf16 v[104:107], v[234:235], v[142:143], v[104:107]
	v_mfma_f32_16x16x16_bf16 v[104:107], v[236:237], v[120:121], v[104:107]
	s_waitcnt lgkmcnt(0)
	s_barrier
	s_waitcnt lgkmcnt(0)
	v_mfma_f32_16x16x16_bf16 v[104:107], v[238:239], v[116:117], v[104:107]
	s_waitcnt vmcnt(45)
	ds_write_b128 v157, v[72:75]
	s_waitcnt vmcnt(43)
	ds_write_b128 v157, v[84:87] offset:4608
	s_waitcnt vmcnt(41)
	ds_write_b128 v157, v[88:91] offset:9216
	s_waitcnt vmcnt(40)
	ds_write_b128 v157, v[92:95] offset:13824
	ds_write_b128 v157, v[76:79] offset:18432
	ds_write_b128 v157, v[80:83] offset:23040
	v_mfma_f32_16x16x16_bf16 v[112:115], v[240:241], v[118:119], v[104:107]
	s_and_saveexec_b64 s[0:1], vcc
	s_cbranch_execz .LBB0_533
	s_waitcnt vmcnt(39)
	ds_write_b32 v158, v165 offset:27648
	s_branch .LBB0_533

.LBB0_932:
	ds_read_b128 v[198:201], v233 offset:8192
	ds_read_b128 v[202:205], v233 offset:9216
	ds_read_b128 v[206:209], v233 offset:10240
	ds_read_b128 v[210:213], v233 offset:11264
	ds_read_b128 v[214:217], v234 offset:32768
	ds_read_b128 v[236:239], v234 offset:33792
	ds_read_b128 v[240:243], v234 offset:34816
	ds_read_b128 v[244:247], v234 offset:35840
	s_setprio 1
	s_waitcnt lgkmcnt(3)
	v_mfma_f32_16x16x32_bf16 v[60:63], v[198:201], v[214:217], v[60:63]
	s_waitcnt lgkmcnt(2)
	v_mfma_f32_16x16x32_bf16 v[172:175], v[198:201], v[236:239], v[172:175]
	s_waitcnt lgkmcnt(1)
	v_mfma_f32_16x16x32_bf16 v[168:171], v[198:201], v[240:243], v[168:171]
	s_waitcnt lgkmcnt(0)
	v_mfma_f32_16x16x32_bf16 v[164:167], v[198:201], v[244:247], v[164:167]
	v_mfma_f32_16x16x32_bf16 v[56:59], v[202:205], v[214:217], v[56:59]
	s_waitcnt vmcnt(11)
	ds_write_b128 v191, v[0:3]
	v_mfma_f32_16x16x32_bf16 v[144:147], v[202:205], v[236:239], v[144:147]
	v_mfma_f32_16x16x32_bf16 v[140:143], v[202:205], v[240:243], v[140:143]
	s_waitcnt vmcnt(10)
	ds_write_b128 v191, v[4:7] offset:4096
	v_mfma_f32_16x16x32_bf16 v[136:139], v[202:205], v[244:247], v[136:139]
	v_mfma_f32_16x16x32_bf16 v[52:55], v[206:209], v[214:217], v[52:55]
	s_waitcnt vmcnt(9)
	ds_write_b128 v191, v[8:11] offset:16384
	v_mfma_f32_16x16x32_bf16 v[116:119], v[206:209], v[236:239], v[116:119]
	v_mfma_f32_16x16x32_bf16 v[112:115], v[206:209], v[240:243], v[112:115]
	s_waitcnt vmcnt(8)
	ds_write_b128 v191, v[12:15] offset:20480
	v_mfma_f32_16x16x32_bf16 v[108:111], v[206:209], v[244:247], v[108:111]
	v_mfma_f32_16x16x32_bf16 v[48:51], v[210:213], v[214:217], v[48:51]
	s_waitcnt vmcnt(7)
	ds_write_b128 v191, v[32:35] offset:24576
	v_mfma_f32_16x16x32_bf16 v[64:67], v[210:213], v[236:239], v[64:67]
	v_mfma_f32_16x16x32_bf16 v[76:79], v[210:213], v[240:243], v[76:79]
	s_waitcnt vmcnt(6)
	ds_write_b128 v191, v[36:39] offset:28672
	v_mfma_f32_16x16x32_bf16 v[72:75], v[210:213], v[244:247], v[72:75]
	s_setprio 0
	ds_read_b128 v[214:217], v234 offset:36864
	ds_read_b128 v[236:239], v234 offset:37888
	ds_read_b128 v[240:243], v234 offset:38912
	ds_read_b128 v[244:247], v234 offset:39936
	s_setprio 1
	s_waitcnt lgkmcnt(3)
	v_mfma_f32_16x16x32_bf16 v[160:163], v[198:201], v[214:217], v[160:163]
	s_waitcnt lgkmcnt(2)
	v_mfma_f32_16x16x32_bf16 v[152:155], v[198:201], v[236:239], v[152:155]
	s_waitcnt lgkmcnt(1)
	v_mfma_f32_16x16x32_bf16 v[156:159], v[198:201], v[240:243], v[156:159]
	s_waitcnt lgkmcnt(0)
	v_mfma_f32_16x16x32_bf16 v[148:151], v[198:201], v[244:247], v[148:151]
	v_mfma_f32_16x16x32_bf16 v[132:135], v[202:205], v[214:217], v[132:135]
	v_mfma_f32_16x16x32_bf16 v[124:127], v[202:205], v[236:239], v[124:127]
	v_mfma_f32_16x16x32_bf16 v[128:131], v[202:205], v[240:243], v[128:131]
	v_mfma_f32_16x16x32_bf16 v[120:123], v[202:205], v[244:247], v[120:123]
	v_mfma_f32_16x16x32_bf16 v[104:107], v[206:209], v[214:217], v[104:107]
	v_mfma_f32_16x16x32_bf16 v[96:99], v[206:209], v[236:239], v[96:99]
	v_mfma_f32_16x16x32_bf16 v[100:103], v[206:209], v[240:243], v[100:103]
	v_mfma_f32_16x16x32_bf16 v[92:95], v[206:209], v[244:247], v[92:95]
	v_mfma_f32_16x16x32_bf16 v[80:83], v[210:213], v[214:217], v[80:83]
	v_mfma_f32_16x16x32_bf16 v[68:71], v[210:213], v[236:239], v[68:71]
	v_mfma_f32_16x16x32_bf16 v[84:87], v[210:213], v[240:243], v[84:87]
	v_mfma_f32_16x16x32_bf16 v[88:91], v[210:213], v[244:247], v[88:91]
	s_setprio 0
	s_waitcnt lgkmcnt(0)
	s_barrier
	s_add_i32 s0, s0, 2
	s_cmp_gt_u32 s0, 29
	s_cbranch_scc1 .LBB0_944

.LBB0_939:
	ds_read_b128 v[198:201], v233
	ds_read_b128 v[202:205], v233 offset:1024
	ds_read_b128 v[206:209], v233 offset:2048
	ds_read_b128 v[210:213], v233 offset:3072
	ds_read_b128 v[214:217], v234 offset:16384
	ds_read_b128 v[236:239], v234 offset:17408
	ds_read_b128 v[240:243], v234 offset:18432
	ds_read_b128 v[244:247], v234 offset:19456
	s_setprio 1
	s_waitcnt lgkmcnt(3)
	v_mfma_f32_16x16x32_bf16 v[60:63], v[198:201], v[214:217], v[60:63]
	s_waitcnt lgkmcnt(2)
	v_mfma_f32_16x16x32_bf16 v[172:175], v[198:201], v[236:239], v[172:175]
	s_waitcnt lgkmcnt(1)
	v_mfma_f32_16x16x32_bf16 v[168:171], v[198:201], v[240:243], v[168:171]
	s_waitcnt lgkmcnt(0)
	v_mfma_f32_16x16x32_bf16 v[164:167], v[198:201], v[244:247], v[164:167]
	v_mfma_f32_16x16x32_bf16 v[56:59], v[202:205], v[214:217], v[56:59]
	s_waitcnt vmcnt(11)
	ds_write_b128 v191, v[16:19] offset:8192
	v_mfma_f32_16x16x32_bf16 v[144:147], v[202:205], v[236:239], v[144:147]
	v_mfma_f32_16x16x32_bf16 v[140:143], v[202:205], v[240:243], v[140:143]
	s_waitcnt vmcnt(10)
	ds_write_b128 v191, v[20:23] offset:12288
	v_mfma_f32_16x16x32_bf16 v[136:139], v[202:205], v[244:247], v[136:139]
	v_mfma_f32_16x16x32_bf16 v[52:55], v[206:209], v[214:217], v[52:55]
	s_waitcnt vmcnt(9)
	ds_write_b128 v191, v[24:27] offset:32768
	v_mfma_f32_16x16x32_bf16 v[116:119], v[206:209], v[236:239], v[116:119]
	v_mfma_f32_16x16x32_bf16 v[112:115], v[206:209], v[240:243], v[112:115]
	s_waitcnt vmcnt(8)
	ds_write_b128 v191, v[28:31] offset:36864
	v_mfma_f32_16x16x32_bf16 v[108:111], v[206:209], v[244:247], v[108:111]
	v_mfma_f32_16x16x32_bf16 v[48:51], v[210:213], v[214:217], v[48:51]
	s_waitcnt vmcnt(7)
	ds_write_b128 v191, v[40:43] offset:40960
	v_mfma_f32_16x16x32_bf16 v[64:67], v[210:213], v[236:239], v[64:67]
	v_mfma_f32_16x16x32_bf16 v[76:79], v[210:213], v[240:243], v[76:79]
	s_waitcnt vmcnt(6)
	ds_write_b128 v191, v[44:47] offset:45056
	v_mfma_f32_16x16x32_bf16 v[72:75], v[210:213], v[244:247], v[72:75]
	s_setprio 0
	ds_read_b128 v[214:217], v234 offset:20480
	ds_read_b128 v[236:239], v234 offset:21504
	ds_read_b128 v[240:243], v234 offset:22528
	ds_read_b128 v[244:247], v234 offset:23552
	s_setprio 1
	s_waitcnt lgkmcnt(3)
	v_mfma_f32_16x16x32_bf16 v[160:163], v[198:201], v[214:217], v[160:163]
	s_waitcnt lgkmcnt(2)
	v_mfma_f32_16x16x32_bf16 v[152:155], v[198:201], v[236:239], v[152:155]
	s_waitcnt lgkmcnt(1)
	v_mfma_f32_16x16x32_bf16 v[156:159], v[198:201], v[240:243], v[156:159]
	s_waitcnt lgkmcnt(0)
	v_mfma_f32_16x16x32_bf16 v[148:151], v[198:201], v[244:247], v[148:151]
	v_mfma_f32_16x16x32_bf16 v[132:135], v[202:205], v[214:217], v[132:135]
	v_mfma_f32_16x16x32_bf16 v[124:127], v[202:205], v[236:239], v[124:127]
	v_mfma_f32_16x16x32_bf16 v[128:131], v[202:205], v[240:243], v[128:131]
	v_mfma_f32_16x16x32_bf16 v[120:123], v[202:205], v[244:247], v[120:123]
	v_mfma_f32_16x16x32_bf16 v[104:107], v[206:209], v[214:217], v[104:107]
	v_mfma_f32_16x16x32_bf16 v[96:99], v[206:209], v[236:239], v[96:99]
	v_mfma_f32_16x16x32_bf16 v[100:103], v[206:209], v[240:243], v[100:103]
	v_mfma_f32_16x16x32_bf16 v[92:95], v[206:209], v[244:247], v[92:95]
	v_mfma_f32_16x16x32_bf16 v[80:83], v[210:213], v[214:217], v[80:83]
	v_mfma_f32_16x16x32_bf16 v[68:71], v[210:213], v[236:239], v[68:71]
	v_mfma_f32_16x16x32_bf16 v[84:87], v[210:213], v[240:243], v[84:87]
	v_mfma_f32_16x16x32_bf16 v[88:91], v[210:213], v[244:247], v[88:91]
	s_setprio 0
	s_waitcnt lgkmcnt(0)
	s_barrier
	s_andn2_b64 vcc, exec, s[2:3]
	s_cbranch_vccnz .Lw_skipy_0
	s_lshl_b32 s4, s1, 5
	s_ashr_i32 s5, s4, 31
	s_lshl_b64 s[4:5], s[4:5], 1
	v_lshl_add_u64 v[16:17], v[180:181], 0, s[4:5]
	v_add_co_u32_e32 v20, vcc, 0x20000, v16
	v_lshl_add_u64 v[40:41], v[182:183], 0, s[4:5]
	s_nop 0
	v_addc_co_u32_e32 v21, vcc, 0, v17, vcc
	v_add_co_u32_e32 v28, vcc, 0x20000, v40
	global_load_dwordx4 v[16:19], v[16:17], off
	s_nop 0
	global_load_dwordx4 v[20:23], v[20:21], off
	v_addc_co_u32_e32 v29, vcc, 0, v41, vcc
	v_add_co_u32_e32 v42, vcc, 0x40000, v40
	global_load_dwordx4 v[24:27], v[40:41], off
	s_nop 0
	global_load_dwordx4 v[28:31], v[28:29], off
	v_addc_co_u32_e32 v43, vcc, 0, v41, vcc
	v_add_co_u32_e32 v44, vcc, 0x60000, v40
	s_nop 1
	v_addc_co_u32_e32 v45, vcc, 0, v41, vcc
	global_load_dwordx4 v[40:43], v[42:43], off
	s_nop 0
	global_load_dwordx4 v[44:47], v[44:45], off

; template <int MODE, int HALF>
; __device__ void gemm_phase(const P& p, int layer, char* smem) {
;     ...
;         for (int mi = 0; mi < 4; ++mi) {
; #pragma unroll
;           for (int j = 0; j < 4; ++j) {
;             int rl = wm * 64 + mi * 16 + lqe * 4 + j;
;             size_t grow = row0 + rl;
;             float r = rsqrtf(RSb[grow] * (1.f / 1024.f) + 1e-6f);
;             float v[8];
; #pragma unroll
;             for (int ni = 0; ni < 8; ++ni) v[ni] = acc[mi][ni][j] * r;
;             if (rot) {
;               int pos = grow < 16384 ? (int)grow : (int)((grow - 16384) & 2047);
.LBB0_955:
	s_or_saveexec_b64 s[0:1], s[0:1]
	v_mov_b64_e32 v[206:207], s[10:11]
	v_mov_b64_e32 v[198:199], s[12:13]
	s_xor_b64 exec, exec, s[0:1]
	v_mov_b64_e32 v[198:199], 0x400
	v_mov_b64_e32 v[206:207], s[48:49]
	s_or_b64 exec, exec, s[0:1]
	v_lshl_add_u32 v202, v205, 2, v186
	v_ashrrev_i32_e32 v203, 31, v202
	v_lshl_add_u64 v[218:219], s[4:5], 0, v[202:203]
	v_lshl_add_u64 v[208:209], v[218:219], 2, s[30:31]
	global_load_dwordx4 v[0:3], v[208:209], off
	global_load_dwordx4 v[4:7], v[208:209], off offset:64
	global_load_dwordx4 v[8:11], v[208:209], off offset:128
	global_load_dwordx4 v[12:15], v[208:209], off offset:192
	s_mov_b32 s0, 0x800000
	s_cmp_lt_i32 s17, 7
	s_waitcnt vmcnt(0)
	v_mov_b32_e32 v201, v0
	v_fmamk_f32 v201, v201, 0x3a800000, v224
	v_cmp_gt_f32_e64 s[0:1], s0, v201
	s_cbranch_scc1 .LBB0_960
	s_cmp_eq_u32 s17, 7
	s_cselect_b64 s[10:11], -1, 0
	s_cbranch_execz .LBB0_961
	s_branch .LBB0_962

; template <int MODE, int HALF>
; __device__ void gemm_phase(const P& p, int layer, char* smem) {
;     ...
;             int rl = wm * 64 + mi * 16 + lqe * 4 + j;
;             size_t grow = row0 + rl;
;             float r = rsqrtf(RSb[grow] * (1.f / 1024.f) + 1e-6f);
;             float v[8];
; #pragma unroll
;             for (int ni = 0; ni < 8; ++ni) v[ni] = acc[mi][ni][j] * r;
;             if (rot) {
;               int pos = grow < 16384 ? (int)grow : (int)((grow - 16384) & 2047);
; #pragma unroll
;               for (int hh = 0; hh < 2; ++hh)
; #pragma unroll
;                 for (int n2 = 0; n2 < 2; ++n2) {
;                   int f = n2 * 16 + lre;
;                   float c = cosT[pos * 32 + f], s = sinT[pos * 32 + f];
;                   float t1 = v[hh * 4 + n2], t2 = v[hh * 4 + n2 + 2];
;                   v[hh * 4 + n2] = t1 * c - t2 * s;
;                   v[hh * 4 + n2 + 2] = t2 * c + t1 * s;
;                 }
;             }
; #pragma unroll
;             for (int ni = 0; ni < 8; ++ni) pb[(lqe * 4 + j) * 136 + ni * 16 + lre] = f2bf(v[ni] * scl);
.LBB0_964:
	s_and_b32 s0, s17, -3
	s_cmp_eq_u32 s0, 1
	s_cselect_b64 vcc, -1, 0
	s_movk_i32 s0, 0x440
	v_lshlrev_b32_e32 v148, 1, v200
	v_cndmask_b32_e32 v201, 1.0, v232, vcc
	v_mul_lo_u32 v152, v205, s0
	v_add3_u32 v203, v189, v148, v152
	v_mul_f32_e32 v148, v201, v216
	v_cvt_pk_bf16_f32 v148, v148, s0
	ds_write_b16 v203, v148 offset:49152
	v_mul_f32_e32 v148, v201, v217
	v_cvt_pk_bf16_f32 v148, v148, s0
	ds_write_b16 v203, v148 offset:49184
	v_mul_f32_e32 v148, v201, v210
	v_cvt_pk_bf16_f32 v148, v148, s0
	ds_write_b16 v203, v148 offset:49216
	v_mul_f32_e32 v148, v201, v211
	v_cvt_pk_bf16_f32 v148, v148, s0
	ds_write_b16 v203, v148 offset:49248
	v_mul_f32_e32 v148, v201, v208
	v_cvt_pk_bf16_f32 v148, v148, s0
	ds_write_b16 v203, v148 offset:49280
	v_mul_f32_e32 v148, v201, v215
	v_cvt_pk_bf16_f32 v148, v148, s0
	ds_write_b16 v203, v148 offset:49312
	v_mul_f32_e32 v148, v201, v212
	v_or_b32_e32 v208, 1, v202
	v_cvt_pk_bf16_f32 v148, v148, s0
	v_ashrrev_i32_e32 v209, 31, v208
	ds_write_b16 v203, v148 offset:49344
	v_mul_f32_e32 v148, v201, v214
	v_lshl_add_u64 v[208:209], s[4:5], 0, v[208:209]
	v_cvt_pk_bf16_f32 v148, v148, s0
	v_lshl_add_u64 v[210:211], v[208:209], 2, s[30:31]
	ds_write_b16 v203, v148 offset:49376
	v_mov_b32_e32 v148, v1
	s_mov_b32 s0, 0x800000
	s_cmp_lt_i32 s17, 7
	v_fmamk_f32 v148, v148, 0x3a800000, v224
	v_cmp_gt_f32_e64 s[0:1], s0, v148
	s_cbranch_scc1 .LBB0_966
	s_cmp_eq_u32 s17, 7
	s_cselect_b64 s[10:11], -1, 0
	s_cbranch_execz .LBB0_967
	s_branch .LBB0_968

; template <int MODE, int HALF>
; __device__ void gemm_phase(const P& p, int layer, char* smem) {
;     ...
;             int rl = wm * 64 + mi * 16 + lqe * 4 + j;
;             size_t grow = row0 + rl;
;             float r = rsqrtf(RSb[grow] * (1.f / 1024.f) + 1e-6f);
;             float v[8];
; #pragma unroll
;             for (int ni = 0; ni < 8; ++ni) v[ni] = acc[mi][ni][j] * r;
;             if (rot) {
;               int pos = grow < 16384 ? (int)grow : (int)((grow - 16384) & 2047);
; #pragma unroll
;               for (int hh = 0; hh < 2; ++hh)
; #pragma unroll
;                 for (int n2 = 0; n2 < 2; ++n2) {
;                   int f = n2 * 16 + lre;
;                   float c = cosT[pos * 32 + f], s = sinT[pos * 32 + f];
;                   float t1 = v[hh * 4 + n2], t2 = v[hh * 4 + n2 + 2];
;                   v[hh * 4 + n2] = t1 * c - t2 * s;
;                   v[hh * 4 + n2 + 2] = t2 * c + t1 * s;
;                 }
;             }
; #pragma unroll
;             for (int ni = 0; ni < 8; ++ni) pb[(lqe * 4 + j) * 136 + ni * 16 + lre] = f2bf(v[ni] * scl);
.LBB0_970:
	v_mul_f32_e32 v148, v201, v148
	v_mul_f32_e32 v149, v201, v168
	v_cvt_pk_bf16_f32 v148, v148, s0
	v_cvt_pk_bf16_f32 v149, v149, s0
	ds_write_b16 v203, v148 offset:49552
	v_mul_f32_e32 v148, v201, v153
	ds_write_b16 v203, v149 offset:49424
	v_mul_f32_e32 v149, v201, v169
	v_cvt_pk_bf16_f32 v148, v148, s0
	v_cvt_pk_bf16_f32 v149, v149, s0
	ds_write_b16 v203, v148 offset:49584
	v_mul_f32_e32 v148, v201, v156
	ds_write_b16 v203, v149 offset:49456
	v_mul_f32_e32 v149, v201, v164
	v_cvt_pk_bf16_f32 v148, v148, s0
	v_cvt_pk_bf16_f32 v149, v149, s0
	ds_write_b16 v203, v148 offset:49616
	v_mul_f32_e32 v148, v201, v152
	ds_write_b16 v203, v149 offset:49488
	v_mul_f32_e32 v149, v201, v165
	v_cvt_pk_bf16_f32 v148, v148, s0
	v_cvt_pk_bf16_f32 v149, v149, s0
	ds_write_b16 v203, v148 offset:49648
	v_or_b32_e32 v148, 2, v202
	ds_write_b16 v203, v149 offset:49520
	v_ashrrev_i32_e32 v149, 31, v148
	v_lshl_add_u64 v[168:169], s[4:5], 0, v[148:149]
	v_lshl_add_u64 v[148:149], v[168:169], 2, s[30:31]
	v_mov_b32_e32 v148, v2
	s_mov_b32 s0, 0x800000
	s_cmp_lt_i32 s17, 7
	v_fmamk_f32 v148, v148, 0x3a800000, v224
	v_cmp_gt_f32_e64 s[0:1], s0, v148
	s_cbranch_scc1 .LBB0_972
	s_cmp_eq_u32 s17, 7
	s_cselect_b64 s[10:11], -1, 0
	s_cbranch_execz .LBB0_973
	s_branch .LBB0_974

; template <int MODE, int HALF>
; __device__ void gemm_phase(const P& p, int layer, char* smem) {
;     ...
;             int rl = wm * 64 + mi * 16 + lqe * 4 + j;
;             size_t grow = row0 + rl;
;             float r = rsqrtf(RSb[grow] * (1.f / 1024.f) + 1e-6f);
;             float v[8];
; #pragma unroll
;             for (int ni = 0; ni < 8; ++ni) v[ni] = acc[mi][ni][j] * r;
;             if (rot) {
;               int pos = grow < 16384 ? (int)grow : (int)((grow - 16384) & 2047);
; #pragma unroll
;               for (int hh = 0; hh < 2; ++hh)
; #pragma unroll
;                 for (int n2 = 0; n2 < 2; ++n2) {
;                   int f = n2 * 16 + lre;
;                   float c = cosT[pos * 32 + f], s = sinT[pos * 32 + f];
;                   float t1 = v[hh * 4 + n2], t2 = v[hh * 4 + n2 + 2];
;                   v[hh * 4 + n2] = t1 * c - t2 * s;
;                   v[hh * 4 + n2 + 2] = t2 * c + t1 * s;
;                 }
;             }
; #pragma unroll
;             for (int ni = 0; ni < 8; ++ni) pb[(lqe * 4 + j) * 136 + ni * 16 + lre] = f2bf(v[ni] * scl);
.LBB0_976:
	v_mul_f32_e32 v148, v201, v148
	v_mul_f32_e32 v149, v201, v164
	v_cvt_pk_bf16_f32 v148, v148, s0
	v_cvt_pk_bf16_f32 v149, v149, s0
	ds_write_b16 v203, v148 offset:49824
	v_mul_f32_e32 v148, v201, v161
	ds_write_b16 v203, v149 offset:49696
	v_mul_f32_e32 v149, v201, v165
	v_cvt_pk_bf16_f32 v148, v148, s0
	v_cvt_pk_bf16_f32 v149, v149, s0
	ds_write_b16 v203, v148 offset:49856
	v_mul_f32_e32 v148, v201, v156
	ds_write_b16 v203, v149 offset:49728
	v_mul_f32_e32 v149, v201, v152
	v_cvt_pk_bf16_f32 v148, v148, s0
	v_cvt_pk_bf16_f32 v149, v149, s0
	ds_write_b16 v203, v148 offset:49888
	v_mul_f32_e32 v148, v201, v160
	ds_write_b16 v203, v149 offset:49760
	v_mul_f32_e32 v149, v201, v153
	v_cvt_pk_bf16_f32 v148, v148, s0
	v_cvt_pk_bf16_f32 v149, v149, s0
	ds_write_b16 v203, v148 offset:49920
	v_or_b32_e32 v148, 3, v202
	ds_write_b16 v203, v149 offset:49792
	v_ashrrev_i32_e32 v149, 31, v148
	v_lshl_add_u64 v[148:149], s[4:5], 0, v[148:149]
	v_lshl_add_u64 v[152:153], v[148:149], 2, s[30:31]
	v_mov_b32_e32 v150, v3
	s_mov_b32 s0, 0x800000
	s_cmp_lt_i32 s17, 7
	s_mov_b32 s18, 0x800000
	v_fmamk_f32 v150, v150, 0x3a800000, v224
	v_cmp_gt_f32_e64 s[0:1], s0, v150
	s_cbranch_scc1 .LBB0_978
	s_cmp_eq_u32 s17, 7
	s_cselect_b64 s[10:11], -1, 0
	s_cbranch_execz .LBB0_979
	s_branch .LBB0_980

; template <int MODE, int HALF>
; __device__ void gemm_phase(const P& p, int layer, char* smem) {
;     ...
;             int rl = wm * 64 + mi * 16 + lqe * 4 + j;
;             size_t grow = row0 + rl;
;             float r = rsqrtf(RSb[grow] * (1.f / 1024.f) + 1e-6f);
;             float v[8];
; #pragma unroll
;             for (int ni = 0; ni < 8; ++ni) v[ni] = acc[mi][ni][j] * r;
;             if (rot) {
;               int pos = grow < 16384 ? (int)grow : (int)((grow - 16384) & 2047);
; #pragma unroll
;               for (int hh = 0; hh < 2; ++hh)
; #pragma unroll
;                 for (int n2 = 0; n2 < 2; ++n2) {
;                   int f = n2 * 16 + lre;
;                   float c = cosT[pos * 32 + f], s = sinT[pos * 32 + f];
;                   float t1 = v[hh * 4 + n2], t2 = v[hh * 4 + n2 + 2];
;                   v[hh * 4 + n2] = t1 * c - t2 * s;
;                   v[hh * 4 + n2 + 2] = t2 * c + t1 * s;
;                 }
;             }
; #pragma unroll
;             for (int ni = 0; ni < 8; ++ni) pb[(lqe * 4 + j) * 136 + ni * 16 + lre] = f2bf(v[ni] * scl);
;           }
;           asm volatile("" ::: "memory");
; #pragma unroll
;           for (int it = 0; it < 4; ++it) {
;             int idx = it * 64 + lane, r = idx >> 4, ch = idx & 15;
;             uint4 o4 = *(const uint4*)(pb + r * 136 + ch * 8);
;             *(uint4*)(dst + (row0 + wm * 64 + mi * 16 + r) * ld + cbase + ch * 8) = o4;
;           }
.LBB0_982:
	v_mul_f32_e32 v153, v201, v160
	v_mul_f32_e32 v152, v201, v152
	v_cvt_pk_bf16_f32 v153, v153, s0
	v_cvt_pk_bf16_f32 v152, v152, s0
	ds_write_b16 v203, v153 offset:49968
	v_mul_f32_e32 v153, v201, v161
	ds_write_b16 v203, v152 offset:50096
	v_mul_f32_e32 v152, v201, v155
	v_cvt_pk_bf16_f32 v153, v153, s0
	v_cvt_pk_bf16_f32 v152, v152, s0
	ds_write_b16 v203, v153 offset:50000
	v_mul_f32_e32 v153, v201, v156
	ds_write_b16 v203, v152 offset:50128
	v_mul_f32_e32 v152, v201, v158
	v_cvt_pk_bf16_f32 v153, v153, s0
	v_cvt_pk_bf16_f32 v152, v152, s0
	ds_write_b16 v203, v153 offset:50032
	v_mul_f32_e32 v153, v201, v157
	ds_write_b16 v203, v152 offset:50160
	v_mul_f32_e32 v152, v201, v154
	v_cvt_pk_bf16_f32 v153, v153, s0
	v_cvt_pk_bf16_f32 v152, v152, s0
	ds_write_b16 v203, v153 offset:50064
	ds_write_b16 v203, v152 offset:50192
	v_lshl_add_u64 v[150:151], s[4:5], 0, v[186:187]
	ds_read_b128 v[152:155], v193 offset:49152
	v_ashrrev_i32_e32 v205, 31, v204
	v_or_b32_e32 v156, v150, v184
	v_lshl_add_u64 v[148:149], v[204:205], 1, v[206:207]
	v_mul_lo_u32 v158, v199, v156
	v_mad_u64_u32 v[156:157], s[0:1], v198, v156, 0
	v_mul_lo_u32 v151, v198, v151
	v_lshl_add_u64 v[148:149], v[148:149], 0, v[176:177]
	v_add3_u32 v157, v157, v151, v158
	v_lshl_add_u64 v[160:161], v[156:157], 1, v[148:149]
	ds_read_b128 v[156:159], v193 offset:50240
	s_waitcnt lgkmcnt(1)
	global_store_dwordx4 v[160:161], v[152:155], off
	s_cmp_lt_i32 s17, 7
	s_nop 0
	v_or_b32_e32 v152, v150, v188
	v_mul_lo_u32 v154, v199, v152
	v_mad_u64_u32 v[152:153], s[0:1], v198, v152, 0
	v_add3_u32 v153, v153, v151, v154
	v_lshl_add_u64 v[152:153], v[152:153], 1, v[148:149]
	s_waitcnt lgkmcnt(0)
	global_store_dwordx4 v[152:153], v[156:159], off
	ds_read_b128 v[152:155], v193 offset:51328
	s_nop 0
	v_or_b32_e32 v156, v150, v190
	v_mul_lo_u32 v158, v199, v156
	v_mad_u64_u32 v[156:157], s[0:1], v198, v156, 0
	v_add3_u32 v157, v157, v151, v158
	v_lshl_add_u64 v[160:161], v[156:157], 1, v[148:149]
	ds_read_b128 v[156:159], v193 offset:52416
	s_waitcnt lgkmcnt(1)
	global_store_dwordx4 v[160:161], v[152:155], off
	s_nop 1
	v_or_b32_e32 v152, v150, v192
	v_mul_lo_u32 v154, v199, v152
	v_mad_u64_u32 v[152:153], s[0:1], v198, v152, 0
	v_add3_u32 v153, v153, v151, v154
	v_lshl_add_u64 v[152:153], v[152:153], 1, v[148:149]
	s_waitcnt lgkmcnt(0)
	global_store_dwordx4 v[152:153], v[156:159], off
	v_add_u32_e32 v152, 16, v202
	v_ashrrev_i32_e32 v153, 31, v152
	v_lshl_add_u64 v[162:163], s[4:5], 0, v[152:153]
	v_lshl_add_u64 v[152:153], v[162:163], 2, s[30:31]
	v_mov_b32_e32 v152, v4
	v_fmamk_f32 v152, v152, 0x3a800000, v224
	v_cmp_gt_f32_e64 s[0:1], s18, v152
	s_cbranch_scc1 .LBB0_984
	s_cmp_eq_u32 s17, 7
	s_cselect_b64 s[10:11], -1, 0
	s_cbranch_execz .LBB0_985
	s_branch .LBB0_986

; template <int MODE, int HALF>
; __device__ void gemm_phase(const P& p, int layer, char* smem) {
;     ...
;             int rl = wm * 64 + mi * 16 + lqe * 4 + j;
;             size_t grow = row0 + rl;
;             float r = rsqrtf(RSb[grow] * (1.f / 1024.f) + 1e-6f);
;             float v[8];
; #pragma unroll
;             for (int ni = 0; ni < 8; ++ni) v[ni] = acc[mi][ni][j] * r;
;             if (rot) {
;               int pos = grow < 16384 ? (int)grow : (int)((grow - 16384) & 2047);
; #pragma unroll
;               for (int hh = 0; hh < 2; ++hh)
; #pragma unroll
;                 for (int n2 = 0; n2 < 2; ++n2) {
;                   int f = n2 * 16 + lre;
;                   float c = cosT[pos * 32 + f], s = sinT[pos * 32 + f];
;                   float t1 = v[hh * 4 + n2], t2 = v[hh * 4 + n2 + 2];
;                   v[hh * 4 + n2] = t1 * c - t2 * s;
;                   v[hh * 4 + n2 + 2] = t2 * c + t1 * s;
;                 }
;             }
; #pragma unroll
;             for (int ni = 0; ni < 8; ++ni) pb[(lqe * 4 + j) * 136 + ni * 16 + lre] = f2bf(v[ni] * scl);
.LBB0_988:
	v_mul_f32_e32 v120, v201, v160
	v_cvt_pk_bf16_f32 v120, v120, s0
	ds_write_b16 v203, v120 offset:49152
	v_mul_f32_e32 v120, v201, v161
	v_cvt_pk_bf16_f32 v120, v120, s0
	ds_write_b16 v203, v120 offset:49184
	v_mul_f32_e32 v120, v201, v154
	v_cvt_pk_bf16_f32 v120, v120, s0
	ds_write_b16 v203, v120 offset:49216
	v_mul_f32_e32 v120, v201, v155
	v_cvt_pk_bf16_f32 v120, v120, s0
	ds_write_b16 v203, v120 offset:49248
	v_mul_f32_e32 v120, v201, v152
	v_cvt_pk_bf16_f32 v120, v120, s0
	ds_write_b16 v203, v120 offset:49280
	v_mul_f32_e32 v120, v201, v159
	v_cvt_pk_bf16_f32 v120, v120, s0
	ds_write_b16 v203, v120 offset:49312
	v_mul_f32_e32 v120, v201, v156
	v_add_u32_e32 v152, 17, v202
	v_cvt_pk_bf16_f32 v120, v120, s0
	v_ashrrev_i32_e32 v153, 31, v152
	ds_write_b16 v203, v120 offset:49344
	v_mul_f32_e32 v120, v201, v158
	v_lshl_add_u64 v[152:153], s[4:5], 0, v[152:153]
	v_cvt_pk_bf16_f32 v120, v120, s0
	v_lshl_add_u64 v[154:155], v[152:153], 2, s[30:31]
	ds_write_b16 v203, v120 offset:49376
	v_mov_b32_e32 v120, v5
	s_mov_b32 s0, 0x800000
	s_cmp_lt_i32 s17, 7
	v_fmamk_f32 v120, v120, 0x3a800000, v224
	v_cmp_gt_f32_e64 s[0:1], s0, v120
	s_cbranch_scc1 .LBB0_990
	s_cmp_eq_u32 s17, 7
	s_cselect_b64 s[10:11], -1, 0
	s_cbranch_execz .LBB0_991
	s_branch .LBB0_992

; template <int MODE, int HALF>
; __device__ void gemm_phase(const P& p, int layer, char* smem) {
;     ...
;             int rl = wm * 64 + mi * 16 + lqe * 4 + j;
;             size_t grow = row0 + rl;
;             float r = rsqrtf(RSb[grow] * (1.f / 1024.f) + 1e-6f);
;             float v[8];
; #pragma unroll
;             for (int ni = 0; ni < 8; ++ni) v[ni] = acc[mi][ni][j] * r;
;             if (rot) {
;               int pos = grow < 16384 ? (int)grow : (int)((grow - 16384) & 2047);
; #pragma unroll
;               for (int hh = 0; hh < 2; ++hh)
; #pragma unroll
;                 for (int n2 = 0; n2 < 2; ++n2) {
;                   int f = n2 * 16 + lre;
;                   float c = cosT[pos * 32 + f], s = sinT[pos * 32 + f];
;                   float t1 = v[hh * 4 + n2], t2 = v[hh * 4 + n2 + 2];
;                   v[hh * 4 + n2] = t1 * c - t2 * s;
;                   v[hh * 4 + n2 + 2] = t2 * c + t1 * s;
;                 }
;             }
; #pragma unroll
;             for (int ni = 0; ni < 8; ++ni) pb[(lqe * 4 + j) * 136 + ni * 16 + lre] = f2bf(v[ni] * scl);
.LBB0_994:
	v_mul_f32_e32 v120, v201, v120
	v_mul_f32_e32 v121, v201, v140
	v_cvt_pk_bf16_f32 v120, v120, s0
	v_cvt_pk_bf16_f32 v121, v121, s0
	ds_write_b16 v203, v120 offset:49552
	v_mul_f32_e32 v120, v201, v125
	ds_write_b16 v203, v121 offset:49424
	v_mul_f32_e32 v121, v201, v141
	v_cvt_pk_bf16_f32 v120, v120, s0
	v_cvt_pk_bf16_f32 v121, v121, s0
	ds_write_b16 v203, v120 offset:49584
	v_mul_f32_e32 v120, v201, v128
	ds_write_b16 v203, v121 offset:49456
	v_mul_f32_e32 v121, v201, v136
	v_cvt_pk_bf16_f32 v120, v120, s0
	v_cvt_pk_bf16_f32 v121, v121, s0
	ds_write_b16 v203, v120 offset:49616
	v_mul_f32_e32 v120, v201, v124
	ds_write_b16 v203, v121 offset:49488
	v_mul_f32_e32 v121, v201, v137
	v_cvt_pk_bf16_f32 v120, v120, s0
	v_cvt_pk_bf16_f32 v121, v121, s0
	ds_write_b16 v203, v120 offset:49648
	v_add_u32_e32 v120, 18, v202
	ds_write_b16 v203, v121 offset:49520
	v_ashrrev_i32_e32 v121, 31, v120
	v_lshl_add_u64 v[140:141], s[4:5], 0, v[120:121]
	v_lshl_add_u64 v[120:121], v[140:141], 2, s[30:31]
	v_mov_b32_e32 v120, v6
	s_mov_b32 s0, 0x800000
	s_cmp_lt_i32 s17, 7
	v_fmamk_f32 v120, v120, 0x3a800000, v224
	v_cmp_gt_f32_e64 s[0:1], s0, v120
	s_cbranch_scc1 .LBB0_996
	s_cmp_eq_u32 s17, 7
	s_cselect_b64 s[10:11], -1, 0
	s_cbranch_execz .LBB0_997
	s_branch .LBB0_998

; template <int MODE, int HALF>
; __device__ void gemm_phase(const P& p, int layer, char* smem) {
;     ...
;             int rl = wm * 64 + mi * 16 + lqe * 4 + j;
;             size_t grow = row0 + rl;
;             float r = rsqrtf(RSb[grow] * (1.f / 1024.f) + 1e-6f);
;             float v[8];
; #pragma unroll
;             for (int ni = 0; ni < 8; ++ni) v[ni] = acc[mi][ni][j] * r;
;             if (rot) {
;               int pos = grow < 16384 ? (int)grow : (int)((grow - 16384) & 2047);
; #pragma unroll
;               for (int hh = 0; hh < 2; ++hh)
; #pragma unroll
;                 for (int n2 = 0; n2 < 2; ++n2) {
;                   int f = n2 * 16 + lre;
;                   float c = cosT[pos * 32 + f], s = sinT[pos * 32 + f];
;                   float t1 = v[hh * 4 + n2], t2 = v[hh * 4 + n2 + 2];
;                   v[hh * 4 + n2] = t1 * c - t2 * s;
;                   v[hh * 4 + n2 + 2] = t2 * c + t1 * s;
;                 }
;             }
; #pragma unroll
;             for (int ni = 0; ni < 8; ++ni) pb[(lqe * 4 + j) * 136 + ni * 16 + lre] = f2bf(v[ni] * scl);
.LBB0_1000:
	v_mul_f32_e32 v120, v201, v120
	v_mul_f32_e32 v121, v201, v136
	v_cvt_pk_bf16_f32 v120, v120, s0
	v_cvt_pk_bf16_f32 v121, v121, s0
	ds_write_b16 v203, v120 offset:49824
	v_mul_f32_e32 v120, v201, v133
	ds_write_b16 v203, v121 offset:49696
	v_mul_f32_e32 v121, v201, v137
	v_cvt_pk_bf16_f32 v120, v120, s0
	v_cvt_pk_bf16_f32 v121, v121, s0
	ds_write_b16 v203, v120 offset:49856
	v_mul_f32_e32 v120, v201, v128
	ds_write_b16 v203, v121 offset:49728
	v_mul_f32_e32 v121, v201, v124
	v_cvt_pk_bf16_f32 v120, v120, s0
	v_cvt_pk_bf16_f32 v121, v121, s0
	ds_write_b16 v203, v120 offset:49888
	v_mul_f32_e32 v120, v201, v132
	ds_write_b16 v203, v121 offset:49760
	v_mul_f32_e32 v121, v201, v125
	v_cvt_pk_bf16_f32 v120, v120, s0
	v_cvt_pk_bf16_f32 v121, v121, s0
	ds_write_b16 v203, v120 offset:49920
	v_add_u32_e32 v120, 19, v202
	ds_write_b16 v203, v121 offset:49792
	v_ashrrev_i32_e32 v121, 31, v120
	v_lshl_add_u64 v[132:133], s[4:5], 0, v[120:121]
	v_lshl_add_u64 v[120:121], v[132:133], 2, s[30:31]
	v_mov_b32_e32 v120, v7
	s_mov_b32 s0, 0x800000
	s_cmp_lt_i32 s17, 7
	v_fmamk_f32 v120, v120, 0x3a800000, v224
	v_cmp_gt_f32_e64 s[0:1], s0, v120
	s_cbranch_scc1 .LBB0_1002
	s_cmp_eq_u32 s17, 7
	s_cselect_b64 s[10:11], -1, 0
	s_cbranch_execz .LBB0_1003
	s_branch .LBB0_1004

; template <int MODE, int HALF>
; __device__ void gemm_phase(const P& p, int layer, char* smem) {
;     ...
;             int rl = wm * 64 + mi * 16 + lqe * 4 + j;
;             size_t grow = row0 + rl;
;             float r = rsqrtf(RSb[grow] * (1.f / 1024.f) + 1e-6f);
;             float v[8];
; #pragma unroll
;             for (int ni = 0; ni < 8; ++ni) v[ni] = acc[mi][ni][j] * r;
;             if (rot) {
;               int pos = grow < 16384 ? (int)grow : (int)((grow - 16384) & 2047);
; #pragma unroll
;               for (int hh = 0; hh < 2; ++hh)
; #pragma unroll
;                 for (int n2 = 0; n2 < 2; ++n2) {
;                   int f = n2 * 16 + lre;
;                   float c = cosT[pos * 32 + f], s = sinT[pos * 32 + f];
;                   float t1 = v[hh * 4 + n2], t2 = v[hh * 4 + n2 + 2];
;                   v[hh * 4 + n2] = t1 * c - t2 * s;
;                   v[hh * 4 + n2 + 2] = t2 * c + t1 * s;
;                 }
;             }
; #pragma unroll
;             for (int ni = 0; ni < 8; ++ni) pb[(lqe * 4 + j) * 136 + ni * 16 + lre] = f2bf(v[ni] * scl);
;           }
;           asm volatile("" ::: "memory");
; #pragma unroll
;           for (int it = 0; it < 4; ++it) {
;             int idx = it * 64 + lane, r = idx >> 4, ch = idx & 15;
;             uint4 o4 = *(const uint4*)(pb + r * 136 + ch * 8);
;             *(uint4*)(dst + (row0 + wm * 64 + mi * 16 + r) * ld + cbase + ch * 8) = o4;
;           }
.LBB0_1006:
	v_mul_f32_e32 v121, v201, v128
	v_mul_f32_e32 v120, v201, v120
	v_cvt_pk_bf16_f32 v121, v121, s0
	v_cvt_pk_bf16_f32 v120, v120, s0
	ds_write_b16 v203, v121 offset:49968
	v_mul_f32_e32 v121, v201, v129
	ds_write_b16 v203, v120 offset:50096
	v_mul_f32_e32 v120, v201, v127
	v_cvt_pk_bf16_f32 v121, v121, s0
	v_cvt_pk_bf16_f32 v120, v120, s0
	ds_write_b16 v203, v121 offset:50000
	v_mul_f32_e32 v121, v201, v124
	ds_write_b16 v203, v120 offset:50128
	v_mul_f32_e32 v120, v201, v122
	v_cvt_pk_bf16_f32 v121, v121, s0
	v_cvt_pk_bf16_f32 v120, v120, s0
	ds_write_b16 v203, v121 offset:50032
	v_mul_f32_e32 v121, v201, v125
	ds_write_b16 v203, v120 offset:50160
	v_mul_f32_e32 v120, v201, v126
	v_cvt_pk_bf16_f32 v121, v121, s0
	v_cvt_pk_bf16_f32 v120, v120, s0
	ds_write_b16 v203, v121 offset:50064
	ds_write_b16 v203, v120 offset:50192
	v_or_b32_e32 v126, 16, v150
	ds_read_b128 v[120:123], v193 offset:49152
	v_or_b32_e32 v124, v126, v184
	v_mul_lo_u32 v127, v199, v124
	v_mad_u64_u32 v[124:125], s[0:1], v198, v124, 0
	v_add3_u32 v125, v125, v151, v127
	v_lshl_add_u64 v[124:125], v[124:125], 1, v[148:149]
	s_waitcnt lgkmcnt(0)
	global_store_dwordx4 v[124:125], v[120:123], off
	ds_read_b128 v[120:123], v193 offset:50240
	v_or_b32_e32 v124, v126, v188
	v_mul_lo_u32 v127, v199, v124
	v_mad_u64_u32 v[124:125], s[0:1], v198, v124, 0
	v_add3_u32 v125, v125, v151, v127
	v_lshl_add_u64 v[124:125], v[124:125], 1, v[148:149]
	s_waitcnt lgkmcnt(0)
	global_store_dwordx4 v[124:125], v[120:123], off
	ds_read_b128 v[120:123], v193 offset:51328
	v_or_b32_e32 v124, v126, v190
	v_mul_lo_u32 v127, v199, v124
	v_mad_u64_u32 v[124:125], s[0:1], v198, v124, 0
	v_add3_u32 v125, v125, v151, v127
	v_lshl_add_u64 v[124:125], v[124:125], 1, v[148:149]
	s_waitcnt lgkmcnt(0)
	global_store_dwordx4 v[124:125], v[120:123], off
	ds_read_b128 v[120:123], v193 offset:52416
	v_or_b32_e32 v124, v126, v192
	v_mul_lo_u32 v126, v199, v124
	v_mad_u64_u32 v[124:125], s[0:1], v198, v124, 0
	v_add3_u32 v125, v125, v151, v126
	v_lshl_add_u64 v[124:125], v[124:125], 1, v[148:149]
	s_waitcnt lgkmcnt(0)
	global_store_dwordx4 v[124:125], v[120:123], off
	s_cmp_lt_i32 s17, 7
	s_nop 0
	v_add_u32_e32 v120, 32, v202
	v_ashrrev_i32_e32 v121, 31, v120
	v_lshl_add_u64 v[130:131], s[4:5], 0, v[120:121]
	v_lshl_add_u64 v[120:121], v[130:131], 2, s[30:31]
	v_mov_b32_e32 v120, v8
	v_fmamk_f32 v120, v120, 0x3a800000, v224
	v_cmp_gt_f32_e64 s[0:1], s18, v120
	s_cbranch_scc1 .LBB0_1008
	s_cmp_eq_u32 s17, 7
	s_cselect_b64 s[10:11], -1, 0
	s_cbranch_execz .LBB0_1009
	s_branch .LBB0_1010

; template <int MODE, int HALF>
; __device__ void gemm_phase(const P& p, int layer, char* smem) {
;     ...
;             int rl = wm * 64 + mi * 16 + lqe * 4 + j;
;             size_t grow = row0 + rl;
;             float r = rsqrtf(RSb[grow] * (1.f / 1024.f) + 1e-6f);
;             float v[8];
; #pragma unroll
;             for (int ni = 0; ni < 8; ++ni) v[ni] = acc[mi][ni][j] * r;
;             if (rot) {
;               int pos = grow < 16384 ? (int)grow : (int)((grow - 16384) & 2047);
; #pragma unroll
;               for (int hh = 0; hh < 2; ++hh)
; #pragma unroll
;                 for (int n2 = 0; n2 < 2; ++n2) {
;                   int f = n2 * 16 + lre;
;                   float c = cosT[pos * 32 + f], s = sinT[pos * 32 + f];
;                   float t1 = v[hh * 4 + n2], t2 = v[hh * 4 + n2 + 2];
;                   v[hh * 4 + n2] = t1 * c - t2 * s;
;                   v[hh * 4 + n2 + 2] = t2 * c + t1 * s;
;                 }
;             }
; #pragma unroll
;             for (int ni = 0; ni < 8; ++ni) pb[(lqe * 4 + j) * 136 + ni * 16 + lre] = f2bf(v[ni] * scl);
.LBB0_1012:
	v_mul_f32_e32 v92, v201, v128
	v_cvt_pk_bf16_f32 v92, v92, s0
	ds_write_b16 v203, v92 offset:49152
	v_mul_f32_e32 v92, v201, v129
	v_cvt_pk_bf16_f32 v92, v92, s0
	ds_write_b16 v203, v92 offset:49184
	v_mul_f32_e32 v92, v201, v122
	v_cvt_pk_bf16_f32 v92, v92, s0
	ds_write_b16 v203, v92 offset:49216
	v_mul_f32_e32 v92, v201, v123
	v_cvt_pk_bf16_f32 v92, v92, s0
	ds_write_b16 v203, v92 offset:49248
	v_mul_f32_e32 v92, v201, v120
	v_cvt_pk_bf16_f32 v92, v92, s0
	ds_write_b16 v203, v92 offset:49280
	v_mul_f32_e32 v92, v201, v127
	v_cvt_pk_bf16_f32 v92, v92, s0
	ds_write_b16 v203, v92 offset:49312
	v_mul_f32_e32 v92, v201, v124
	v_add_u32_e32 v120, 33, v202
	v_cvt_pk_bf16_f32 v92, v92, s0
	v_ashrrev_i32_e32 v121, 31, v120
	ds_write_b16 v203, v92 offset:49344
	v_mul_f32_e32 v92, v201, v126
	v_lshl_add_u64 v[120:121], s[4:5], 0, v[120:121]
	v_cvt_pk_bf16_f32 v92, v92, s0
	v_lshl_add_u64 v[122:123], v[120:121], 2, s[30:31]
	ds_write_b16 v203, v92 offset:49376
	v_mov_b32_e32 v92, v9
	s_mov_b32 s0, 0x800000
	s_cmp_lt_i32 s17, 7
	v_fmamk_f32 v92, v92, 0x3a800000, v224
	v_cmp_gt_f32_e64 s[0:1], s0, v92
	s_cbranch_scc1 .LBB0_1014
	s_cmp_eq_u32 s17, 7
	s_cselect_b64 s[10:11], -1, 0
	s_cbranch_execz .LBB0_1015
	s_branch .LBB0_1016

; template <int MODE, int HALF>
; __device__ void gemm_phase(const P& p, int layer, char* smem) {
;     ...
;             int rl = wm * 64 + mi * 16 + lqe * 4 + j;
;             size_t grow = row0 + rl;
;             float r = rsqrtf(RSb[grow] * (1.f / 1024.f) + 1e-6f);
;             float v[8];
; #pragma unroll
;             for (int ni = 0; ni < 8; ++ni) v[ni] = acc[mi][ni][j] * r;
;             if (rot) {
;               int pos = grow < 16384 ? (int)grow : (int)((grow - 16384) & 2047);
; #pragma unroll
;               for (int hh = 0; hh < 2; ++hh)
; #pragma unroll
;                 for (int n2 = 0; n2 < 2; ++n2) {
;                   int f = n2 * 16 + lre;
;                   float c = cosT[pos * 32 + f], s = sinT[pos * 32 + f];
;                   float t1 = v[hh * 4 + n2], t2 = v[hh * 4 + n2 + 2];
;                   v[hh * 4 + n2] = t1 * c - t2 * s;
;                   v[hh * 4 + n2 + 2] = t2 * c + t1 * s;
;                 }
;             }
; #pragma unroll
;             for (int ni = 0; ni < 8; ++ni) pb[(lqe * 4 + j) * 136 + ni * 16 + lre] = f2bf(v[ni] * scl);
.LBB0_1018:
	v_mul_f32_e32 v92, v201, v92
	v_mul_f32_e32 v93, v201, v112
	v_cvt_pk_bf16_f32 v92, v92, s0
	v_cvt_pk_bf16_f32 v93, v93, s0
	ds_write_b16 v203, v92 offset:49552
	v_mul_f32_e32 v92, v201, v97
	ds_write_b16 v203, v93 offset:49424
	v_mul_f32_e32 v93, v201, v113
	v_cvt_pk_bf16_f32 v92, v92, s0
	v_cvt_pk_bf16_f32 v93, v93, s0
	ds_write_b16 v203, v92 offset:49584
	v_mul_f32_e32 v92, v201, v100
	ds_write_b16 v203, v93 offset:49456
	v_mul_f32_e32 v93, v201, v108
	v_cvt_pk_bf16_f32 v92, v92, s0
	v_cvt_pk_bf16_f32 v93, v93, s0
	ds_write_b16 v203, v92 offset:49616
	v_mul_f32_e32 v92, v201, v96
	ds_write_b16 v203, v93 offset:49488
	v_mul_f32_e32 v93, v201, v109
	v_cvt_pk_bf16_f32 v92, v92, s0
	v_cvt_pk_bf16_f32 v93, v93, s0
	ds_write_b16 v203, v92 offset:49648
	v_add_u32_e32 v92, 34, v202
	ds_write_b16 v203, v93 offset:49520
	v_ashrrev_i32_e32 v93, 31, v92
	v_lshl_add_u64 v[112:113], s[4:5], 0, v[92:93]
	v_lshl_add_u64 v[92:93], v[112:113], 2, s[30:31]
	v_mov_b32_e32 v92, v10
	s_mov_b32 s0, 0x800000
	s_cmp_lt_i32 s17, 7
	v_fmamk_f32 v92, v92, 0x3a800000, v224
	v_cmp_gt_f32_e64 s[0:1], s0, v92
	s_cbranch_scc1 .LBB0_1020
	s_cmp_eq_u32 s17, 7
	s_cselect_b64 s[10:11], -1, 0
	s_cbranch_execz .LBB0_1021
	s_branch .LBB0_1022

; template <int MODE, int HALF>
; __device__ void gemm_phase(const P& p, int layer, char* smem) {
;     ...
;             int rl = wm * 64 + mi * 16 + lqe * 4 + j;
;             size_t grow = row0 + rl;
;             float r = rsqrtf(RSb[grow] * (1.f / 1024.f) + 1e-6f);
;             float v[8];
; #pragma unroll
;             for (int ni = 0; ni < 8; ++ni) v[ni] = acc[mi][ni][j] * r;
;             if (rot) {
;               int pos = grow < 16384 ? (int)grow : (int)((grow - 16384) & 2047);
; #pragma unroll
;               for (int hh = 0; hh < 2; ++hh)
; #pragma unroll
;                 for (int n2 = 0; n2 < 2; ++n2) {
;                   int f = n2 * 16 + lre;
;                   float c = cosT[pos * 32 + f], s = sinT[pos * 32 + f];
;                   float t1 = v[hh * 4 + n2], t2 = v[hh * 4 + n2 + 2];
;                   v[hh * 4 + n2] = t1 * c - t2 * s;
;                   v[hh * 4 + n2 + 2] = t2 * c + t1 * s;
;                 }
;             }
; #pragma unroll
;             for (int ni = 0; ni < 8; ++ni) pb[(lqe * 4 + j) * 136 + ni * 16 + lre] = f2bf(v[ni] * scl);
.LBB0_1024:
	v_mul_f32_e32 v92, v201, v92
	v_mul_f32_e32 v93, v201, v108
	v_cvt_pk_bf16_f32 v92, v92, s0
	v_cvt_pk_bf16_f32 v93, v93, s0
	ds_write_b16 v203, v92 offset:49824
	v_mul_f32_e32 v92, v201, v105
	ds_write_b16 v203, v93 offset:49696
	v_mul_f32_e32 v93, v201, v109
	v_cvt_pk_bf16_f32 v92, v92, s0
	v_cvt_pk_bf16_f32 v93, v93, s0
	ds_write_b16 v203, v92 offset:49856
	v_mul_f32_e32 v92, v201, v100
	ds_write_b16 v203, v93 offset:49728
	v_mul_f32_e32 v93, v201, v96
	v_cvt_pk_bf16_f32 v92, v92, s0
	v_cvt_pk_bf16_f32 v93, v93, s0
	ds_write_b16 v203, v92 offset:49888
	v_mul_f32_e32 v92, v201, v104
	ds_write_b16 v203, v93 offset:49760
	v_mul_f32_e32 v93, v201, v97
	v_cvt_pk_bf16_f32 v92, v92, s0
	v_cvt_pk_bf16_f32 v93, v93, s0
	ds_write_b16 v203, v92 offset:49920
	v_add_u32_e32 v92, 35, v202
	ds_write_b16 v203, v93 offset:49792
	v_ashrrev_i32_e32 v93, 31, v92
	v_lshl_add_u64 v[104:105], s[4:5], 0, v[92:93]
	v_lshl_add_u64 v[92:93], v[104:105], 2, s[30:31]
	v_mov_b32_e32 v92, v11
	s_mov_b32 s0, 0x800000
	s_cmp_lt_i32 s17, 7
	v_fmamk_f32 v92, v92, 0x3a800000, v224
	v_cmp_gt_f32_e64 s[0:1], s0, v92
	s_cbranch_scc1 .LBB0_1026
	s_cmp_eq_u32 s17, 7
	s_cselect_b64 s[10:11], -1, 0
	s_cbranch_execz .LBB0_1027
	s_branch .LBB0_1028

; template <int MODE, int HALF>
; __device__ void gemm_phase(const P& p, int layer, char* smem) {
;     ...
;             int rl = wm * 64 + mi * 16 + lqe * 4 + j;
;             size_t grow = row0 + rl;
;             float r = rsqrtf(RSb[grow] * (1.f / 1024.f) + 1e-6f);
;             float v[8];
; #pragma unroll
;             for (int ni = 0; ni < 8; ++ni) v[ni] = acc[mi][ni][j] * r;
;             if (rot) {
;               int pos = grow < 16384 ? (int)grow : (int)((grow - 16384) & 2047);
; #pragma unroll
;               for (int hh = 0; hh < 2; ++hh)
; #pragma unroll
;                 for (int n2 = 0; n2 < 2; ++n2) {
;                   int f = n2 * 16 + lre;
;                   float c = cosT[pos * 32 + f], s = sinT[pos * 32 + f];
;                   float t1 = v[hh * 4 + n2], t2 = v[hh * 4 + n2 + 2];
;                   v[hh * 4 + n2] = t1 * c - t2 * s;
;                   v[hh * 4 + n2 + 2] = t2 * c + t1 * s;
;                 }
;             }
; #pragma unroll
;             for (int ni = 0; ni < 8; ++ni) pb[(lqe * 4 + j) * 136 + ni * 16 + lre] = f2bf(v[ni] * scl);
;           }
;           asm volatile("" ::: "memory");
; #pragma unroll
;           for (int it = 0; it < 4; ++it) {
;             int idx = it * 64 + lane, r = idx >> 4, ch = idx & 15;
;             uint4 o4 = *(const uint4*)(pb + r * 136 + ch * 8);
;             *(uint4*)(dst + (row0 + wm * 64 + mi * 16 + r) * ld + cbase + ch * 8) = o4;
;           }
.LBB0_1030:
	v_mul_f32_e32 v93, v201, v100
	v_mul_f32_e32 v92, v201, v92
	v_cvt_pk_bf16_f32 v93, v93, s0
	v_cvt_pk_bf16_f32 v92, v92, s0
	ds_write_b16 v203, v93 offset:49968
	v_mul_f32_e32 v93, v201, v101
	ds_write_b16 v203, v92 offset:50096
	v_mul_f32_e32 v92, v201, v99
	v_cvt_pk_bf16_f32 v93, v93, s0
	v_cvt_pk_bf16_f32 v92, v92, s0
	ds_write_b16 v203, v93 offset:50000
	v_mul_f32_e32 v93, v201, v96
	ds_write_b16 v203, v92 offset:50128
	v_mul_f32_e32 v92, v201, v94
	v_cvt_pk_bf16_f32 v93, v93, s0
	v_cvt_pk_bf16_f32 v92, v92, s0
	ds_write_b16 v203, v93 offset:50032
	v_mul_f32_e32 v93, v201, v97
	ds_write_b16 v203, v92 offset:50160
	v_mul_f32_e32 v92, v201, v98
	v_cvt_pk_bf16_f32 v93, v93, s0
	v_cvt_pk_bf16_f32 v92, v92, s0
	ds_write_b16 v203, v93 offset:50064
	ds_write_b16 v203, v92 offset:50192
	v_or_b32_e32 v98, 32, v150
	ds_read_b128 v[92:95], v193 offset:49152
	v_or_b32_e32 v96, v98, v184
	v_mul_lo_u32 v99, v199, v96
	v_mad_u64_u32 v[96:97], s[0:1], v198, v96, 0
	v_add3_u32 v97, v97, v151, v99
	v_lshl_add_u64 v[96:97], v[96:97], 1, v[148:149]
	s_waitcnt lgkmcnt(0)
	global_store_dwordx4 v[96:97], v[92:95], off
	ds_read_b128 v[92:95], v193 offset:50240
	v_or_b32_e32 v96, v98, v188
	v_mul_lo_u32 v99, v199, v96
	v_mad_u64_u32 v[96:97], s[0:1], v198, v96, 0
	v_add3_u32 v97, v97, v151, v99
	v_lshl_add_u64 v[96:97], v[96:97], 1, v[148:149]
	s_waitcnt lgkmcnt(0)
	global_store_dwordx4 v[96:97], v[92:95], off
	ds_read_b128 v[92:95], v193 offset:51328
	v_or_b32_e32 v96, v98, v190
	v_mul_lo_u32 v99, v199, v96
	v_mad_u64_u32 v[96:97], s[0:1], v198, v96, 0
	v_add3_u32 v97, v97, v151, v99
	v_lshl_add_u64 v[96:97], v[96:97], 1, v[148:149]
	s_waitcnt lgkmcnt(0)
	global_store_dwordx4 v[96:97], v[92:95], off
	ds_read_b128 v[92:95], v193 offset:52416
	v_or_b32_e32 v96, v98, v192
	v_mul_lo_u32 v98, v199, v96
	v_mad_u64_u32 v[96:97], s[0:1], v198, v96, 0
	v_add3_u32 v97, v97, v151, v98
	v_lshl_add_u64 v[96:97], v[96:97], 1, v[148:149]
	s_waitcnt lgkmcnt(0)
	global_store_dwordx4 v[96:97], v[92:95], off
	s_cmp_lt_i32 s17, 7
	s_nop 0
	v_add_u32_e32 v92, 48, v202
	v_ashrrev_i32_e32 v93, 31, v92
	v_lshl_add_u64 v[102:103], s[4:5], 0, v[92:93]
	v_lshl_add_u64 v[92:93], v[102:103], 2, s[30:31]
	v_mov_b32_e32 v92, v12
	v_fmamk_f32 v92, v92, 0x3a800000, v224
	v_cmp_gt_f32_e64 s[0:1], s18, v92
	s_cbranch_scc1 .LBB0_1032
	s_cmp_eq_u32 s17, 7
	s_cselect_b64 s[10:11], -1, 0
	s_cbranch_execz .LBB0_1033
	s_branch .LBB0_1034

; template <int MODE, int HALF>
; __device__ void gemm_phase(const P& p, int layer, char* smem) {
;     ...
;             int rl = wm * 64 + mi * 16 + lqe * 4 + j;
;             size_t grow = row0 + rl;
;             float r = rsqrtf(RSb[grow] * (1.f / 1024.f) + 1e-6f);
;             float v[8];
; #pragma unroll
;             for (int ni = 0; ni < 8; ++ni) v[ni] = acc[mi][ni][j] * r;
;             if (rot) {
;               int pos = grow < 16384 ? (int)grow : (int)((grow - 16384) & 2047);
; #pragma unroll
;               for (int hh = 0; hh < 2; ++hh)
; #pragma unroll
;                 for (int n2 = 0; n2 < 2; ++n2) {
;                   int f = n2 * 16 + lre;
;                   float c = cosT[pos * 32 + f], s = sinT[pos * 32 + f];
;                   float t1 = v[hh * 4 + n2], t2 = v[hh * 4 + n2 + 2];
;                   v[hh * 4 + n2] = t1 * c - t2 * s;
;                   v[hh * 4 + n2 + 2] = t2 * c + t1 * s;
;                 }
;             }
; #pragma unroll
;             for (int ni = 0; ni < 8; ++ni) pb[(lqe * 4 + j) * 136 + ni * 16 + lre] = f2bf(v[ni] * scl);
.LBB0_1036:
	v_mul_f32_e32 v64, v201, v100
	v_cvt_pk_bf16_f32 v64, v64, s0
	ds_write_b16 v203, v64 offset:49152
	v_mul_f32_e32 v64, v201, v101
	v_cvt_pk_bf16_f32 v64, v64, s0
	ds_write_b16 v203, v64 offset:49184
	v_mul_f32_e32 v64, v201, v94
	v_cvt_pk_bf16_f32 v64, v64, s0
	ds_write_b16 v203, v64 offset:49216
	v_mul_f32_e32 v64, v201, v95
	v_cvt_pk_bf16_f32 v64, v64, s0
	ds_write_b16 v203, v64 offset:49248
	v_mul_f32_e32 v64, v201, v92
	v_cvt_pk_bf16_f32 v64, v64, s0
	ds_write_b16 v203, v64 offset:49280
	v_mul_f32_e32 v64, v201, v99
	v_cvt_pk_bf16_f32 v64, v64, s0
	ds_write_b16 v203, v64 offset:49312
	v_mul_f32_e32 v64, v201, v96
	v_add_u32_e32 v92, 49, v202
	v_cvt_pk_bf16_f32 v64, v64, s0
	v_ashrrev_i32_e32 v93, 31, v92
	ds_write_b16 v203, v64 offset:49344
	v_mul_f32_e32 v64, v201, v98
	v_lshl_add_u64 v[94:95], s[4:5], 0, v[92:93]
	v_cvt_pk_bf16_f32 v64, v64, s0
	v_lshl_add_u64 v[92:93], v[94:95], 2, s[30:31]
	ds_write_b16 v203, v64 offset:49376
	v_mov_b32_e32 v64, v13
	s_mov_b32 s0, 0x800000
	s_cmp_lt_i32 s17, 7
	v_fmamk_f32 v64, v64, 0x3a800000, v224
	v_cmp_gt_f32_e64 s[0:1], s0, v64
	s_cbranch_scc1 .LBB0_1038
	s_cmp_eq_u32 s17, 7
	s_cselect_b64 s[10:11], -1, 0
	s_cbranch_execz .LBB0_1039
	s_branch .LBB0_1040

; template <int MODE, int HALF>
; __device__ void gemm_phase(const P& p, int layer, char* smem) {
;     ...
;             int rl = wm * 64 + mi * 16 + lqe * 4 + j;
;             size_t grow = row0 + rl;
;             float r = rsqrtf(RSb[grow] * (1.f / 1024.f) + 1e-6f);
;             float v[8];
; #pragma unroll
;             for (int ni = 0; ni < 8; ++ni) v[ni] = acc[mi][ni][j] * r;
;             if (rot) {
;               int pos = grow < 16384 ? (int)grow : (int)((grow - 16384) & 2047);
; #pragma unroll
;               for (int hh = 0; hh < 2; ++hh)
; #pragma unroll
;                 for (int n2 = 0; n2 < 2; ++n2) {
;                   int f = n2 * 16 + lre;
;                   float c = cosT[pos * 32 + f], s = sinT[pos * 32 + f];
;                   float t1 = v[hh * 4 + n2], t2 = v[hh * 4 + n2 + 2];
;                   v[hh * 4 + n2] = t1 * c - t2 * s;
;                   v[hh * 4 + n2 + 2] = t2 * c + t1 * s;
;                 }
;             }
; #pragma unroll
;             for (int ni = 0; ni < 8; ++ni) pb[(lqe * 4 + j) * 136 + ni * 16 + lre] = f2bf(v[ni] * scl);
.LBB0_1042:
	v_mul_f32_e32 v64, v201, v64
	v_mul_f32_e32 v65, v201, v92
	v_cvt_pk_bf16_f32 v64, v64, s0
	v_cvt_pk_bf16_f32 v65, v65, s0
	ds_write_b16 v203, v64 offset:49552
	v_mul_f32_e32 v64, v201, v69
	ds_write_b16 v203, v65 offset:49424
	v_mul_f32_e32 v65, v201, v93
	v_cvt_pk_bf16_f32 v64, v64, s0
	v_cvt_pk_bf16_f32 v65, v65, s0
	ds_write_b16 v203, v64 offset:49584
	v_mul_f32_e32 v64, v201, v76
	ds_write_b16 v203, v65 offset:49456
	v_mul_f32_e32 v65, v201, v72
	v_cvt_pk_bf16_f32 v64, v64, s0
	v_cvt_pk_bf16_f32 v65, v65, s0
	ds_write_b16 v203, v64 offset:49616
	v_mul_f32_e32 v64, v201, v68
	ds_write_b16 v203, v65 offset:49488
	v_mul_f32_e32 v65, v201, v73
	v_cvt_pk_bf16_f32 v64, v64, s0
	v_cvt_pk_bf16_f32 v65, v65, s0
	ds_write_b16 v203, v64 offset:49648
	v_add_u32_e32 v64, 50, v202
	ds_write_b16 v203, v65 offset:49520
	v_ashrrev_i32_e32 v65, 31, v64
	v_lshl_add_u64 v[84:85], s[4:5], 0, v[64:65]
	v_lshl_add_u64 v[64:65], v[84:85], 2, s[30:31]
	v_mov_b32_e32 v64, v14
	s_mov_b32 s0, 0x800000
	s_cmp_lt_i32 s17, 7
	v_fmamk_f32 v64, v64, 0x3a800000, v224
	v_cmp_gt_f32_e64 s[0:1], s0, v64
	s_cbranch_scc1 .LBB0_1044
	s_cmp_eq_u32 s17, 7
	s_cselect_b64 s[10:11], -1, 0
	s_cbranch_execz .LBB0_1045
	s_branch .LBB0_1046

; template <int MODE, int HALF>
; __device__ void gemm_phase(const P& p, int layer, char* smem) {
;     ...
;             int rl = wm * 64 + mi * 16 + lqe * 4 + j;
;             size_t grow = row0 + rl;
;             float r = rsqrtf(RSb[grow] * (1.f / 1024.f) + 1e-6f);
;             float v[8];
; #pragma unroll
;             for (int ni = 0; ni < 8; ++ni) v[ni] = acc[mi][ni][j] * r;
;             if (rot) {
;               int pos = grow < 16384 ? (int)grow : (int)((grow - 16384) & 2047);
; #pragma unroll
;               for (int hh = 0; hh < 2; ++hh)
; #pragma unroll
;                 for (int n2 = 0; n2 < 2; ++n2) {
;                   int f = n2 * 16 + lre;
;                   float c = cosT[pos * 32 + f], s = sinT[pos * 32 + f];
;                   float t1 = v[hh * 4 + n2], t2 = v[hh * 4 + n2 + 2];
;                   v[hh * 4 + n2] = t1 * c - t2 * s;
;                   v[hh * 4 + n2 + 2] = t2 * c + t1 * s;
;                 }
;             }
; #pragma unroll
;             for (int ni = 0; ni < 8; ++ni) pb[(lqe * 4 + j) * 136 + ni * 16 + lre] = f2bf(v[ni] * scl);
.LBB0_1048:
	v_mul_f32_e32 v64, v201, v64
	v_mul_f32_e32 v65, v201, v80
	v_cvt_pk_bf16_f32 v64, v64, s0
	v_cvt_pk_bf16_f32 v65, v65, s0
	ds_write_b16 v203, v64 offset:49824
	v_mul_f32_e32 v64, v201, v77
	ds_write_b16 v203, v65 offset:49696
	v_mul_f32_e32 v65, v201, v81
	v_cvt_pk_bf16_f32 v64, v64, s0
	v_cvt_pk_bf16_f32 v65, v65, s0
	ds_write_b16 v203, v64 offset:49856
	v_mul_f32_e32 v64, v201, v72
	ds_write_b16 v203, v65 offset:49728
	v_mul_f32_e32 v65, v201, v68
	v_cvt_pk_bf16_f32 v64, v64, s0
	v_cvt_pk_bf16_f32 v65, v65, s0
	ds_write_b16 v203, v64 offset:49888
	v_mul_f32_e32 v64, v201, v76
	ds_write_b16 v203, v65 offset:49760
	v_mul_f32_e32 v65, v201, v69
	v_cvt_pk_bf16_f32 v64, v64, s0
	v_cvt_pk_bf16_f32 v65, v65, s0
	ds_write_b16 v203, v64 offset:49920
	v_add_u32_e32 v64, 51, v202
	ds_write_b16 v203, v65 offset:49792
	v_ashrrev_i32_e32 v65, 31, v64
	v_lshl_add_u64 v[76:77], s[4:5], 0, v[64:65]
	v_lshl_add_u64 v[64:65], v[76:77], 2, s[30:31]
	v_mov_b32_e32 v64, v15
	s_mov_b32 s0, 0x800000
	s_cmp_lt_i32 s17, 7
	v_fmamk_f32 v64, v64, 0x3a800000, v224
	v_cmp_gt_f32_e64 s[0:1], s0, v64
	s_cbranch_scc1 .LBB0_1050
	s_cmp_eq_u32 s17, 7
	s_cselect_b64 s[10:11], -1, 0
	s_cbranch_execz .LBB0_1051
	s_branch .LBB0_1052
